# all GEMM K-loops peeled (C=0 first MFMAs, no accumulator zeroing); xor-16/32 shuffle reductions in the fused epilogues via v_permlane16/32_swap instead of ds_bpermute
# baseline (speedup 1.0000x reference)
.LBB0_740:
	s_mov_b32 s48, s6
	s_ashr_i32 s49, s6, 31
	s_mov_b32 s94, s7
	s_lshl_b64 s[6:7], s[48:49], 20
	s_add_u32 s56, s70, s6
	s_addc_u32 s57, s71, s7
	s_and_b64 s[6:7], exec, s[52:53]
	s_mov_b32 s50, s5
	s_cselect_b32 s5, s57, s39
	s_cselect_b32 s6, s56, s38
	s_add_u32 s60, s80, s60
	s_addc_u32 s61, s81, s61
	s_mov_b32 s67, s8
	s_and_b64 s[8:9], exec, s[52:53]
	s_cselect_b32 s7, s61, s37
	s_cselect_b32 s8, s60, s36
	s_add_u32 s9, s36, 0x100
	s_addc_u32 s10, s37, 0
	s_add_u32 s36, s38, 0x80080
	s_addc_u32 s37, s39, 0
	s_mov_b32 s11, -2
	s_waitcnt lgkmcnt(0)
	s_add_u32 s12, s36, 0xfff80080
	s_addc_u32 s13, s37, -1
	s_add_i32 s14, 0, 0x10000
	s_cmp_eq_u32 s11, 28
	s_cselect_b32 s63, s5, s13
	s_cselect_b32 s62, s6, s12
	s_cselect_b32 s39, s7, s10
	s_cselect_b32 s38, s8, s9
	s_add_i32 s15, 0, 0x14000
	v_add_u32_e32 v144, s14, v230
	v_add_u32_e32 v160, s15, v230
	ds_read_b128 v[124:127], v144
	ds_read_b128 v[128:131], v144 offset:1024
	ds_read_b128 v[136:139], v144 offset:2048
	ds_read_b128 v[144:147], v144 offset:3072
	ds_read_b128 v[148:151], v160
	ds_read_b128 v[152:155], v160 offset:1024
	ds_read_b128 v[156:159], v160 offset:2048
	ds_read_b128 v[160:163], v160 offset:3072
	v_lshl_add_u64 v[196:197], s[36:37], 0, v[222:223]
	s_add_i32 m0, s21, 0xc000
	ds_read_b128 v[164:167], v243
	ds_read_b128 v[168:171], v243 offset:1024
	ds_read_b128 v[172:175], v243 offset:2048
	ds_read_b128 v[176:179], v243 offset:3072
	ds_read_b128 v[180:183], v243 offset:4096
	ds_read_b128 v[184:187], v243 offset:5120
	ds_read_b128 v[188:191], v243 offset:6144
	ds_read_b128 v[192:195], v243 offset:7168
	global_load_lds_dwordx4 v[196:197], off
	v_lshl_add_u64 v[196:197], s[36:37], 0, v[220:221]
	s_add_i32 m0, s21, 0xe000
	s_nop 0
	global_load_lds_dwordx4 v[196:197], off
	s_waitcnt vmcnt(8)
	s_waitcnt lgkmcnt(0)
	s_barrier
	s_setprio 1
	s_waitcnt lgkmcnt(0)
	v_mfma_f32_16x16x32_bf16 v[140:143], v[124:127], v[164:167], 0
	v_mfma_f32_16x16x32_bf16 v[132:135], v[136:139], v[164:167], 0
	v_mfma_f32_16x16x32_bf16 v[112:115], v[124:127], v[172:175], 0
	v_mfma_f32_16x16x32_bf16 v[108:111], v[136:139], v[172:175], 0
	v_mfma_f32_16x16x32_bf16 v[96:99], v[124:127], v[180:183], 0
	v_mfma_f32_16x16x32_bf16 v[92:95], v[136:139], v[180:183], 0
	v_mfma_f32_16x16x32_bf16 v[80:83], v[124:127], v[188:191], 0
	v_mfma_f32_16x16x32_bf16 v[76:79], v[136:139], v[188:191], 0
	v_mfma_f32_16x16x32_bf16 v[140:143], v[128:131], v[168:171], v[140:143]
	v_mfma_f32_16x16x32_bf16 v[132:135], v[144:147], v[168:171], v[132:135]
	v_mfma_f32_16x16x32_bf16 v[112:115], v[128:131], v[176:179], v[112:115]
	v_mfma_f32_16x16x32_bf16 v[108:111], v[144:147], v[176:179], v[108:111]
	v_mfma_f32_16x16x32_bf16 v[96:99], v[128:131], v[184:187], v[96:99]
	v_mfma_f32_16x16x32_bf16 v[92:95], v[144:147], v[184:187], v[92:95]
	v_mfma_f32_16x16x32_bf16 v[80:83], v[128:131], v[192:195], v[80:83]
	v_mfma_f32_16x16x32_bf16 v[76:79], v[144:147], v[192:195], v[76:79]
	s_setprio 0
	s_setprio 1
	v_mfma_f32_16x16x32_bf16 v[120:123], v[148:151], v[164:167], 0
	v_mfma_f32_16x16x32_bf16 v[116:119], v[156:159], v[164:167], 0
	v_mfma_f32_16x16x32_bf16 v[104:107], v[148:151], v[172:175], 0
	v_mfma_f32_16x16x32_bf16 v[100:103], v[156:159], v[172:175], 0
	v_mfma_f32_16x16x32_bf16 v[88:91], v[148:151], v[180:183], 0
	v_mfma_f32_16x16x32_bf16 v[84:87], v[156:159], v[180:183], 0
	v_mfma_f32_16x16x32_bf16 v[72:75], v[148:151], v[188:191], 0
	v_mfma_f32_16x16x32_bf16 v[68:71], v[156:159], v[188:191], 0
	v_mfma_f32_16x16x32_bf16 v[120:123], v[152:155], v[168:171], v[120:123]
	v_mfma_f32_16x16x32_bf16 v[116:119], v[160:163], v[168:171], v[116:119]
	v_mfma_f32_16x16x32_bf16 v[104:107], v[152:155], v[176:179], v[104:107]
	v_mfma_f32_16x16x32_bf16 v[100:103], v[160:163], v[176:179], v[100:103]
	v_mfma_f32_16x16x32_bf16 v[88:91], v[152:155], v[184:187], v[88:91]
	v_mfma_f32_16x16x32_bf16 v[84:87], v[160:163], v[184:187], v[84:87]
	v_mfma_f32_16x16x32_bf16 v[72:75], v[152:155], v[192:195], v[72:75]
	v_mfma_f32_16x16x32_bf16 v[68:71], v[160:163], v[192:195], v[68:71]
	s_setprio 0
	s_barrier
	s_add_i32 s12, s14, s82
	v_lshl_add_u64 v[196:197], s[38:39], 0, v[2:3]
	s_mov_b32 m0, s12
	ds_read_b128 v[164:167], v243 offset:16384
	ds_read_b128 v[168:171], v243 offset:17408
	ds_read_b128 v[172:175], v243 offset:18432
	ds_read_b128 v[176:179], v243 offset:19456
	ds_read_b128 v[180:183], v243 offset:20480
	ds_read_b128 v[184:187], v243 offset:21504
	ds_read_b128 v[188:191], v243 offset:22528
	ds_read_b128 v[192:195], v243 offset:23552
	global_load_lds_dwordx4 v[196:197], off
	s_add_i32 m0, s12, 0x2000
	s_add_u32 s12, s38, 0x80000
	v_lshl_add_u64 v[198:199], s[38:39], 0, v[218:219]
	s_addc_u32 s13, s39, 0
	s_add_i32 s14, s15, s82
	global_load_lds_dwordx4 v[198:199], off
	v_lshl_add_u64 v[200:201], s[12:13], 0, v[2:3]
	s_mov_b32 m0, s14
	v_lshl_add_u64 v[202:203], s[62:63], 0, v[216:217]
	global_load_lds_dwordx4 v[200:201], off
	v_lshl_add_u64 v[200:201], s[12:13], 0, v[218:219]
	s_add_i32 m0, s14, 0x2000
	s_nop 0
	global_load_lds_dwordx4 v[200:201], off
	v_lshl_add_u64 v[200:201], s[62:63], 0, v[0:1]
	s_mov_b32 m0, s21
	s_nop 0
	global_load_lds_dwordx4 v[200:201], off
	s_mov_b32 m0, s83
	s_nop 0
	global_load_lds_dwordx4 v[202:203], off
	s_waitcnt vmcnt(8)
	s_waitcnt lgkmcnt(0)
	s_barrier
	s_setprio 1
	s_waitcnt lgkmcnt(0)
	v_mfma_f32_16x16x32_bf16 v[64:67], v[124:127], v[164:167], 0
	v_mfma_f32_16x16x32_bf16 v[60:63], v[136:139], v[164:167], 0
	v_mfma_f32_16x16x32_bf16 v[48:51], v[124:127], v[172:175], 0
	v_mfma_f32_16x16x32_bf16 v[44:47], v[136:139], v[172:175], 0
	v_mfma_f32_16x16x32_bf16 v[32:35], v[124:127], v[180:183], 0
	v_mfma_f32_16x16x32_bf16 v[28:31], v[136:139], v[180:183], 0
	v_mfma_f32_16x16x32_bf16 v[16:19], v[124:127], v[188:191], 0
	v_mfma_f32_16x16x32_bf16 v[12:15], v[136:139], v[188:191], 0
	v_mfma_f32_16x16x32_bf16 v[64:67], v[128:131], v[168:171], v[64:67]
	v_mfma_f32_16x16x32_bf16 v[60:63], v[144:147], v[168:171], v[60:63]
	v_mfma_f32_16x16x32_bf16 v[48:51], v[128:131], v[176:179], v[48:51]
	v_mfma_f32_16x16x32_bf16 v[44:47], v[144:147], v[176:179], v[44:47]
	v_mfma_f32_16x16x32_bf16 v[32:35], v[128:131], v[184:187], v[32:35]
	v_mfma_f32_16x16x32_bf16 v[28:31], v[144:147], v[184:187], v[28:31]
	v_mfma_f32_16x16x32_bf16 v[16:19], v[128:131], v[192:195], v[16:19]
	v_mfma_f32_16x16x32_bf16 v[12:15], v[144:147], v[192:195], v[12:15]
	s_setprio 0
	s_setprio 1
	v_mfma_f32_16x16x32_bf16 v[56:59], v[148:151], v[164:167], 0
	v_mfma_f32_16x16x32_bf16 v[52:55], v[156:159], v[164:167], 0
	v_mfma_f32_16x16x32_bf16 v[40:43], v[148:151], v[172:175], 0
	v_mfma_f32_16x16x32_bf16 v[36:39], v[156:159], v[172:175], 0
	v_mfma_f32_16x16x32_bf16 v[24:27], v[148:151], v[180:183], 0
	v_mfma_f32_16x16x32_bf16 v[20:23], v[156:159], v[180:183], 0
	v_mfma_f32_16x16x32_bf16 v[8:11], v[148:151], v[188:191], 0
	v_mfma_f32_16x16x32_bf16 v[4:7], v[156:159], v[188:191], 0
	v_mfma_f32_16x16x32_bf16 v[56:59], v[152:155], v[168:171], v[56:59]
	v_mfma_f32_16x16x32_bf16 v[52:55], v[160:163], v[168:171], v[52:55]
	v_mfma_f32_16x16x32_bf16 v[40:43], v[152:155], v[176:179], v[40:43]
	v_mfma_f32_16x16x32_bf16 v[36:39], v[160:163], v[176:179], v[36:39]
	v_mfma_f32_16x16x32_bf16 v[24:27], v[152:155], v[184:187], v[24:27]
	v_mfma_f32_16x16x32_bf16 v[20:23], v[160:163], v[184:187], v[20:23]
	v_mfma_f32_16x16x32_bf16 v[8:11], v[152:155], v[192:195], v[8:11]
	v_mfma_f32_16x16x32_bf16 v[4:7], v[160:163], v[192:195], v[4:7]
	s_setprio 0
	s_barrier
	s_add_i32 s14, 0, 0x18000
	s_add_i32 s15, 0, 0x1c000
	v_add_u32_e32 v144, s14, v230
	v_add_u32_e32 v160, s15, v230
	ds_read_b128 v[124:127], v144
	ds_read_b128 v[128:131], v144 offset:1024
	ds_read_b128 v[136:139], v144 offset:2048
	ds_read_b128 v[144:147], v144 offset:3072
	ds_read_b128 v[148:151], v160
	ds_read_b128 v[152:155], v160 offset:1024
	ds_read_b128 v[156:159], v160 offset:2048
	ds_read_b128 v[160:163], v160 offset:3072
	s_add_u32 s12, s62, 0x80000
	s_addc_u32 s13, s63, 0
	s_mov_b32 m0, s84
	v_lshl_add_u64 v[204:205], s[12:13], 0, v[0:1]
	ds_read_b128 v[164:167], v243 offset:32768
	ds_read_b128 v[168:171], v243 offset:33792
	ds_read_b128 v[172:175], v243 offset:34816
	ds_read_b128 v[176:179], v243 offset:35840
	ds_read_b128 v[180:183], v243 offset:36864
	ds_read_b128 v[184:187], v243 offset:37888
	ds_read_b128 v[188:191], v243 offset:38912
	ds_read_b128 v[192:195], v243 offset:39936
	global_load_lds_dwordx4 v[204:205], off
	v_lshl_add_u64 v[204:205], s[12:13], 0, v[216:217]
	s_mov_b32 m0, s85
	s_nop 0
	global_load_lds_dwordx4 v[204:205], off
	s_waitcnt vmcnt(8)
	s_waitcnt lgkmcnt(0)
	s_barrier
	s_setprio 1
	s_waitcnt lgkmcnt(0)
	v_mfma_f32_16x16x32_bf16 v[140:143], v[124:127], v[164:167], v[140:143]
	v_mfma_f32_16x16x32_bf16 v[132:135], v[136:139], v[164:167], v[132:135]
	v_mfma_f32_16x16x32_bf16 v[112:115], v[124:127], v[172:175], v[112:115]
	v_mfma_f32_16x16x32_bf16 v[108:111], v[136:139], v[172:175], v[108:111]
	v_mfma_f32_16x16x32_bf16 v[96:99], v[124:127], v[180:183], v[96:99]
	v_mfma_f32_16x16x32_bf16 v[92:95], v[136:139], v[180:183], v[92:95]
	v_mfma_f32_16x16x32_bf16 v[80:83], v[124:127], v[188:191], v[80:83]
	v_mfma_f32_16x16x32_bf16 v[76:79], v[136:139], v[188:191], v[76:79]
	v_mfma_f32_16x16x32_bf16 v[140:143], v[128:131], v[168:171], v[140:143]
	v_mfma_f32_16x16x32_bf16 v[132:135], v[144:147], v[168:171], v[132:135]
	v_mfma_f32_16x16x32_bf16 v[112:115], v[128:131], v[176:179], v[112:115]
	v_mfma_f32_16x16x32_bf16 v[108:111], v[144:147], v[176:179], v[108:111]
	v_mfma_f32_16x16x32_bf16 v[96:99], v[128:131], v[184:187], v[96:99]
	v_mfma_f32_16x16x32_bf16 v[92:95], v[144:147], v[184:187], v[92:95]
	v_mfma_f32_16x16x32_bf16 v[80:83], v[128:131], v[192:195], v[80:83]
	v_mfma_f32_16x16x32_bf16 v[76:79], v[144:147], v[192:195], v[76:79]
	s_setprio 0
	s_setprio 1
	v_mfma_f32_16x16x32_bf16 v[120:123], v[148:151], v[164:167], v[120:123]
	v_mfma_f32_16x16x32_bf16 v[116:119], v[156:159], v[164:167], v[116:119]
	v_mfma_f32_16x16x32_bf16 v[104:107], v[148:151], v[172:175], v[104:107]
	v_mfma_f32_16x16x32_bf16 v[100:103], v[156:159], v[172:175], v[100:103]
	v_mfma_f32_16x16x32_bf16 v[88:91], v[148:151], v[180:183], v[88:91]
	v_mfma_f32_16x16x32_bf16 v[84:87], v[156:159], v[180:183], v[84:87]
	v_mfma_f32_16x16x32_bf16 v[72:75], v[148:151], v[188:191], v[72:75]
	v_mfma_f32_16x16x32_bf16 v[68:71], v[156:159], v[188:191], v[68:71]
	v_mfma_f32_16x16x32_bf16 v[120:123], v[152:155], v[168:171], v[120:123]
	v_mfma_f32_16x16x32_bf16 v[116:119], v[160:163], v[168:171], v[116:119]
	v_mfma_f32_16x16x32_bf16 v[104:107], v[152:155], v[176:179], v[104:107]
	v_mfma_f32_16x16x32_bf16 v[100:103], v[160:163], v[176:179], v[100:103]
	v_mfma_f32_16x16x32_bf16 v[88:91], v[152:155], v[184:187], v[88:91]
	v_mfma_f32_16x16x32_bf16 v[84:87], v[160:163], v[184:187], v[84:87]
	v_mfma_f32_16x16x32_bf16 v[72:75], v[152:155], v[192:195], v[72:75]
	v_mfma_f32_16x16x32_bf16 v[68:71], v[160:163], v[192:195], v[68:71]
	s_setprio 0
	s_barrier
	s_add_i32 s12, s14, s82
	v_lshl_add_u64 v[196:197], v[196:197], 0, s[68:69]
	s_mov_b32 m0, s12
	ds_read_b128 v[164:167], v243 offset:49152
	ds_read_b128 v[168:171], v243 offset:50176
	ds_read_b128 v[172:175], v243 offset:51200
	ds_read_b128 v[176:179], v243 offset:52224
	ds_read_b128 v[180:183], v243 offset:53248
	ds_read_b128 v[184:187], v243 offset:54272
	ds_read_b128 v[188:191], v243 offset:55296
	ds_read_b128 v[192:195], v243 offset:56320
	global_load_lds_dwordx4 v[196:197], off
	s_add_i32 m0, s12, 0x2000
	s_add_u32 s12, s38, 0x80080
	v_lshl_add_u64 v[196:197], v[198:199], 0, s[68:69]
	s_addc_u32 s13, s39, 0
	s_add_i32 s14, s15, s82
	global_load_lds_dwordx4 v[196:197], off
	v_lshl_add_u64 v[196:197], s[12:13], 0, v[2:3]
	s_mov_b32 m0, s14
	s_nop 0
	global_load_lds_dwordx4 v[196:197], off
	v_lshl_add_u64 v[196:197], s[12:13], 0, v[218:219]
	s_add_i32 m0, s14, 0x2000
	s_nop 0
	global_load_lds_dwordx4 v[196:197], off
	v_lshl_add_u64 v[196:197], v[200:201], 0, s[68:69]
	s_mov_b32 m0, s89
	s_nop 0
	global_load_lds_dwordx4 v[196:197], off
	v_lshl_add_u64 v[196:197], v[202:203], 0, s[68:69]
	s_mov_b32 m0, s90
	s_nop 0
	global_load_lds_dwordx4 v[196:197], off
	s_waitcnt vmcnt(8)
	s_waitcnt lgkmcnt(0)
	s_barrier
	s_setprio 1
	s_waitcnt lgkmcnt(0)
	v_mfma_f32_16x16x32_bf16 v[64:67], v[124:127], v[164:167], v[64:67]
	v_mfma_f32_16x16x32_bf16 v[60:63], v[136:139], v[164:167], v[60:63]
	v_mfma_f32_16x16x32_bf16 v[48:51], v[124:127], v[172:175], v[48:51]
	v_mfma_f32_16x16x32_bf16 v[44:47], v[136:139], v[172:175], v[44:47]
	v_mfma_f32_16x16x32_bf16 v[32:35], v[124:127], v[180:183], v[32:35]
	v_mfma_f32_16x16x32_bf16 v[28:31], v[136:139], v[180:183], v[28:31]
	v_mfma_f32_16x16x32_bf16 v[16:19], v[124:127], v[188:191], v[16:19]
	v_mfma_f32_16x16x32_bf16 v[12:15], v[136:139], v[188:191], v[12:15]
	v_mfma_f32_16x16x32_bf16 v[64:67], v[128:131], v[168:171], v[64:67]
	v_mfma_f32_16x16x32_bf16 v[60:63], v[144:147], v[168:171], v[60:63]
	v_mfma_f32_16x16x32_bf16 v[48:51], v[128:131], v[176:179], v[48:51]
	v_mfma_f32_16x16x32_bf16 v[44:47], v[144:147], v[176:179], v[44:47]
	v_mfma_f32_16x16x32_bf16 v[32:35], v[128:131], v[184:187], v[32:35]
	v_mfma_f32_16x16x32_bf16 v[28:31], v[144:147], v[184:187], v[28:31]
	v_mfma_f32_16x16x32_bf16 v[16:19], v[128:131], v[192:195], v[16:19]
	v_mfma_f32_16x16x32_bf16 v[12:15], v[144:147], v[192:195], v[12:15]
	s_setprio 0
	s_setprio 1
	v_mfma_f32_16x16x32_bf16 v[56:59], v[148:151], v[164:167], v[56:59]
	v_mfma_f32_16x16x32_bf16 v[52:55], v[156:159], v[164:167], v[52:55]
	v_mfma_f32_16x16x32_bf16 v[40:43], v[148:151], v[172:175], v[40:43]
	v_mfma_f32_16x16x32_bf16 v[36:39], v[156:159], v[172:175], v[36:39]
	v_mfma_f32_16x16x32_bf16 v[24:27], v[148:151], v[180:183], v[24:27]
	v_mfma_f32_16x16x32_bf16 v[20:23], v[156:159], v[180:183], v[20:23]
	v_mfma_f32_16x16x32_bf16 v[8:11], v[148:151], v[188:191], v[8:11]
	v_mfma_f32_16x16x32_bf16 v[4:7], v[156:159], v[188:191], v[4:7]
	v_mfma_f32_16x16x32_bf16 v[56:59], v[152:155], v[168:171], v[56:59]
	v_mfma_f32_16x16x32_bf16 v[52:55], v[160:163], v[168:171], v[52:55]
	v_mfma_f32_16x16x32_bf16 v[40:43], v[152:155], v[176:179], v[40:43]
	v_mfma_f32_16x16x32_bf16 v[36:39], v[160:163], v[176:179], v[36:39]
	v_mfma_f32_16x16x32_bf16 v[24:27], v[152:155], v[184:187], v[24:27]
	v_mfma_f32_16x16x32_bf16 v[20:23], v[160:163], v[184:187], v[20:23]
	v_mfma_f32_16x16x32_bf16 v[8:11], v[152:155], v[192:195], v[8:11]
	v_mfma_f32_16x16x32_bf16 v[4:7], v[160:163], v[192:195], v[4:7]
	s_setprio 0
	s_barrier
	s_add_i32 s11, s11, 2
	s_add_u32 s9, s9, 0x100
	s_addc_u32 s10, s10, 0
	s_add_u32 s36, s36, 0x100
	s_addc_u32 s37, s37, 0
	s_cmp_gt_u32 s11, 29

.LBB0_744:
	v_mul_f32_e32 v124, v141, v141
	v_mul_f32_e32 v125, v143, v143
	v_fmac_f32_e32 v124, v140, v140
	v_fmac_f32_e32 v125, v142, v142
	v_add_f32_e32 v124, v124, v125
	v_mul_f32_e32 v125, v133, v133
	v_mul_f32_e32 v126, v135, v135
	v_fmac_f32_e32 v125, v132, v132
	v_fmac_f32_e32 v126, v134, v134
	v_add_f32_e32 v125, v125, v126
	v_add_f32_e32 v124, v124, v125
	v_mul_f32_e32 v125, v121, v121
	v_mul_f32_e32 v126, v123, v123
	v_fmac_f32_e32 v125, v120, v120
	v_fmac_f32_e32 v126, v122, v122
	v_add_f32_e32 v125, v125, v126
	v_add_f32_e32 v124, v124, v125
	v_mul_f32_e32 v125, v117, v117
	v_mul_f32_e32 v126, v119, v119
	v_fmac_f32_e32 v125, v116, v116
	v_fmac_f32_e32 v126, v118, v118
	v_add_f32_e32 v125, v125, v126
	v_add_f32_e32 v124, v124, v125
	v_mov_b32_e32 v125, v124
	s_nop 1
	v_permlane16_swap_b32_e32 v124, v125
	v_mov_b32_e32 v246, v234
	s_waitcnt lgkmcnt(0)
	v_add_f32_e32 v125, v124, v125
	v_mov_b32_e32 v126, v125
	s_nop 1
	v_permlane32_swap_b32_e32 v125, v126
	v_cmp_gt_u32_e64 s[36:37], 16, v246
	v_lshl_add_u32 v124, v246, 4, s92
	s_and_saveexec_b64 s[38:39], s[36:37]
	s_cbranch_execz .LBB0_746
	s_waitcnt lgkmcnt(0)
	v_add_f32_e32 v125, v125, v126
	ds_write_b32 v124, v125
.LBB0_746:
	s_or_b64 exec, exec, s[38:39]
	v_mul_f32_e32 v125, v113, v113
	s_waitcnt lgkmcnt(0)
	v_mul_f32_e32 v126, v115, v115
	v_fmac_f32_e32 v125, v112, v112
	v_fmac_f32_e32 v126, v114, v114
	v_add_f32_e32 v125, v125, v126
	v_mul_f32_e32 v126, v109, v109
	v_mul_f32_e32 v127, v111, v111
	v_fmac_f32_e32 v126, v108, v108
	v_fmac_f32_e32 v127, v110, v110
	v_add_f32_e32 v126, v126, v127
	v_add_f32_e32 v125, v125, v126
	v_mul_f32_e32 v126, v105, v105
	v_mul_f32_e32 v127, v107, v107
	v_fmac_f32_e32 v126, v104, v104
	v_fmac_f32_e32 v127, v106, v106
	v_add_f32_e32 v126, v126, v127
	v_add_f32_e32 v125, v125, v126
	v_mul_f32_e32 v126, v101, v101
	v_mul_f32_e32 v127, v103, v103
	v_fmac_f32_e32 v126, v100, v100
	v_fmac_f32_e32 v127, v102, v102
	v_add_f32_e32 v126, v126, v127
	v_add_f32_e32 v125, v125, v126
	v_mov_b32_e32 v126, v125
	s_nop 1
	v_permlane16_swap_b32_e32 v125, v126
	s_waitcnt lgkmcnt(0)
	v_add_f32_e32 v125, v125, v126
	v_mov_b32_e32 v126, v125
	s_nop 1
	v_permlane32_swap_b32_e32 v125, v126
	s_and_saveexec_b64 s[38:39], s[36:37]
	s_cbranch_execz .LBB0_748
	s_waitcnt lgkmcnt(0)
	v_add_f32_e32 v125, v125, v126
	ds_write_b32 v124, v125 offset:256
.LBB0_748:
	s_or_b64 exec, exec, s[38:39]
	v_mul_f32_e32 v125, v97, v97
	s_waitcnt lgkmcnt(0)
	v_mul_f32_e32 v126, v99, v99
	v_fmac_f32_e32 v125, v96, v96
	v_fmac_f32_e32 v126, v98, v98
	v_add_f32_e32 v125, v125, v126
	v_mul_f32_e32 v126, v93, v93
	v_mul_f32_e32 v127, v95, v95
	v_fmac_f32_e32 v126, v92, v92
	v_fmac_f32_e32 v127, v94, v94
	v_add_f32_e32 v126, v126, v127
	v_add_f32_e32 v125, v125, v126
	v_mul_f32_e32 v126, v89, v89
	v_mul_f32_e32 v127, v91, v91
	v_fmac_f32_e32 v126, v88, v88
	v_fmac_f32_e32 v127, v90, v90
	v_add_f32_e32 v126, v126, v127
	v_add_f32_e32 v125, v125, v126
	v_mul_f32_e32 v126, v85, v85
	v_mul_f32_e32 v127, v87, v87
	v_fmac_f32_e32 v126, v84, v84
	v_fmac_f32_e32 v127, v86, v86
	v_add_f32_e32 v126, v126, v127
	v_add_f32_e32 v125, v125, v126
	v_mov_b32_e32 v126, v125
	s_nop 1
	v_permlane16_swap_b32_e32 v125, v126
	s_waitcnt lgkmcnt(0)
	v_add_f32_e32 v125, v125, v126
	v_mov_b32_e32 v126, v125
	s_nop 1
	v_permlane32_swap_b32_e32 v125, v126
	s_and_saveexec_b64 s[38:39], s[36:37]
	s_cbranch_execz .LBB0_750
	s_waitcnt lgkmcnt(0)
	v_add_f32_e32 v125, v125, v126
	ds_write_b32 v124, v125 offset:512
.LBB0_750:
	s_or_b64 exec, exec, s[38:39]
	v_mul_f32_e32 v125, v81, v81
	s_waitcnt lgkmcnt(0)
	v_mul_f32_e32 v126, v83, v83
	v_fmac_f32_e32 v125, v80, v80
	v_fmac_f32_e32 v126, v82, v82
	v_add_f32_e32 v125, v125, v126
	v_mul_f32_e32 v126, v77, v77
	v_mul_f32_e32 v127, v79, v79
	v_fmac_f32_e32 v126, v76, v76
	v_fmac_f32_e32 v127, v78, v78
	v_add_f32_e32 v126, v126, v127
	v_add_f32_e32 v125, v125, v126
	v_mul_f32_e32 v126, v73, v73
	v_mul_f32_e32 v127, v75, v75
	v_fmac_f32_e32 v126, v72, v72
	v_fmac_f32_e32 v127, v74, v74
	v_add_f32_e32 v126, v126, v127
	v_add_f32_e32 v125, v125, v126
	v_mul_f32_e32 v126, v69, v69
	v_mul_f32_e32 v127, v71, v71
	v_fmac_f32_e32 v126, v68, v68
	v_fmac_f32_e32 v127, v70, v70
	v_add_f32_e32 v126, v126, v127
	v_add_f32_e32 v125, v125, v126
	v_mov_b32_e32 v126, v125
	s_nop 1
	v_permlane16_swap_b32_e32 v125, v126
	s_waitcnt lgkmcnt(0)
	v_add_f32_e32 v125, v125, v126
	v_mov_b32_e32 v126, v125
	s_nop 1
	v_permlane32_swap_b32_e32 v125, v126
	s_and_saveexec_b64 s[38:39], s[36:37]
	s_cbranch_execz .LBB0_752
	s_waitcnt lgkmcnt(0)
	v_add_f32_e32 v125, v125, v126
	ds_write_b32 v124, v125 offset:768
.LBB0_752:
	s_or_b64 exec, exec, s[38:39]
	v_mul_f32_e32 v125, v65, v65
	s_waitcnt lgkmcnt(0)
	v_mul_f32_e32 v126, v67, v67
	v_fmac_f32_e32 v125, v64, v64
	v_fmac_f32_e32 v126, v66, v66
	v_add_f32_e32 v125, v125, v126
	v_mul_f32_e32 v126, v61, v61
	v_mul_f32_e32 v127, v63, v63
	v_fmac_f32_e32 v126, v60, v60
	v_fmac_f32_e32 v127, v62, v62
	v_add_f32_e32 v126, v126, v127
	v_add_f32_e32 v125, v125, v126
	v_mul_f32_e32 v126, v57, v57
	v_mul_f32_e32 v127, v59, v59
	v_fmac_f32_e32 v126, v56, v56
	v_fmac_f32_e32 v127, v58, v58
	v_add_f32_e32 v126, v126, v127
	v_add_f32_e32 v125, v125, v126
	v_mul_f32_e32 v126, v53, v53
	v_mul_f32_e32 v127, v55, v55
	v_fmac_f32_e32 v126, v52, v52
	v_fmac_f32_e32 v127, v54, v54
	v_add_f32_e32 v126, v126, v127
	v_add_f32_e32 v125, v125, v126
	v_mov_b32_e32 v126, v125
	s_nop 1
	v_permlane16_swap_b32_e32 v125, v126
	s_waitcnt lgkmcnt(0)
	v_add_f32_e32 v125, v125, v126
	v_mov_b32_e32 v126, v125
	s_nop 1
	v_permlane32_swap_b32_e32 v125, v126
	s_and_saveexec_b64 s[38:39], s[36:37]
	s_cbranch_execz .LBB0_754
	s_waitcnt lgkmcnt(0)
	v_add_f32_e32 v125, v125, v126
	ds_write_b32 v124, v125 offset:2048
.LBB0_754:
	s_or_b64 exec, exec, s[38:39]
	v_mul_f32_e32 v125, v49, v49
	s_waitcnt lgkmcnt(0)
	v_mul_f32_e32 v126, v51, v51
	v_fmac_f32_e32 v125, v48, v48
	v_fmac_f32_e32 v126, v50, v50
	v_add_f32_e32 v125, v125, v126
	v_mul_f32_e32 v126, v45, v45
	v_mul_f32_e32 v127, v47, v47
	v_fmac_f32_e32 v126, v44, v44
	v_fmac_f32_e32 v127, v46, v46
	v_add_f32_e32 v126, v126, v127
	v_add_f32_e32 v125, v125, v126
	v_mul_f32_e32 v126, v41, v41
	v_mul_f32_e32 v127, v43, v43
	v_fmac_f32_e32 v126, v40, v40
	v_fmac_f32_e32 v127, v42, v42
	v_add_f32_e32 v126, v126, v127
	v_add_f32_e32 v125, v125, v126
	v_mul_f32_e32 v126, v37, v37
	v_mul_f32_e32 v127, v39, v39
	v_fmac_f32_e32 v126, v36, v36
	v_fmac_f32_e32 v127, v38, v38
	v_add_f32_e32 v126, v126, v127
	v_add_f32_e32 v125, v125, v126
	v_mov_b32_e32 v126, v125
	s_nop 1
	v_permlane16_swap_b32_e32 v125, v126
	s_waitcnt lgkmcnt(0)
	v_add_f32_e32 v125, v125, v126
	v_mov_b32_e32 v126, v125
	s_nop 1
	v_permlane32_swap_b32_e32 v125, v126
	s_and_saveexec_b64 s[38:39], s[36:37]
	s_cbranch_execz .LBB0_756
	s_waitcnt lgkmcnt(0)
	v_add_f32_e32 v125, v125, v126
	ds_write_b32 v124, v125 offset:2304
.LBB0_756:
	s_or_b64 exec, exec, s[38:39]
	v_mul_f32_e32 v125, v33, v33
	s_waitcnt lgkmcnt(0)
	v_mul_f32_e32 v126, v35, v35
	v_fmac_f32_e32 v125, v32, v32
	v_fmac_f32_e32 v126, v34, v34
	v_add_f32_e32 v125, v125, v126
	v_mul_f32_e32 v126, v29, v29
	v_mul_f32_e32 v127, v31, v31
	v_fmac_f32_e32 v126, v28, v28
	v_fmac_f32_e32 v127, v30, v30
	v_add_f32_e32 v126, v126, v127
	v_add_f32_e32 v125, v125, v126
	v_mul_f32_e32 v126, v25, v25
	v_mul_f32_e32 v127, v27, v27
	v_fmac_f32_e32 v126, v24, v24
	v_fmac_f32_e32 v127, v26, v26
	v_add_f32_e32 v126, v126, v127
	v_add_f32_e32 v125, v125, v126
	v_mul_f32_e32 v126, v21, v21
	v_mul_f32_e32 v127, v23, v23
	v_fmac_f32_e32 v126, v20, v20
	v_fmac_f32_e32 v127, v22, v22
	v_add_f32_e32 v126, v126, v127
	v_add_f32_e32 v125, v125, v126
	v_mov_b32_e32 v126, v125
	s_nop 1
	v_permlane16_swap_b32_e32 v125, v126
	s_waitcnt lgkmcnt(0)
	v_add_f32_e32 v125, v125, v126
	v_mov_b32_e32 v126, v125
	s_nop 1
	v_permlane32_swap_b32_e32 v125, v126
	s_and_saveexec_b64 s[38:39], s[36:37]
	s_cbranch_execz .LBB0_758
	s_waitcnt lgkmcnt(0)
	v_add_f32_e32 v125, v125, v126
	ds_write_b32 v124, v125 offset:2560
.LBB0_758:
	s_or_b64 exec, exec, s[38:39]
	v_mul_f32_e32 v125, v17, v17
	s_waitcnt lgkmcnt(0)
	v_mul_f32_e32 v126, v19, v19
	v_fmac_f32_e32 v125, v16, v16
	v_fmac_f32_e32 v126, v18, v18
	v_add_f32_e32 v125, v125, v126
	v_mul_f32_e32 v126, v13, v13
	v_mul_f32_e32 v127, v15, v15
	v_fmac_f32_e32 v126, v12, v12
	v_fmac_f32_e32 v127, v14, v14
	v_add_f32_e32 v126, v126, v127
	v_add_f32_e32 v125, v125, v126
	v_mul_f32_e32 v126, v9, v9
	v_mul_f32_e32 v127, v11, v11
	v_fmac_f32_e32 v126, v8, v8
	v_fmac_f32_e32 v127, v10, v10
	v_add_f32_e32 v126, v126, v127
	v_add_f32_e32 v125, v125, v126
	v_mul_f32_e32 v126, v5, v5
	v_mul_f32_e32 v127, v7, v7
	v_fmac_f32_e32 v126, v4, v4
	v_fmac_f32_e32 v127, v6, v6
	v_add_f32_e32 v126, v126, v127
	v_add_f32_e32 v125, v125, v126
	v_mov_b32_e32 v126, v125
	s_nop 1
	v_permlane16_swap_b32_e32 v125, v126
	s_waitcnt lgkmcnt(0)
	v_add_f32_e32 v125, v125, v126
	v_mov_b32_e32 v126, v125
	s_nop 1
	v_permlane32_swap_b32_e32 v125, v126
	s_and_saveexec_b64 s[38:39], s[36:37]
	s_cbranch_execz .LBB0_760
	s_waitcnt lgkmcnt(0)
	v_add_f32_e32 v125, v125, v126
	ds_write_b32 v124, v125 offset:2816

.LBB0_776:
	v_add_f32_e32 v212, v212, v213
	v_add_f32_e32 v213, v214, v215
	v_add_f32_e32 v212, v212, v213
	v_mov_b32_e32 v213, v212
	s_nop 1
	v_permlane32_swap_b32_e32 v212, v213
	s_and_saveexec_b64 s[62:63], s[38:39]
	s_cbranch_execz .LBB0_778
	s_waitcnt lgkmcnt(0)
	v_add_f32_e32 v212, v212, v213
	v_fmamk_f32 v212, v212, 0x3a000000, v232
	v_rsq_f32_e32 v212, v212
	v_lshl_add_u32 v213, v247, 2, 0
	v_add_u32_e32 v213, 0x21400, v213
	ds_write_b32 v213, v212
.LBB0_778:
	s_or_b64 exec, exec, s[62:63]
	v_or_b32_e32 v212, s87, v248
	s_waitcnt lgkmcnt(0)
	v_lshl_add_u32 v213, v212, 2, 0
	s_waitcnt lgkmcnt(0)
	s_barrier
	v_add_u32_e32 v213, 0x21400, v213
	ds_read_b32 v214, v213
	s_waitcnt vmcnt(0)
	v_lshlrev_b32_e32 v246, 16, v208
	v_and_b32_e32 v247, 0xffff0000, v208
	v_lshlrev_b32_e32 v208, 16, v209
	v_and_b32_e32 v209, 0xffff0000, v209
	s_waitcnt lgkmcnt(0)
	v_pk_mul_f32 v[142:143], v[142:143], v[214:215] op_sel_hi:[1,0]
	v_pk_mul_f32 v[140:141], v[140:141], v[214:215] op_sel_hi:[1,0]
	v_pk_fma_f32 v[142:143], v[146:147], v[142:143], v[208:209]
	v_pk_fma_f32 v[140:141], v[144:145], v[140:141], v[246:247]
	v_mul_f32_e32 v209, v143, v143
	v_mul_f32_e32 v208, v141, v141
	v_fmac_f32_e32 v208, v140, v140
	v_fmac_f32_e32 v209, v142, v142
	v_add_f32_e32 v215, v208, v209
	v_cvt_pk_bf16_f32 v140, v140, v141
	v_cvt_pk_bf16_f32 v141, v142, v143
	v_lshlrev_b32_e32 v142, 16, v210
	v_and_b32_e32 v143, 0xffff0000, v210
	v_lshlrev_b32_e32 v208, 16, v211
	v_and_b32_e32 v209, 0xffff0000, v211
	v_pk_mul_f32 v[134:135], v[134:135], v[214:215] op_sel_hi:[1,0]
	v_pk_mul_f32 v[132:133], v[132:133], v[214:215] op_sel_hi:[1,0]
	v_pk_fma_f32 v[134:135], v[138:139], v[134:135], v[208:209]
	v_pk_fma_f32 v[132:133], v[136:137], v[132:133], v[142:143]
	v_mul_f32_e32 v143, v135, v135
	v_mul_f32_e32 v142, v133, v133
	v_fmac_f32_e32 v142, v132, v132
	v_fmac_f32_e32 v143, v134, v134
	v_add_f32_e32 v142, v142, v143
	v_add_f32_e32 v208, v215, v142
	v_cvt_pk_bf16_f32 v142, v132, v133
	v_cvt_pk_bf16_f32 v143, v134, v135
	v_lshlrev_b32_e32 v134, 16, v204
	v_and_b32_e32 v135, 0xffff0000, v204
	v_lshlrev_b32_e32 v204, 16, v205
	v_and_b32_e32 v205, 0xffff0000, v205
	v_pk_mul_f32 v[122:123], v[122:123], v[214:215] op_sel_hi:[1,0]
	v_pk_mul_f32 v[120:121], v[120:121], v[214:215] op_sel_hi:[1,0]
	v_pk_fma_f32 v[122:123], v[130:131], v[122:123], v[204:205]
	v_pk_fma_f32 v[120:121], v[128:129], v[120:121], v[134:135]
	v_mul_f32_e32 v135, v123, v123
	v_mul_f32_e32 v134, v121, v121
	v_fmac_f32_e32 v134, v120, v120
	v_fmac_f32_e32 v135, v122, v122
	v_add_f32_e32 v134, v134, v135
	v_add_f32_e32 v208, v134, v208
	v_lshlrev_b32_e32 v134, 16, v206
	v_and_b32_e32 v135, 0xffff0000, v206
	v_lshlrev_b32_e32 v204, 16, v207
	v_and_b32_e32 v205, 0xffff0000, v207
	v_pk_mul_f32 v[118:119], v[118:119], v[214:215] op_sel_hi:[1,0]
	v_pk_mul_f32 v[116:117], v[116:117], v[214:215] op_sel_hi:[1,0]
	v_pk_fma_f32 v[204:205], v[126:127], v[118:119], v[204:205]
	v_pk_fma_f32 v[134:135], v[124:125], v[116:117], v[134:135]
	v_mul_f32_e32 v117, v205, v205
	v_mul_f32_e32 v116, v135, v135
	v_fmac_f32_e32 v116, v134, v134
	v_fmac_f32_e32 v117, v204, v204
	v_add_f32_e32 v116, v116, v117
	v_add_f32_e32 v119, v116, v208
	v_mov_b32_e32 v206, v119
	s_nop 1
	v_permlane16_swap_b32_e32 v119, v206
	v_add_u32_e32 v228, v212, v245
	v_ashrrev_i32_e32 v229, 31, v228
	v_lshlrev_b64 v[132:133], 12, v[228:229]
	v_lshl_add_u64 v[116:117], s[26:27], 0, v[132:133]
	v_lshl_add_u64 v[132:133], v[226:227], 1, v[116:117]
	s_waitcnt lgkmcnt(0)
	v_add_f32_e32 v116, v119, v206
	v_mov_b32_e32 v117, v116
	s_nop 1
	v_permlane32_swap_b32_e32 v116, v117
	global_store_dwordx4 v[132:133], v[140:143], off
	v_cvt_pk_bf16_f32 v118, v120, v121
	v_cvt_pk_bf16_f32 v119, v122, v123
	v_cvt_pk_bf16_f32 v120, v134, v135
	v_cvt_pk_bf16_f32 v121, v204, v205
	global_store_dwordx4 v[132:133], v[118:121], off offset:256
	s_and_saveexec_b64 s[62:63], s[36:37]
	s_cbranch_execz .LBB0_780
	v_lshl_add_u32 v118, v212, 4, s91
	s_waitcnt lgkmcnt(0)
	v_add_f32_e32 v116, v116, v117
	ds_write_b32 v118, v116
.LBB0_780:
	s_or_b64 exec, exec, s[62:63]
	v_or_b32_e32 v116, 16, v212
	s_waitcnt lgkmcnt(0)
	v_lshl_add_u32 v117, v116, 2, 0
	v_add_u32_e32 v117, 0x21400, v117
	ds_read_b32 v118, v117
	v_lshlrev_b32_e32 v132, 16, v201
	v_and_b32_e32 v133, 0xffff0000, v201
	v_lshlrev_b32_e32 v122, 16, v200
	v_and_b32_e32 v123, 0xffff0000, v200
	s_waitcnt lgkmcnt(0)
	v_pk_mul_f32 v[114:115], v[114:115], v[118:119] op_sel_hi:[1,0]
	v_pk_mul_f32 v[112:113], v[112:113], v[118:119] op_sel_hi:[1,0]
	v_pk_fma_f32 v[114:115], v[146:147], v[114:115], v[132:133]
	v_pk_fma_f32 v[112:113], v[144:145], v[112:113], v[122:123]
	v_mul_f32_e32 v119, v115, v115
	v_mul_f32_e32 v117, v113, v113
	v_fmac_f32_e32 v119, v114, v114
	v_fmac_f32_e32 v117, v112, v112
	v_cvt_pk_bf16_f32 v112, v112, v113
	v_cvt_pk_bf16_f32 v113, v114, v115
	v_lshlrev_b32_e32 v114, 16, v202
	v_and_b32_e32 v115, 0xffff0000, v202
	v_lshlrev_b32_e32 v122, 16, v203
	v_and_b32_e32 v123, 0xffff0000, v203
	v_pk_mul_f32 v[110:111], v[110:111], v[118:119] op_sel_hi:[1,0]
	v_pk_mul_f32 v[108:109], v[108:109], v[118:119] op_sel_hi:[1,0]
	v_pk_fma_f32 v[110:111], v[138:139], v[110:111], v[122:123]
	v_pk_fma_f32 v[108:109], v[136:137], v[108:109], v[114:115]
	v_mul_f32_e32 v115, v111, v111
	v_mul_f32_e32 v114, v109, v109
	v_add_u32_e32 v120, v116, v245
	v_fmac_f32_e32 v114, v108, v108
	v_fmac_f32_e32 v115, v110, v110
	v_ashrrev_i32_e32 v121, 31, v120
	v_add_f32_e32 v117, v117, v119
	v_add_f32_e32 v114, v114, v115
	v_add_f32_e32 v117, v117, v114
	v_cvt_pk_bf16_f32 v114, v108, v109
	v_cvt_pk_bf16_f32 v115, v110, v111
	v_lshlrev_b64 v[108:109], 12, v[120:121]
	v_lshlrev_b32_e32 v110, 16, v196
	v_and_b32_e32 v111, 0xffff0000, v196
	v_lshlrev_b32_e32 v120, 16, v197
	v_and_b32_e32 v121, 0xffff0000, v197
	v_pk_mul_f32 v[106:107], v[106:107], v[118:119] op_sel_hi:[1,0]
	v_pk_mul_f32 v[104:105], v[104:105], v[118:119] op_sel_hi:[1,0]
	v_pk_fma_f32 v[106:107], v[130:131], v[106:107], v[120:121]
	v_pk_fma_f32 v[104:105], v[128:129], v[104:105], v[110:111]
	v_mul_f32_e32 v111, v107, v107
	v_mul_f32_e32 v110, v105, v105
	v_fmac_f32_e32 v110, v104, v104
	v_fmac_f32_e32 v111, v106, v106
	v_add_f32_e32 v110, v110, v111
	v_add_f32_e32 v117, v110, v117
	v_lshlrev_b32_e32 v110, 16, v198
	v_and_b32_e32 v111, 0xffff0000, v198
	v_lshlrev_b32_e32 v120, 16, v199
	v_and_b32_e32 v121, 0xffff0000, v199
	v_pk_mul_f32 v[102:103], v[102:103], v[118:119] op_sel_hi:[1,0]
	v_pk_mul_f32 v[100:101], v[100:101], v[118:119] op_sel_hi:[1,0]
	v_pk_fma_f32 v[118:119], v[126:127], v[102:103], v[120:121]
	v_pk_fma_f32 v[110:111], v[124:125], v[100:101], v[110:111]
	v_mul_f32_e32 v101, v119, v119
	v_mul_f32_e32 v100, v111, v111
	v_fmac_f32_e32 v100, v110, v110
	v_fmac_f32_e32 v101, v118, v118
	v_add_f32_e32 v100, v100, v101
	v_add_f32_e32 v103, v100, v117
	v_mov_b32_e32 v117, v103
	s_nop 1
	v_permlane16_swap_b32_e32 v103, v117
	v_lshl_add_u64 v[100:101], s[26:27], 0, v[108:109]
	v_lshl_add_u64 v[108:109], v[226:227], 1, v[100:101]
	global_store_dwordx4 v[108:109], v[112:115], off
	v_cvt_pk_bf16_f32 v102, v104, v105
	s_waitcnt lgkmcnt(0)
	v_add_f32_e32 v100, v103, v117
	v_mov_b32_e32 v101, v100
	s_nop 1
	v_permlane32_swap_b32_e32 v100, v101
	v_cvt_pk_bf16_f32 v103, v106, v107
	v_cvt_pk_bf16_f32 v104, v110, v111
	v_cvt_pk_bf16_f32 v105, v118, v119
	global_store_dwordx4 v[108:109], v[102:105], off offset:256
	s_and_saveexec_b64 s[62:63], s[36:37]
	s_cbranch_execz .LBB0_782
	v_lshl_add_u32 v102, v116, 4, s91
	s_waitcnt lgkmcnt(0)
	v_add_f32_e32 v100, v100, v101
	ds_write_b32 v102, v100
.LBB0_782:
	s_or_b64 exec, exec, s[62:63]
	v_or_b32_e32 v100, 32, v212
	s_waitcnt lgkmcnt(0)
	v_lshl_add_u32 v101, v100, 2, 0
	v_add_u32_e32 v101, 0x21400, v101
	ds_read_b32 v102, v101
	v_lshlrev_b32_e32 v108, 16, v193
	v_and_b32_e32 v109, 0xffff0000, v193
	v_lshlrev_b32_e32 v106, 16, v192
	v_and_b32_e32 v107, 0xffff0000, v192
	s_waitcnt lgkmcnt(0)
	v_pk_mul_f32 v[98:99], v[98:99], v[102:103] op_sel_hi:[1,0]
	v_pk_mul_f32 v[96:97], v[96:97], v[102:103] op_sel_hi:[1,0]
	v_pk_fma_f32 v[98:99], v[146:147], v[98:99], v[108:109]
	v_pk_fma_f32 v[96:97], v[144:145], v[96:97], v[106:107]
	v_mul_f32_e32 v103, v99, v99
	v_mul_f32_e32 v101, v97, v97
	v_fmac_f32_e32 v103, v98, v98
	v_fmac_f32_e32 v101, v96, v96
	v_cvt_pk_bf16_f32 v96, v96, v97
	v_cvt_pk_bf16_f32 v97, v98, v99
	v_lshlrev_b32_e32 v98, 16, v194
	v_and_b32_e32 v99, 0xffff0000, v194
	v_lshlrev_b32_e32 v106, 16, v195
	v_and_b32_e32 v107, 0xffff0000, v195
	v_pk_mul_f32 v[94:95], v[94:95], v[102:103] op_sel_hi:[1,0]
	v_pk_mul_f32 v[92:93], v[92:93], v[102:103] op_sel_hi:[1,0]
	v_pk_fma_f32 v[94:95], v[138:139], v[94:95], v[106:107]
	v_pk_fma_f32 v[92:93], v[136:137], v[92:93], v[98:99]
	v_mul_f32_e32 v99, v95, v95
	v_mul_f32_e32 v98, v93, v93
	v_add_u32_e32 v104, v100, v245
	v_fmac_f32_e32 v98, v92, v92
	v_fmac_f32_e32 v99, v94, v94
	v_ashrrev_i32_e32 v105, 31, v104
	v_add_f32_e32 v101, v101, v103
	v_add_f32_e32 v98, v98, v99
	v_add_f32_e32 v101, v101, v98
	v_cvt_pk_bf16_f32 v98, v92, v93
	v_cvt_pk_bf16_f32 v99, v94, v95
	v_lshlrev_b64 v[92:93], 12, v[104:105]
	v_lshlrev_b32_e32 v94, 16, v188
	v_and_b32_e32 v95, 0xffff0000, v188
	v_lshlrev_b32_e32 v104, 16, v189
	v_and_b32_e32 v105, 0xffff0000, v189
	v_pk_mul_f32 v[90:91], v[90:91], v[102:103] op_sel_hi:[1,0]
	v_pk_mul_f32 v[88:89], v[88:89], v[102:103] op_sel_hi:[1,0]
	v_pk_fma_f32 v[90:91], v[130:131], v[90:91], v[104:105]
	v_pk_fma_f32 v[88:89], v[128:129], v[88:89], v[94:95]
	v_mul_f32_e32 v95, v91, v91
	v_mul_f32_e32 v94, v89, v89
	v_fmac_f32_e32 v94, v88, v88
	v_fmac_f32_e32 v95, v90, v90
	v_add_f32_e32 v94, v94, v95
	v_add_f32_e32 v101, v94, v101
	v_lshlrev_b32_e32 v94, 16, v190
	v_and_b32_e32 v95, 0xffff0000, v190
	v_lshlrev_b32_e32 v104, 16, v191
	v_and_b32_e32 v105, 0xffff0000, v191
	v_pk_mul_f32 v[86:87], v[86:87], v[102:103] op_sel_hi:[1,0]
	v_pk_mul_f32 v[84:85], v[84:85], v[102:103] op_sel_hi:[1,0]
	v_pk_fma_f32 v[102:103], v[126:127], v[86:87], v[104:105]
	v_pk_fma_f32 v[94:95], v[124:125], v[84:85], v[94:95]
	v_mul_f32_e32 v85, v103, v103
	v_mul_f32_e32 v84, v95, v95
	v_fmac_f32_e32 v84, v94, v94
	v_fmac_f32_e32 v85, v102, v102
	v_add_f32_e32 v84, v84, v85
	v_add_f32_e32 v87, v84, v101
	v_mov_b32_e32 v101, v87
	s_nop 1
	v_permlane16_swap_b32_e32 v87, v101
	v_lshl_add_u64 v[84:85], s[26:27], 0, v[92:93]
	v_lshl_add_u64 v[92:93], v[226:227], 1, v[84:85]
	global_store_dwordx4 v[92:93], v[96:99], off
	v_cvt_pk_bf16_f32 v86, v88, v89
	s_waitcnt lgkmcnt(0)
	v_add_f32_e32 v84, v87, v101
	v_mov_b32_e32 v85, v84
	s_nop 1
	v_permlane32_swap_b32_e32 v84, v85
	v_cvt_pk_bf16_f32 v87, v90, v91
	v_cvt_pk_bf16_f32 v88, v94, v95
	v_cvt_pk_bf16_f32 v89, v102, v103
	global_store_dwordx4 v[92:93], v[86:89], off offset:256
	s_and_saveexec_b64 s[62:63], s[36:37]
	s_cbranch_execz .LBB0_784
	v_lshl_add_u32 v86, v100, 4, s91
	s_waitcnt lgkmcnt(0)
	v_add_f32_e32 v84, v84, v85
	ds_write_b32 v86, v84
.LBB0_784:
	s_or_b64 exec, exec, s[62:63]
	v_or_b32_e32 v84, 48, v212
	s_waitcnt lgkmcnt(0)
	v_lshl_add_u32 v85, v84, 2, 0
	v_add_u32_e32 v85, 0x21400, v85
	ds_read_b32 v86, v85
	v_lshlrev_b32_e32 v92, 16, v185
	v_and_b32_e32 v93, 0xffff0000, v185
	v_lshlrev_b32_e32 v90, 16, v184
	v_and_b32_e32 v91, 0xffff0000, v184
	s_waitcnt lgkmcnt(0)
	v_pk_mul_f32 v[82:83], v[82:83], v[86:87] op_sel_hi:[1,0]
	v_pk_mul_f32 v[80:81], v[80:81], v[86:87] op_sel_hi:[1,0]
	v_pk_fma_f32 v[82:83], v[146:147], v[82:83], v[92:93]
	v_pk_fma_f32 v[80:81], v[144:145], v[80:81], v[90:91]
	v_mul_f32_e32 v87, v83, v83
	v_mul_f32_e32 v85, v81, v81
	v_fmac_f32_e32 v87, v82, v82
	v_fmac_f32_e32 v85, v80, v80
	v_cvt_pk_bf16_f32 v80, v80, v81
	v_cvt_pk_bf16_f32 v81, v82, v83
	v_lshlrev_b32_e32 v82, 16, v186
	v_and_b32_e32 v83, 0xffff0000, v186
	v_lshlrev_b32_e32 v90, 16, v187
	v_and_b32_e32 v91, 0xffff0000, v187
	v_pk_mul_f32 v[78:79], v[78:79], v[86:87] op_sel_hi:[1,0]
	v_pk_mul_f32 v[76:77], v[76:77], v[86:87] op_sel_hi:[1,0]
	v_pk_fma_f32 v[78:79], v[138:139], v[78:79], v[90:91]
	v_pk_fma_f32 v[76:77], v[136:137], v[76:77], v[82:83]
	v_mul_f32_e32 v83, v79, v79
	v_mul_f32_e32 v82, v77, v77
	v_add_u32_e32 v88, v84, v245
	v_fmac_f32_e32 v82, v76, v76
	v_fmac_f32_e32 v83, v78, v78
	v_ashrrev_i32_e32 v89, 31, v88
	v_add_f32_e32 v85, v85, v87
	v_add_f32_e32 v82, v82, v83
	v_add_f32_e32 v85, v85, v82
	v_cvt_pk_bf16_f32 v82, v76, v77
	v_cvt_pk_bf16_f32 v83, v78, v79
	v_lshlrev_b64 v[76:77], 12, v[88:89]
	v_lshlrev_b32_e32 v78, 16, v180
	v_and_b32_e32 v79, 0xffff0000, v180
	v_lshlrev_b32_e32 v88, 16, v181
	v_and_b32_e32 v89, 0xffff0000, v181
	v_pk_mul_f32 v[74:75], v[74:75], v[86:87] op_sel_hi:[1,0]
	v_pk_mul_f32 v[72:73], v[72:73], v[86:87] op_sel_hi:[1,0]
	v_pk_fma_f32 v[74:75], v[130:131], v[74:75], v[88:89]
	v_pk_fma_f32 v[72:73], v[128:129], v[72:73], v[78:79]
	v_mul_f32_e32 v79, v75, v75
	v_mul_f32_e32 v78, v73, v73
	v_fmac_f32_e32 v78, v72, v72
	v_fmac_f32_e32 v79, v74, v74
	v_add_f32_e32 v78, v78, v79
	v_add_f32_e32 v85, v78, v85
	v_lshlrev_b32_e32 v78, 16, v182
	v_and_b32_e32 v79, 0xffff0000, v182
	v_lshlrev_b32_e32 v88, 16, v183
	v_and_b32_e32 v89, 0xffff0000, v183
	v_pk_mul_f32 v[70:71], v[70:71], v[86:87] op_sel_hi:[1,0]
	v_pk_mul_f32 v[68:69], v[68:69], v[86:87] op_sel_hi:[1,0]
	v_pk_fma_f32 v[86:87], v[126:127], v[70:71], v[88:89]
	v_pk_fma_f32 v[78:79], v[124:125], v[68:69], v[78:79]
	v_mul_f32_e32 v69, v87, v87
	v_mul_f32_e32 v68, v79, v79
	v_fmac_f32_e32 v68, v78, v78
	v_fmac_f32_e32 v69, v86, v86
	v_add_f32_e32 v68, v68, v69
	v_add_f32_e32 v71, v68, v85
	ds_bpermute_b32 v85, v231, v71
	v_lshl_add_u64 v[68:69], s[26:27], 0, v[76:77]
	v_lshl_add_u64 v[76:77], v[226:227], 1, v[68:69]
	global_store_dwordx4 v[76:77], v[80:83], off
	v_cvt_pk_bf16_f32 v70, v72, v73
	s_waitcnt lgkmcnt(0)
	v_add_f32_e32 v68, v71, v85
	v_mov_b32_e32 v69, v68
	s_nop 1
	v_permlane32_swap_b32_e32 v68, v69
	v_cvt_pk_bf16_f32 v71, v74, v75
	v_cvt_pk_bf16_f32 v72, v78, v79
	v_cvt_pk_bf16_f32 v73, v86, v87
	global_store_dwordx4 v[76:77], v[70:73], off offset:256
	s_and_saveexec_b64 s[62:63], s[36:37]
	s_cbranch_execz .LBB0_786
	v_lshl_add_u32 v70, v84, 4, s91
	s_waitcnt lgkmcnt(0)
	v_add_f32_e32 v68, v68, v69
	ds_write_b32 v70, v68
.LBB0_786:
	s_or_b64 exec, exec, s[62:63]
	ds_read_b32 v70, v213 offset:512
	v_lshlrev_b32_e32 v76, 16, v177
	v_and_b32_e32 v77, 0xffff0000, v177
	v_lshlrev_b32_e32 v74, 16, v176
	v_and_b32_e32 v75, 0xffff0000, v176
	s_waitcnt lgkmcnt(0)
	v_pk_mul_f32 v[66:67], v[66:67], v[70:71] op_sel_hi:[1,0]
	v_pk_mul_f32 v[64:65], v[64:65], v[70:71] op_sel_hi:[1,0]
	v_pk_fma_f32 v[66:67], v[146:147], v[66:67], v[76:77]
	v_pk_fma_f32 v[64:65], v[144:145], v[64:65], v[74:75]
	v_mul_f32_e32 v71, v67, v67
	v_mul_f32_e32 v69, v65, v65
	v_fmac_f32_e32 v71, v66, v66
	v_fmac_f32_e32 v69, v64, v64
	v_cvt_pk_bf16_f32 v64, v64, v65
	v_cvt_pk_bf16_f32 v65, v66, v67
	v_lshlrev_b32_e32 v66, 16, v178
	v_and_b32_e32 v67, 0xffff0000, v178
	v_lshlrev_b32_e32 v74, 16, v179
	v_and_b32_e32 v75, 0xffff0000, v179
	v_pk_mul_f32 v[62:63], v[62:63], v[70:71] op_sel_hi:[1,0]
	v_pk_mul_f32 v[60:61], v[60:61], v[70:71] op_sel_hi:[1,0]
	v_pk_fma_f32 v[62:63], v[138:139], v[62:63], v[74:75]
	v_pk_fma_f32 v[60:61], v[136:137], v[60:61], v[66:67]
	v_add_u32_e32 v68, 0x80, v212
	v_mul_f32_e32 v66, v61, v61
	v_mul_f32_e32 v67, v63, v63
	v_add_u32_e32 v72, v68, v245
	v_fmac_f32_e32 v66, v60, v60
	v_fmac_f32_e32 v67, v62, v62
	v_ashrrev_i32_e32 v73, 31, v72
	v_add_f32_e32 v69, v69, v71
	v_add_f32_e32 v66, v66, v67
	v_add_f32_e32 v69, v69, v66
	v_cvt_pk_bf16_f32 v66, v60, v61
	v_cvt_pk_bf16_f32 v67, v62, v63
	v_lshlrev_b64 v[60:61], 12, v[72:73]
	v_lshlrev_b32_e32 v62, 16, v172
	v_and_b32_e32 v63, 0xffff0000, v172
	v_lshlrev_b32_e32 v72, 16, v173
	v_and_b32_e32 v73, 0xffff0000, v173
	v_pk_mul_f32 v[58:59], v[58:59], v[70:71] op_sel_hi:[1,0]
	v_pk_mul_f32 v[56:57], v[56:57], v[70:71] op_sel_hi:[1,0]
	v_pk_fma_f32 v[58:59], v[130:131], v[58:59], v[72:73]
	v_pk_fma_f32 v[56:57], v[128:129], v[56:57], v[62:63]
	v_mul_f32_e32 v63, v59, v59
	v_mul_f32_e32 v62, v57, v57
	v_fmac_f32_e32 v62, v56, v56
	v_fmac_f32_e32 v63, v58, v58
	v_add_f32_e32 v62, v62, v63
	v_add_f32_e32 v69, v62, v69
	v_lshlrev_b32_e32 v62, 16, v174
	v_and_b32_e32 v63, 0xffff0000, v174
	v_lshlrev_b32_e32 v72, 16, v175
	v_and_b32_e32 v73, 0xffff0000, v175
	v_pk_mul_f32 v[54:55], v[54:55], v[70:71] op_sel_hi:[1,0]
	v_pk_mul_f32 v[52:53], v[52:53], v[70:71] op_sel_hi:[1,0]
	v_pk_fma_f32 v[70:71], v[126:127], v[54:55], v[72:73]
	v_pk_fma_f32 v[62:63], v[124:125], v[52:53], v[62:63]
	v_mul_f32_e32 v53, v71, v71
	v_mul_f32_e32 v52, v63, v63
	v_fmac_f32_e32 v52, v62, v62
	v_fmac_f32_e32 v53, v70, v70
	v_add_f32_e32 v52, v52, v53
	v_add_f32_e32 v55, v52, v69
	v_mov_b32_e32 v69, v55
	s_nop 1
	v_permlane16_swap_b32_e32 v55, v69
	v_lshl_add_u64 v[52:53], s[26:27], 0, v[60:61]
	v_lshl_add_u64 v[60:61], v[226:227], 1, v[52:53]
	global_store_dwordx4 v[60:61], v[64:67], off
	v_cvt_pk_bf16_f32 v54, v56, v57
	s_waitcnt lgkmcnt(0)
	v_add_f32_e32 v52, v55, v69
	v_mov_b32_e32 v53, v52
	s_nop 1
	v_permlane32_swap_b32_e32 v52, v53
	v_cvt_pk_bf16_f32 v55, v58, v59
	v_cvt_pk_bf16_f32 v56, v62, v63
	v_cvt_pk_bf16_f32 v57, v70, v71
	global_store_dwordx4 v[60:61], v[54:57], off offset:256
	s_and_saveexec_b64 s[62:63], s[36:37]
	s_cbranch_execz .LBB0_788
	v_lshl_add_u32 v54, v68, 4, s91
	s_waitcnt lgkmcnt(0)
	v_add_f32_e32 v52, v52, v53
	ds_write_b32 v54, v52
.LBB0_788:
	s_or_b64 exec, exec, s[62:63]
	ds_read_b32 v54, v213 offset:576
	v_lshlrev_b32_e32 v60, 16, v169
	v_and_b32_e32 v61, 0xffff0000, v169
	v_lshlrev_b32_e32 v58, 16, v168
	v_and_b32_e32 v59, 0xffff0000, v168
	s_waitcnt lgkmcnt(0)
	v_pk_mul_f32 v[50:51], v[50:51], v[54:55] op_sel_hi:[1,0]
	v_pk_mul_f32 v[48:49], v[48:49], v[54:55] op_sel_hi:[1,0]
	v_pk_fma_f32 v[50:51], v[146:147], v[50:51], v[60:61]
	v_pk_fma_f32 v[48:49], v[144:145], v[48:49], v[58:59]
	v_mul_f32_e32 v55, v51, v51
	v_mul_f32_e32 v53, v49, v49
	v_fmac_f32_e32 v55, v50, v50
	v_fmac_f32_e32 v53, v48, v48
	v_cvt_pk_bf16_f32 v48, v48, v49
	v_cvt_pk_bf16_f32 v49, v50, v51
	v_lshlrev_b32_e32 v50, 16, v170
	v_and_b32_e32 v51, 0xffff0000, v170
	v_lshlrev_b32_e32 v58, 16, v171
	v_and_b32_e32 v59, 0xffff0000, v171
	v_pk_mul_f32 v[46:47], v[46:47], v[54:55] op_sel_hi:[1,0]
	v_pk_mul_f32 v[44:45], v[44:45], v[54:55] op_sel_hi:[1,0]
	v_pk_fma_f32 v[46:47], v[138:139], v[46:47], v[58:59]
	v_pk_fma_f32 v[44:45], v[136:137], v[44:45], v[50:51]
	v_add_u32_e32 v52, 0x90, v212
	v_mul_f32_e32 v50, v45, v45
	v_mul_f32_e32 v51, v47, v47
	v_add_u32_e32 v56, v52, v245
	v_fmac_f32_e32 v50, v44, v44
	v_fmac_f32_e32 v51, v46, v46
	v_ashrrev_i32_e32 v57, 31, v56
	v_add_f32_e32 v53, v53, v55
	v_add_f32_e32 v50, v50, v51
	v_add_f32_e32 v53, v53, v50
	v_cvt_pk_bf16_f32 v50, v44, v45
	v_cvt_pk_bf16_f32 v51, v46, v47
	v_lshlrev_b64 v[44:45], 12, v[56:57]
	v_lshlrev_b32_e32 v46, 16, v164
	v_and_b32_e32 v47, 0xffff0000, v164
	v_lshlrev_b32_e32 v56, 16, v165
	v_and_b32_e32 v57, 0xffff0000, v165
	v_pk_mul_f32 v[42:43], v[42:43], v[54:55] op_sel_hi:[1,0]
	v_pk_mul_f32 v[40:41], v[40:41], v[54:55] op_sel_hi:[1,0]
	v_pk_fma_f32 v[42:43], v[130:131], v[42:43], v[56:57]
	v_pk_fma_f32 v[40:41], v[128:129], v[40:41], v[46:47]
	v_mul_f32_e32 v47, v43, v43
	v_mul_f32_e32 v46, v41, v41
	v_fmac_f32_e32 v46, v40, v40
	v_fmac_f32_e32 v47, v42, v42
	v_add_f32_e32 v46, v46, v47
	v_add_f32_e32 v53, v46, v53
	v_lshlrev_b32_e32 v46, 16, v166
	v_and_b32_e32 v47, 0xffff0000, v166
	v_lshlrev_b32_e32 v56, 16, v167
	v_and_b32_e32 v57, 0xffff0000, v167
	v_pk_mul_f32 v[38:39], v[38:39], v[54:55] op_sel_hi:[1,0]
	v_pk_mul_f32 v[36:37], v[36:37], v[54:55] op_sel_hi:[1,0]
	v_pk_fma_f32 v[54:55], v[126:127], v[38:39], v[56:57]
	v_pk_fma_f32 v[46:47], v[124:125], v[36:37], v[46:47]
	v_mul_f32_e32 v37, v55, v55
	v_mul_f32_e32 v36, v47, v47
	v_fmac_f32_e32 v36, v46, v46
	v_fmac_f32_e32 v37, v54, v54
	v_add_f32_e32 v36, v36, v37
	v_add_f32_e32 v39, v36, v53
	v_mov_b32_e32 v53, v39
	s_nop 1
	v_permlane16_swap_b32_e32 v39, v53
	v_lshl_add_u64 v[36:37], s[26:27], 0, v[44:45]
	v_lshl_add_u64 v[44:45], v[226:227], 1, v[36:37]
	global_store_dwordx4 v[44:45], v[48:51], off
	v_cvt_pk_bf16_f32 v38, v40, v41
	s_waitcnt lgkmcnt(0)
	v_add_f32_e32 v36, v39, v53
	v_mov_b32_e32 v37, v36
	s_nop 1
	v_permlane32_swap_b32_e32 v36, v37
	v_cvt_pk_bf16_f32 v39, v42, v43
	v_cvt_pk_bf16_f32 v40, v46, v47
	v_cvt_pk_bf16_f32 v41, v54, v55
	global_store_dwordx4 v[44:45], v[38:41], off offset:256
	s_and_saveexec_b64 s[62:63], s[36:37]
	s_cbranch_execz .LBB0_790
	v_lshl_add_u32 v38, v52, 4, s91
	s_waitcnt lgkmcnt(0)
	v_add_f32_e32 v36, v36, v37
	ds_write_b32 v38, v36
.LBB0_790:
	s_or_b64 exec, exec, s[62:63]
	ds_read_b32 v38, v213 offset:640
	v_lshlrev_b32_e32 v44, 16, v161
	v_and_b32_e32 v45, 0xffff0000, v161
	v_lshlrev_b32_e32 v42, 16, v160
	v_and_b32_e32 v43, 0xffff0000, v160
	s_waitcnt lgkmcnt(0)
	v_pk_mul_f32 v[34:35], v[34:35], v[38:39] op_sel_hi:[1,0]
	v_pk_mul_f32 v[32:33], v[32:33], v[38:39] op_sel_hi:[1,0]
	v_pk_fma_f32 v[34:35], v[146:147], v[34:35], v[44:45]
	v_pk_fma_f32 v[32:33], v[144:145], v[32:33], v[42:43]
	v_mul_f32_e32 v39, v35, v35
	v_mul_f32_e32 v37, v33, v33
	v_fmac_f32_e32 v39, v34, v34
	v_fmac_f32_e32 v37, v32, v32
	v_cvt_pk_bf16_f32 v32, v32, v33
	v_cvt_pk_bf16_f32 v33, v34, v35
	v_lshlrev_b32_e32 v34, 16, v162
	v_and_b32_e32 v35, 0xffff0000, v162
	v_lshlrev_b32_e32 v42, 16, v163
	v_and_b32_e32 v43, 0xffff0000, v163
	v_pk_mul_f32 v[30:31], v[30:31], v[38:39] op_sel_hi:[1,0]
	v_pk_mul_f32 v[28:29], v[28:29], v[38:39] op_sel_hi:[1,0]
	v_pk_fma_f32 v[30:31], v[138:139], v[30:31], v[42:43]
	v_pk_fma_f32 v[28:29], v[136:137], v[28:29], v[34:35]
	v_add_u32_e32 v36, 0xa0, v212
	v_mul_f32_e32 v34, v29, v29
	v_mul_f32_e32 v35, v31, v31
	v_add_u32_e32 v40, v36, v245
	v_fmac_f32_e32 v34, v28, v28
	v_fmac_f32_e32 v35, v30, v30
	v_ashrrev_i32_e32 v41, 31, v40
	v_add_f32_e32 v37, v37, v39
	v_add_f32_e32 v34, v34, v35
	v_add_f32_e32 v37, v37, v34
	v_cvt_pk_bf16_f32 v34, v28, v29
	v_cvt_pk_bf16_f32 v35, v30, v31
	v_lshlrev_b64 v[28:29], 12, v[40:41]
	v_lshlrev_b32_e32 v30, 16, v156
	v_and_b32_e32 v31, 0xffff0000, v156
	v_lshlrev_b32_e32 v40, 16, v157
	v_and_b32_e32 v41, 0xffff0000, v157
	v_pk_mul_f32 v[26:27], v[26:27], v[38:39] op_sel_hi:[1,0]
	v_pk_mul_f32 v[24:25], v[24:25], v[38:39] op_sel_hi:[1,0]
	v_pk_fma_f32 v[26:27], v[130:131], v[26:27], v[40:41]
	v_pk_fma_f32 v[24:25], v[128:129], v[24:25], v[30:31]
	v_mul_f32_e32 v31, v27, v27
	v_mul_f32_e32 v30, v25, v25
	v_fmac_f32_e32 v30, v24, v24
	v_fmac_f32_e32 v31, v26, v26
	v_add_f32_e32 v30, v30, v31
	v_add_f32_e32 v37, v30, v37
	v_lshlrev_b32_e32 v30, 16, v158
	v_and_b32_e32 v31, 0xffff0000, v158
	v_lshlrev_b32_e32 v40, 16, v159
	v_and_b32_e32 v41, 0xffff0000, v159
	v_pk_mul_f32 v[22:23], v[22:23], v[38:39] op_sel_hi:[1,0]
	v_pk_mul_f32 v[20:21], v[20:21], v[38:39] op_sel_hi:[1,0]
	v_pk_fma_f32 v[38:39], v[126:127], v[22:23], v[40:41]
	v_pk_fma_f32 v[30:31], v[124:125], v[20:21], v[30:31]
	v_mul_f32_e32 v21, v39, v39
	v_mul_f32_e32 v20, v31, v31
	v_fmac_f32_e32 v20, v30, v30
	v_fmac_f32_e32 v21, v38, v38
	v_add_f32_e32 v20, v20, v21
	v_add_f32_e32 v23, v20, v37
	v_mov_b32_e32 v37, v23
	s_nop 1
	v_permlane16_swap_b32_e32 v23, v37
	v_lshl_add_u64 v[20:21], s[26:27], 0, v[28:29]
	v_lshl_add_u64 v[28:29], v[226:227], 1, v[20:21]
	global_store_dwordx4 v[28:29], v[32:35], off
	v_cvt_pk_bf16_f32 v22, v24, v25
	s_waitcnt lgkmcnt(0)
	v_add_f32_e32 v20, v23, v37
	v_mov_b32_e32 v21, v20
	s_nop 1
	v_permlane32_swap_b32_e32 v20, v21
	v_cvt_pk_bf16_f32 v23, v26, v27
	v_cvt_pk_bf16_f32 v24, v30, v31
	v_cvt_pk_bf16_f32 v25, v38, v39
	global_store_dwordx4 v[28:29], v[22:25], off offset:256
	s_and_saveexec_b64 s[62:63], s[36:37]
	s_cbranch_execz .LBB0_792
	v_lshl_add_u32 v22, v36, 4, s91
	s_waitcnt lgkmcnt(0)
	v_add_f32_e32 v20, v20, v21
	ds_write_b32 v22, v20
.LBB0_792:
	s_or_b64 exec, exec, s[62:63]
	ds_read_b32 v22, v213 offset:704
	v_lshlrev_b32_e32 v28, 16, v153
	v_and_b32_e32 v29, 0xffff0000, v153
	v_lshlrev_b32_e32 v26, 16, v152
	v_and_b32_e32 v27, 0xffff0000, v152
	s_waitcnt lgkmcnt(0)
	v_pk_mul_f32 v[18:19], v[18:19], v[22:23] op_sel_hi:[1,0]
	v_pk_mul_f32 v[16:17], v[16:17], v[22:23] op_sel_hi:[1,0]
	v_pk_fma_f32 v[18:19], v[146:147], v[18:19], v[28:29]
	v_pk_fma_f32 v[16:17], v[144:145], v[16:17], v[26:27]
	v_mul_f32_e32 v23, v19, v19
	v_mul_f32_e32 v21, v17, v17
	v_fmac_f32_e32 v23, v18, v18
	v_fmac_f32_e32 v21, v16, v16
	v_cvt_pk_bf16_f32 v16, v16, v17
	v_cvt_pk_bf16_f32 v17, v18, v19
	v_lshlrev_b32_e32 v18, 16, v154
	v_and_b32_e32 v19, 0xffff0000, v154
	v_lshlrev_b32_e32 v26, 16, v155
	v_and_b32_e32 v27, 0xffff0000, v155
	v_pk_mul_f32 v[14:15], v[14:15], v[22:23] op_sel_hi:[1,0]
	v_pk_mul_f32 v[12:13], v[12:13], v[22:23] op_sel_hi:[1,0]
	v_pk_fma_f32 v[14:15], v[138:139], v[14:15], v[26:27]
	v_pk_fma_f32 v[12:13], v[136:137], v[12:13], v[18:19]
	v_add_u32_e32 v20, 0xb0, v212
	v_mul_f32_e32 v18, v13, v13
	v_mul_f32_e32 v19, v15, v15
	v_add_u32_e32 v24, v20, v245
	v_fmac_f32_e32 v18, v12, v12
	v_fmac_f32_e32 v19, v14, v14
	v_ashrrev_i32_e32 v25, 31, v24
	v_add_f32_e32 v21, v21, v23
	v_add_f32_e32 v18, v18, v19
	v_add_f32_e32 v21, v21, v18
	v_cvt_pk_bf16_f32 v18, v12, v13
	v_cvt_pk_bf16_f32 v19, v14, v15
	v_lshlrev_b64 v[12:13], 12, v[24:25]
	v_lshlrev_b32_e32 v14, 16, v148
	v_and_b32_e32 v15, 0xffff0000, v148
	v_lshlrev_b32_e32 v24, 16, v149
	v_and_b32_e32 v25, 0xffff0000, v149
	v_pk_mul_f32 v[10:11], v[10:11], v[22:23] op_sel_hi:[1,0]
	v_pk_mul_f32 v[8:9], v[8:9], v[22:23] op_sel_hi:[1,0]
	v_pk_fma_f32 v[10:11], v[130:131], v[10:11], v[24:25]
	v_pk_fma_f32 v[8:9], v[128:129], v[8:9], v[14:15]
	v_mul_f32_e32 v15, v11, v11
	v_mul_f32_e32 v14, v9, v9
	v_fmac_f32_e32 v14, v8, v8
	v_fmac_f32_e32 v15, v10, v10
	v_add_f32_e32 v14, v14, v15
	v_add_f32_e32 v21, v14, v21
	v_lshlrev_b32_e32 v14, 16, v150
	v_and_b32_e32 v15, 0xffff0000, v150
	v_lshlrev_b32_e32 v24, 16, v151
	v_and_b32_e32 v25, 0xffff0000, v151
	v_pk_mul_f32 v[6:7], v[6:7], v[22:23] op_sel_hi:[1,0]
	v_pk_mul_f32 v[4:5], v[4:5], v[22:23] op_sel_hi:[1,0]
	v_pk_fma_f32 v[22:23], v[126:127], v[6:7], v[24:25]
	v_pk_fma_f32 v[14:15], v[124:125], v[4:5], v[14:15]
	v_mul_f32_e32 v5, v23, v23
	v_mul_f32_e32 v4, v15, v15
	v_fmac_f32_e32 v4, v14, v14
	v_fmac_f32_e32 v5, v22, v22
	v_add_f32_e32 v4, v4, v5
	v_add_f32_e32 v7, v4, v21
	v_mov_b32_e32 v21, v7
	s_nop 1
	v_permlane16_swap_b32_e32 v7, v21
	v_lshl_add_u64 v[4:5], s[26:27], 0, v[12:13]
	v_lshl_add_u64 v[12:13], v[226:227], 1, v[4:5]
	global_store_dwordx4 v[12:13], v[16:19], off
	v_cvt_pk_bf16_f32 v6, v8, v9
	s_waitcnt lgkmcnt(0)
	v_add_f32_e32 v4, v7, v21
	v_mov_b32_e32 v5, v4
	s_nop 1
	v_permlane32_swap_b32_e32 v4, v5
	v_cvt_pk_bf16_f32 v7, v10, v11
	v_cvt_pk_bf16_f32 v8, v14, v15
	v_cvt_pk_bf16_f32 v9, v22, v23
	global_store_dwordx4 v[12:13], v[6:9], off offset:256
	s_and_saveexec_b64 s[62:63], s[36:37]
	s_cbranch_execz .LBB0_794
	v_lshl_add_u32 v6, v20, 4, s91
	s_waitcnt lgkmcnt(0)
	v_add_f32_e32 v4, v4, v5
	ds_write_b32 v6, v4

.LBB0_853:
	v_and_b32_e32 v203, 15, v16
	v_bfe_u32 v201, v16, 4, 2
	s_and_b32 s5, s5, 3
	v_lshlrev_b32_e32 v16, 4, v201
	v_lshlrev_b32_e32 v202, 2, v203
	v_lshl_or_b32 v16, v203, 6, v16
	v_and_b32_e32 v19, 32, v202
	s_lshl_b32 s14, s8, 13
	s_lshl_b32 s15, s5, 12
	s_add_i32 m0, s10, 0x18000
	v_lshl_add_u64 v[10:11], v[10:11], 0, s[68:69]
	v_bitop3_b32 v140, v16, s15, v19 bitop3:0xde
	v_bitop3_b32 v16, v16, s14, v19 bitop3:0xde
	s_nop 0
	global_load_lds_dwordx4 v[10:11], off
	v_lshl_add_u64 v[8:9], v[8:9], 0, s[68:69]
	s_add_i32 m0, s10, 0x1a000
	s_add_i32 s14, s10, 0x8000
	s_add_i32 s15, s10, 0xa000
	global_load_lds_dwordx4 v[8:9], off
	v_lshl_add_u64 v[6:7], v[6:7], 0, s[68:69]
	s_mov_b32 m0, s14
	s_add_u32 s16, s20, 0x80080
	global_load_lds_dwordx4 v[6:7], off
	v_lshl_add_u64 v[4:5], v[4:5], 0, s[68:69]
	s_mov_b32 m0, s15
	s_addc_u32 s17, s21, 0
	global_load_lds_dwordx4 v[4:5], off
	s_add_i32 m0, s10, 0x1c000
	v_lshl_add_u64 v[4:5], s[16:17], 0, v[2:3]
	global_load_lds_dwordx4 v[4:5], off
	v_lshl_add_u64 v[4:5], s[16:17], 0, v[134:135]
	s_add_i32 m0, s10, 0x1e000
	v_readlane_b32 s16, v254, 25
	global_load_lds_dwordx4 v[4:5], off
	v_readlane_b32 s17, v254, 26
	s_add_u32 s16, s16, s24
	s_addc_u32 s17, s17, s25
	s_add_u32 s16, s2, s16
	s_addc_u32 s17, s3, s17
	s_and_b32 s18, s18, 7
	s_lshl_b32 s18, s18, 23
	s_lshl_b32 s19, s19, 20
	v_lshlrev_b32_e32 v4, 15, v15
	s_or_b32 s18, s18, s19
	v_and_b32_e32 v4, 0xffff0000, v4
	s_add_u32 s18, s2, s18
	v_lshl_add_u32 v4, v17, 12, v4
	v_and_b32_e32 v5, 1, v15
	s_addc_u32 s19, s3, 0
	v_lshl_or_b32 v4, v5, 6, v4
	s_add_u32 s24, s18, 0x22180080
	v_lshl_add_u32 v4, v18, 1, v4
	v_mov_b32_e32 v5, v3
	s_addc_u32 s25, s19, 0
	v_lshl_add_u64 v[136:137], s[24:25], 0, v[4:5]
	v_lshlrev_b32_e32 v4, 15, v12
	v_and_b32_e32 v4, 0xffff0000, v4
	v_lshl_add_u32 v4, v13, 12, v4
	v_and_b32_e32 v5, 1, v12
	v_lshl_or_b32 v4, v5, 6, v4
	s_waitcnt vmcnt(8)
	s_barrier
	s_waitcnt vmcnt(6)
	v_lshl_add_u32 v4, v14, 1, v4
	v_mov_b32_e32 v5, v3
	v_lshl_add_u64 v[138:139], s[24:25], 0, v[4:5]
	v_lshl_or_b32 v200, s8, 6, v203
	s_mov_b32 s28, -2
	s_mov_b64 s[24:25], 0
	v_add_u32_e32 v141, 0, v16
	s_barrier
	s_add_u32 s26, s18, s24
	s_addc_u32 s27, s19, s25
	s_add_u32 s26, s26, 0x22100100
	s_addc_u32 s27, s27, 0
	s_add_u32 s29, s16, s24
	s_addc_u32 s30, s17, s25
	s_add_i32 s31, 0, 0x10000
	s_cmpk_eq_i32 s24, 0xf00
	s_cselect_b32 s37, s23, s27
	s_cselect_b32 s36, s22, s26
	s_cselect_b32 s27, s21, s30
	s_cselect_b32 s26, s20, s29
	s_add_i32 s29, 0, 0x14000
	v_add_u32_e32 v154, s31, v140
	v_add_u32_e32 v170, s29, v140
	ds_read_b128 v[142:145], v154
	ds_read_b128 v[146:149], v154 offset:1024
	ds_read_b128 v[150:153], v154 offset:2048
	ds_read_b128 v[154:157], v154 offset:3072
	ds_read_b128 v[158:161], v170
	ds_read_b128 v[162:165], v170 offset:1024
	ds_read_b128 v[166:169], v170 offset:2048
	ds_read_b128 v[170:173], v170 offset:3072
	v_lshl_add_u64 v[198:199], v[138:139], 0, s[24:25]
	s_add_i32 m0, s10, 0xc000
	ds_read_b128 v[174:177], v141
	ds_read_b128 v[178:181], v141 offset:1024
	ds_read_b128 v[182:185], v141 offset:2048
	ds_read_b128 v[186:189], v141 offset:3072
	ds_read_b128 v[190:193], v141 offset:4096
	ds_read_b128 v[194:197], v141 offset:5120
	ds_read_b128 v[204:207], v141 offset:6144
	ds_read_b128 v[208:211], v141 offset:7168
	global_load_lds_dwordx4 v[198:199], off
	v_lshl_add_u64 v[198:199], v[136:137], 0, s[24:25]
	s_add_i32 m0, s10, 0xe000
	s_nop 0
	global_load_lds_dwordx4 v[198:199], off
	s_waitcnt vmcnt(8)
	s_waitcnt lgkmcnt(0)
	s_barrier
	s_setprio 1
	s_waitcnt lgkmcnt(0)
	v_mfma_f32_16x16x32_bf16 v[128:131], v[142:145], v[174:177], 0
	v_mfma_f32_16x16x32_bf16 v[124:127], v[150:153], v[174:177], 0
	v_mfma_f32_16x16x32_bf16 v[112:115], v[142:145], v[182:185], 0
	v_mfma_f32_16x16x32_bf16 v[108:111], v[150:153], v[182:185], 0
	v_mfma_f32_16x16x32_bf16 v[96:99], v[142:145], v[190:193], 0
	v_mfma_f32_16x16x32_bf16 v[92:95], v[150:153], v[190:193], 0
	v_mfma_f32_16x16x32_bf16 v[80:83], v[142:145], v[204:207], 0
	v_mfma_f32_16x16x32_bf16 v[76:79], v[150:153], v[204:207], 0
	v_mfma_f32_16x16x32_bf16 v[128:131], v[146:149], v[178:181], v[128:131]
	v_mfma_f32_16x16x32_bf16 v[124:127], v[154:157], v[178:181], v[124:127]
	v_mfma_f32_16x16x32_bf16 v[112:115], v[146:149], v[186:189], v[112:115]
	v_mfma_f32_16x16x32_bf16 v[108:111], v[154:157], v[186:189], v[108:111]
	v_mfma_f32_16x16x32_bf16 v[96:99], v[146:149], v[194:197], v[96:99]
	v_mfma_f32_16x16x32_bf16 v[92:95], v[154:157], v[194:197], v[92:95]
	v_mfma_f32_16x16x32_bf16 v[80:83], v[146:149], v[208:211], v[80:83]
	v_mfma_f32_16x16x32_bf16 v[76:79], v[154:157], v[208:211], v[76:79]
	s_setprio 0
	s_setprio 1
	v_mfma_f32_16x16x32_bf16 v[120:123], v[158:161], v[174:177], 0
	v_mfma_f32_16x16x32_bf16 v[116:119], v[166:169], v[174:177], 0
	v_mfma_f32_16x16x32_bf16 v[104:107], v[158:161], v[182:185], 0
	v_mfma_f32_16x16x32_bf16 v[100:103], v[166:169], v[182:185], 0
	v_mfma_f32_16x16x32_bf16 v[88:91], v[158:161], v[190:193], 0
	v_mfma_f32_16x16x32_bf16 v[84:87], v[166:169], v[190:193], 0
	v_mfma_f32_16x16x32_bf16 v[72:75], v[158:161], v[204:207], 0
	v_mfma_f32_16x16x32_bf16 v[68:71], v[166:169], v[204:207], 0
	v_mfma_f32_16x16x32_bf16 v[120:123], v[162:165], v[178:181], v[120:123]
	v_mfma_f32_16x16x32_bf16 v[116:119], v[170:173], v[178:181], v[116:119]
	v_mfma_f32_16x16x32_bf16 v[104:107], v[162:165], v[186:189], v[104:107]
	v_mfma_f32_16x16x32_bf16 v[100:103], v[170:173], v[186:189], v[100:103]
	v_mfma_f32_16x16x32_bf16 v[88:91], v[162:165], v[194:197], v[88:91]
	v_mfma_f32_16x16x32_bf16 v[84:87], v[170:173], v[194:197], v[84:87]
	v_mfma_f32_16x16x32_bf16 v[72:75], v[162:165], v[208:211], v[72:75]
	v_mfma_f32_16x16x32_bf16 v[68:71], v[170:173], v[208:211], v[68:71]
	s_setprio 0
	s_barrier
	s_add_i32 s30, s31, s9
	v_lshl_add_u64 v[198:199], s[26:27], 0, v[2:3]
	s_mov_b32 m0, s30
	ds_read_b128 v[174:177], v141 offset:16384
	ds_read_b128 v[178:181], v141 offset:17408
	ds_read_b128 v[182:185], v141 offset:18432
	ds_read_b128 v[186:189], v141 offset:19456
	ds_read_b128 v[190:193], v141 offset:20480
	ds_read_b128 v[194:197], v141 offset:21504
	ds_read_b128 v[204:207], v141 offset:22528
	ds_read_b128 v[208:211], v141 offset:23552
	global_load_lds_dwordx4 v[198:199], off
	s_add_i32 m0, s30, 0x2000
	s_add_u32 s30, s26, 0x80000
	v_lshl_add_u64 v[212:213], s[26:27], 0, v[134:135]
	s_addc_u32 s31, s27, 0
	s_add_i32 s29, s29, s9
	global_load_lds_dwordx4 v[212:213], off
	v_lshl_add_u64 v[214:215], s[30:31], 0, v[2:3]
	s_mov_b32 m0, s29
	v_lshl_add_u64 v[216:217], s[36:37], 0, v[132:133]
	global_load_lds_dwordx4 v[214:215], off
	v_lshl_add_u64 v[214:215], s[30:31], 0, v[134:135]
	s_add_i32 m0, s29, 0x2000
	s_nop 0
	global_load_lds_dwordx4 v[214:215], off
	v_lshl_add_u64 v[214:215], s[36:37], 0, v[0:1]
	s_mov_b32 m0, s10
	s_nop 0
	global_load_lds_dwordx4 v[214:215], off
	s_mov_b32 m0, s11
	s_nop 0
	global_load_lds_dwordx4 v[216:217], off
	s_waitcnt vmcnt(8)
	s_waitcnt lgkmcnt(0)
	s_barrier
	s_setprio 1
	s_waitcnt lgkmcnt(0)
	v_mfma_f32_16x16x32_bf16 v[64:67], v[142:145], v[174:177], 0
	v_mfma_f32_16x16x32_bf16 v[60:63], v[150:153], v[174:177], 0
	v_mfma_f32_16x16x32_bf16 v[48:51], v[142:145], v[182:185], 0
	v_mfma_f32_16x16x32_bf16 v[44:47], v[150:153], v[182:185], 0
	v_mfma_f32_16x16x32_bf16 v[32:35], v[142:145], v[190:193], 0
	v_mfma_f32_16x16x32_bf16 v[28:31], v[150:153], v[190:193], 0
	v_mfma_f32_16x16x32_bf16 v[16:19], v[142:145], v[204:207], 0
	v_mfma_f32_16x16x32_bf16 v[12:15], v[150:153], v[204:207], 0
	v_mfma_f32_16x16x32_bf16 v[64:67], v[146:149], v[178:181], v[64:67]
	v_mfma_f32_16x16x32_bf16 v[60:63], v[154:157], v[178:181], v[60:63]
	v_mfma_f32_16x16x32_bf16 v[48:51], v[146:149], v[186:189], v[48:51]
	v_mfma_f32_16x16x32_bf16 v[44:47], v[154:157], v[186:189], v[44:47]
	v_mfma_f32_16x16x32_bf16 v[32:35], v[146:149], v[194:197], v[32:35]
	v_mfma_f32_16x16x32_bf16 v[28:31], v[154:157], v[194:197], v[28:31]
	v_mfma_f32_16x16x32_bf16 v[16:19], v[146:149], v[208:211], v[16:19]
	v_mfma_f32_16x16x32_bf16 v[12:15], v[154:157], v[208:211], v[12:15]
	s_setprio 0
	s_setprio 1
	v_mfma_f32_16x16x32_bf16 v[56:59], v[158:161], v[174:177], 0
	v_mfma_f32_16x16x32_bf16 v[52:55], v[166:169], v[174:177], 0
	v_mfma_f32_16x16x32_bf16 v[40:43], v[158:161], v[182:185], 0
	v_mfma_f32_16x16x32_bf16 v[36:39], v[166:169], v[182:185], 0
	v_mfma_f32_16x16x32_bf16 v[24:27], v[158:161], v[190:193], 0
	v_mfma_f32_16x16x32_bf16 v[20:23], v[166:169], v[190:193], 0
	v_mfma_f32_16x16x32_bf16 v[8:11], v[158:161], v[204:207], 0
	v_mfma_f32_16x16x32_bf16 v[4:7], v[166:169], v[204:207], 0
	v_mfma_f32_16x16x32_bf16 v[56:59], v[162:165], v[178:181], v[56:59]
	v_mfma_f32_16x16x32_bf16 v[52:55], v[170:173], v[178:181], v[52:55]
	v_mfma_f32_16x16x32_bf16 v[40:43], v[162:165], v[186:189], v[40:43]
	v_mfma_f32_16x16x32_bf16 v[36:39], v[170:173], v[186:189], v[36:39]
	v_mfma_f32_16x16x32_bf16 v[24:27], v[162:165], v[194:197], v[24:27]
	v_mfma_f32_16x16x32_bf16 v[20:23], v[170:173], v[194:197], v[20:23]
	v_mfma_f32_16x16x32_bf16 v[8:11], v[162:165], v[208:211], v[8:11]
	v_mfma_f32_16x16x32_bf16 v[4:7], v[170:173], v[208:211], v[4:7]
	s_setprio 0
	s_barrier
	s_add_i32 s29, 0, 0x18000
	s_add_i32 s33, 0, 0x1c000
	v_add_u32_e32 v154, s29, v140
	v_add_u32_e32 v170, s33, v140
	ds_read_b128 v[142:145], v154
	ds_read_b128 v[146:149], v154 offset:1024
	ds_read_b128 v[150:153], v154 offset:2048
	ds_read_b128 v[154:157], v154 offset:3072
	ds_read_b128 v[158:161], v170
	ds_read_b128 v[162:165], v170 offset:1024
	ds_read_b128 v[166:169], v170 offset:2048
	ds_read_b128 v[170:173], v170 offset:3072
	s_add_u32 s30, s36, 0x80000
	s_addc_u32 s31, s37, 0
	s_mov_b32 m0, s12
	v_lshl_add_u64 v[218:219], s[30:31], 0, v[0:1]
	ds_read_b128 v[174:177], v141 offset:32768
	ds_read_b128 v[178:181], v141 offset:33792
	ds_read_b128 v[182:185], v141 offset:34816
	ds_read_b128 v[186:189], v141 offset:35840
	ds_read_b128 v[190:193], v141 offset:36864
	ds_read_b128 v[194:197], v141 offset:37888
	ds_read_b128 v[204:207], v141 offset:38912
	ds_read_b128 v[208:211], v141 offset:39936
	global_load_lds_dwordx4 v[218:219], off
	v_lshl_add_u64 v[218:219], s[30:31], 0, v[132:133]
	s_mov_b32 m0, s13
	s_nop 0
	global_load_lds_dwordx4 v[218:219], off
	s_waitcnt vmcnt(8)
	s_waitcnt lgkmcnt(0)
	s_barrier
	s_setprio 1
	s_waitcnt lgkmcnt(0)
	v_mfma_f32_16x16x32_bf16 v[128:131], v[142:145], v[174:177], v[128:131]
	v_mfma_f32_16x16x32_bf16 v[124:127], v[150:153], v[174:177], v[124:127]
	v_mfma_f32_16x16x32_bf16 v[112:115], v[142:145], v[182:185], v[112:115]
	v_mfma_f32_16x16x32_bf16 v[108:111], v[150:153], v[182:185], v[108:111]
	v_mfma_f32_16x16x32_bf16 v[96:99], v[142:145], v[190:193], v[96:99]
	v_mfma_f32_16x16x32_bf16 v[92:95], v[150:153], v[190:193], v[92:95]
	v_mfma_f32_16x16x32_bf16 v[80:83], v[142:145], v[204:207], v[80:83]
	v_mfma_f32_16x16x32_bf16 v[76:79], v[150:153], v[204:207], v[76:79]
	v_mfma_f32_16x16x32_bf16 v[128:131], v[146:149], v[178:181], v[128:131]
	v_mfma_f32_16x16x32_bf16 v[124:127], v[154:157], v[178:181], v[124:127]
	v_mfma_f32_16x16x32_bf16 v[112:115], v[146:149], v[186:189], v[112:115]
	v_mfma_f32_16x16x32_bf16 v[108:111], v[154:157], v[186:189], v[108:111]
	v_mfma_f32_16x16x32_bf16 v[96:99], v[146:149], v[194:197], v[96:99]
	v_mfma_f32_16x16x32_bf16 v[92:95], v[154:157], v[194:197], v[92:95]
	v_mfma_f32_16x16x32_bf16 v[80:83], v[146:149], v[208:211], v[80:83]
	v_mfma_f32_16x16x32_bf16 v[76:79], v[154:157], v[208:211], v[76:79]
	s_setprio 0
	s_setprio 1
	v_mfma_f32_16x16x32_bf16 v[120:123], v[158:161], v[174:177], v[120:123]
	v_mfma_f32_16x16x32_bf16 v[116:119], v[166:169], v[174:177], v[116:119]
	v_mfma_f32_16x16x32_bf16 v[104:107], v[158:161], v[182:185], v[104:107]
	v_mfma_f32_16x16x32_bf16 v[100:103], v[166:169], v[182:185], v[100:103]
	v_mfma_f32_16x16x32_bf16 v[88:91], v[158:161], v[190:193], v[88:91]
	v_mfma_f32_16x16x32_bf16 v[84:87], v[166:169], v[190:193], v[84:87]
	v_mfma_f32_16x16x32_bf16 v[72:75], v[158:161], v[204:207], v[72:75]
	v_mfma_f32_16x16x32_bf16 v[68:71], v[166:169], v[204:207], v[68:71]
	v_mfma_f32_16x16x32_bf16 v[120:123], v[162:165], v[178:181], v[120:123]
	v_mfma_f32_16x16x32_bf16 v[116:119], v[170:173], v[178:181], v[116:119]
	v_mfma_f32_16x16x32_bf16 v[104:107], v[162:165], v[186:189], v[104:107]
	v_mfma_f32_16x16x32_bf16 v[100:103], v[170:173], v[186:189], v[100:103]
	v_mfma_f32_16x16x32_bf16 v[88:91], v[162:165], v[194:197], v[88:91]
	v_mfma_f32_16x16x32_bf16 v[84:87], v[170:173], v[194:197], v[84:87]
	v_mfma_f32_16x16x32_bf16 v[72:75], v[162:165], v[208:211], v[72:75]
	v_mfma_f32_16x16x32_bf16 v[68:71], v[170:173], v[208:211], v[68:71]
	s_setprio 0
	s_barrier
	s_add_i32 s29, s29, s9
	v_lshl_add_u64 v[198:199], v[198:199], 0, s[68:69]
	s_mov_b32 m0, s29
	ds_read_b128 v[174:177], v141 offset:49152
	ds_read_b128 v[178:181], v141 offset:50176
	ds_read_b128 v[182:185], v141 offset:51200
	ds_read_b128 v[186:189], v141 offset:52224
	ds_read_b128 v[190:193], v141 offset:53248
	ds_read_b128 v[194:197], v141 offset:54272
	ds_read_b128 v[204:207], v141 offset:55296
	ds_read_b128 v[208:211], v141 offset:56320
	global_load_lds_dwordx4 v[198:199], off
	s_add_i32 m0, s29, 0x2000
	s_add_u32 s26, s26, 0x80080
	v_lshl_add_u64 v[198:199], v[212:213], 0, s[68:69]
	s_addc_u32 s27, s27, 0
	s_add_i32 s29, s33, s9
	global_load_lds_dwordx4 v[198:199], off
	v_lshl_add_u64 v[198:199], s[26:27], 0, v[2:3]
	s_mov_b32 m0, s29
	s_nop 0
	global_load_lds_dwordx4 v[198:199], off
	v_lshl_add_u64 v[198:199], s[26:27], 0, v[134:135]
	s_add_i32 m0, s29, 0x2000
	s_nop 0
	global_load_lds_dwordx4 v[198:199], off
	v_lshl_add_u64 v[198:199], v[214:215], 0, s[68:69]
	s_mov_b32 m0, s14
	s_nop 0
	global_load_lds_dwordx4 v[198:199], off
	v_lshl_add_u64 v[198:199], v[216:217], 0, s[68:69]
	s_mov_b32 m0, s15
	s_nop 0
	global_load_lds_dwordx4 v[198:199], off
	s_waitcnt vmcnt(8)
	s_waitcnt lgkmcnt(0)
	s_barrier
	s_setprio 1
	s_waitcnt lgkmcnt(0)
	v_mfma_f32_16x16x32_bf16 v[64:67], v[142:145], v[174:177], v[64:67]
	v_mfma_f32_16x16x32_bf16 v[60:63], v[150:153], v[174:177], v[60:63]
	v_mfma_f32_16x16x32_bf16 v[48:51], v[142:145], v[182:185], v[48:51]
	v_mfma_f32_16x16x32_bf16 v[44:47], v[150:153], v[182:185], v[44:47]
	v_mfma_f32_16x16x32_bf16 v[32:35], v[142:145], v[190:193], v[32:35]
	v_mfma_f32_16x16x32_bf16 v[28:31], v[150:153], v[190:193], v[28:31]
	v_mfma_f32_16x16x32_bf16 v[16:19], v[142:145], v[204:207], v[16:19]
	v_mfma_f32_16x16x32_bf16 v[12:15], v[150:153], v[204:207], v[12:15]
	v_mfma_f32_16x16x32_bf16 v[64:67], v[146:149], v[178:181], v[64:67]
	v_mfma_f32_16x16x32_bf16 v[60:63], v[154:157], v[178:181], v[60:63]
	v_mfma_f32_16x16x32_bf16 v[48:51], v[146:149], v[186:189], v[48:51]
	v_mfma_f32_16x16x32_bf16 v[44:47], v[154:157], v[186:189], v[44:47]
	v_mfma_f32_16x16x32_bf16 v[32:35], v[146:149], v[194:197], v[32:35]
	v_mfma_f32_16x16x32_bf16 v[28:31], v[154:157], v[194:197], v[28:31]
	v_mfma_f32_16x16x32_bf16 v[16:19], v[146:149], v[208:211], v[16:19]
	v_mfma_f32_16x16x32_bf16 v[12:15], v[154:157], v[208:211], v[12:15]
	s_setprio 0
	s_setprio 1
	v_mfma_f32_16x16x32_bf16 v[56:59], v[158:161], v[174:177], v[56:59]
	v_mfma_f32_16x16x32_bf16 v[52:55], v[166:169], v[174:177], v[52:55]
	v_mfma_f32_16x16x32_bf16 v[40:43], v[158:161], v[182:185], v[40:43]
	v_mfma_f32_16x16x32_bf16 v[36:39], v[166:169], v[182:185], v[36:39]
	v_mfma_f32_16x16x32_bf16 v[24:27], v[158:161], v[190:193], v[24:27]
	v_mfma_f32_16x16x32_bf16 v[20:23], v[166:169], v[190:193], v[20:23]
	v_mfma_f32_16x16x32_bf16 v[8:11], v[158:161], v[204:207], v[8:11]
	v_mfma_f32_16x16x32_bf16 v[4:7], v[166:169], v[204:207], v[4:7]
	v_mfma_f32_16x16x32_bf16 v[56:59], v[162:165], v[178:181], v[56:59]
	v_mfma_f32_16x16x32_bf16 v[52:55], v[170:173], v[178:181], v[52:55]
	v_mfma_f32_16x16x32_bf16 v[40:43], v[162:165], v[186:189], v[40:43]
	v_mfma_f32_16x16x32_bf16 v[36:39], v[170:173], v[186:189], v[36:39]
	v_mfma_f32_16x16x32_bf16 v[24:27], v[162:165], v[194:197], v[24:27]
	v_mfma_f32_16x16x32_bf16 v[20:23], v[170:173], v[194:197], v[20:23]
	v_mfma_f32_16x16x32_bf16 v[8:11], v[162:165], v[208:211], v[8:11]
	v_mfma_f32_16x16x32_bf16 v[4:7], v[170:173], v[208:211], v[4:7]
	s_setprio 0
	s_barrier
	s_add_i32 s28, s28, 2
	s_add_u32 s24, s24, 0x100
	s_addc_u32 s25, s25, 0
	s_cmp_lt_u32 s28, 30

.LBB0_857:
	s_lshl_b32 s7, s7, 8
	v_add_u32_e32 v0, s7, v200
	v_lshlrev_b32_e32 v2, 3, v201
	v_or_b32_e32 v136, 16, v0
	v_or_b32_e32 v138, 32, v0
	v_or_b32_e32 v140, 48, v0
	v_lshl_add_u64 v[132:133], s[2:3], 0, v[2:3]
	s_mov_b64 s[10:11], 0x800000
	v_ashrrev_i32_e32 v1, 31, v0
	v_ashrrev_i32_e32 v137, 31, v136
	v_ashrrev_i32_e32 v139, 31, v138
	v_ashrrev_i32_e32 v141, 31, v140
	v_lshl_add_u64 v[132:133], v[132:133], 0, s[10:11]
	v_lshlrev_b64 v[134:135], 5, v[0:1]
	v_lshlrev_b64 v[136:137], 5, v[136:137]
	v_lshlrev_b64 v[138:139], 5, v[138:139]
	v_lshlrev_b64 v[140:141], 5, v[140:141]
	v_lshl_add_u64 v[134:135], v[132:133], 0, v[134:135]
	v_lshl_add_u64 v[136:137], v[132:133], 0, v[136:137]
	v_lshl_add_u64 v[138:139], v[132:133], 0, v[138:139]
	v_lshl_add_u64 v[132:133], v[132:133], 0, v[140:141]
	s_barrier
	global_load_dwordx2 v[140:141], v[134:135], off
	s_nop 0
	global_load_dwordx2 v[136:137], v[136:137], off
	s_nop 0
	global_load_dwordx2 v[138:139], v[138:139], off
	s_nop 0
	global_load_dwordx2 v[132:133], v[132:133], off
	s_movk_i32 s9, 0x1000
	v_add_co_u32_e32 v134, vcc, s9, v134
	s_mov_b32 s9, 0xff61b1e6
	s_nop 0
	v_addc_co_u32_e32 v135, vcc, 0, v135, vcc
	global_load_dwordx2 v[142:143], v[134:135], off
	global_load_dwordx2 v[144:145], v[134:135], off offset:512
	global_load_dwordx2 v[146:147], v[134:135], off offset:1024
	s_nop 0
	global_load_dwordx2 v[134:135], v[134:135], off offset:1536
	v_cmp_lt_i32_e32 vcc, v236, v237
	s_waitcnt vmcnt(0)
	v_add_f32_e32 v140, v140, v141
	v_cndmask_b32_e32 v2, v234, v236, vcc
	v_lshlrev_b32_e32 v204, 2, v2
	v_mov_b32_e32 v141, v140
	s_nop 1
	v_permlane16_swap_b32_e32 v140, v141
	v_cmp_lt_i32_e32 vcc, v252, v237
	v_add_f32_e32 v136, v136, v137
	v_add_f32_e32 v132, v132, v133
	v_cndmask_b32_e32 v148, v234, v252, vcc
	v_lshlrev_b32_e32 v2, 2, v148
	v_add_f32_e32 v133, v142, v143
	s_waitcnt lgkmcnt(0)
	v_add_f32_e32 v149, v140, v141
	v_add_f32_e32 v137, v138, v139
	v_add_f32_e32 v139, v144, v145
	v_add_f32_e32 v144, v134, v135
	v_mov_b32_e32 v134, v136
	s_nop 1
	v_permlane16_swap_b32_e32 v136, v134
	v_mov_b32_e32 v145, v133
	s_nop 1
	v_permlane16_swap_b32_e32 v133, v145
	v_mov_b32_e32 v150, v149
	s_nop 1
	v_permlane32_swap_b32_e32 v149, v150
	v_mov_b32_e32 v142, v132
	s_nop 1
	v_permlane16_swap_b32_e32 v132, v142
	v_add_f32_e32 v143, v146, v147
	s_waitcnt lgkmcnt(3)
	v_add_f32_e32 v140, v136, v134
	s_waitcnt lgkmcnt(2)
	v_add_f32_e32 v134, v133, v145
	s_waitcnt lgkmcnt(1)
	v_add_f32_e32 v133, v149, v150
	v_fmamk_f32 v133, v133, 0x3a000000, v232
	s_waitcnt lgkmcnt(0)
	v_add_f32_e32 v136, v132, v142
	v_rsq_f32_e32 v142, v133
	v_mov_b32_e32 v135, v137
	s_nop 1
	v_permlane16_swap_b32_e32 v137, v135
	v_mov_b32_e32 v146, v139
	s_nop 1
	v_permlane16_swap_b32_e32 v139, v146
	ds_bpermute_b32 v147, v204, v143
	v_mul_f32_e32 v142, 0x3d8293ee, v142
	v_pk_mul_f32 v[196:197], v[130:131], v[142:143] op_sel_hi:[1,0]
	v_pk_mul_f32 v[130:131], v[126:127], v[142:143] op_sel_hi:[1,0]
	v_pk_mul_f32 v[198:199], v[128:129], v[142:143] op_sel_hi:[1,0]
	v_pk_mul_f32 v[194:195], v[124:125], v[142:143] op_sel_hi:[1,0]
	v_pk_mul_f32 v[128:129], v[122:123], v[142:143] op_sel_hi:[1,0]
	v_pk_mul_f32 v[126:127], v[118:119], v[142:143] op_sel_hi:[1,0]
	v_pk_mul_f32 v[118:119], v[116:117], v[142:143] op_sel_hi:[1,0]
	v_max_f32_e32 v116, v196, v197
	v_max_f32_e32 v117, v130, v131
	v_pk_mul_f32 v[190:191], v[120:121], v[142:143] op_sel_hi:[1,0]
	v_max_f32_e32 v120, v128, v129
	v_max_f32_e32 v121, v126, v127
	v_max3_f32 v116, v198, v199, v116
	v_max3_f32 v117, v194, v195, v117
	v_max3_f32 v120, v190, v191, v120
	v_max3_f32 v116, v116, s9, v117
	v_max3_f32 v117, v118, v119, v121
	v_max3_f32 v122, v116, v120, v117
	ds_bpermute_b32 v123, v204, v122
	v_mov_b32_e32 v148, v144
	s_nop 1
	v_permlane16_swap_b32_e32 v144, v148
	s_waitcnt lgkmcnt(4)
	v_add_f32_e32 v138, v137, v135
	s_waitcnt lgkmcnt(3)
	v_add_f32_e32 v132, v139, v146
	s_waitcnt lgkmcnt(2)
	v_add_f32_e32 v120, v143, v147
	s_waitcnt lgkmcnt(1)
	v_max_f32_e32 v123, v123, v123
	s_waitcnt lgkmcnt(0)
	v_add_f32_e32 v116, v144, v148
	v_max_f32_e32 v122, v122, v123
	v_mov_b32_e32 v141, v140
	s_nop 1
	v_permlane32_swap_b32_e32 v140, v141
	ds_bpermute_b32 v139, v2, v138
	ds_bpermute_b32 v137, v2, v136
	ds_bpermute_b32 v135, v2, v134
	ds_bpermute_b32 v133, v2, v132
	ds_bpermute_b32 v121, v2, v120
	ds_bpermute_b32 v117, v2, v116
	ds_bpermute_b32 v123, v2, v122
	s_lshl_b32 s9, s5, 2
	v_cmp_eq_u32_e32 vcc, 0, v201
	s_add_i32 s9, s9, 0
	s_and_saveexec_b64 s[20:21], vcc
	v_readlane_b32 s16, v254, 54
	v_readlane_b32 s18, v254, 56
	v_readlane_b32 s17, v254, 55
	v_readlane_b32 s19, v254, 57
	s_cbranch_execz .LBB0_859
	s_lshl_b32 s10, s8, 10
	s_add_i32 s10, s9, s10
	s_waitcnt lgkmcnt(0)
	v_max_f32_e32 v123, v123, v123
	v_max_f32_e32 v122, v122, v122
	v_lshl_add_u32 v124, v203, 4, s10
	v_max_f32_e32 v122, v122, v123
	ds_write_b32 v124, v122

.LBB0_873:
	s_or_b64 exec, exec, s[20:21]
	s_and_b32 s6, s6, 0xffffff00
	v_or_b32_e32 v18, s6, v202
	s_waitcnt lgkmcnt(0)
	s_barrier
	v_lshl_add_u32 v4, v18, 2, 0
	ds_read_b128 v[6:9], v4
	s_waitcnt lgkmcnt(0)
	v_max_f32_e32 v5, v9, v9
	v_max_f32_e32 v8, v8, v8
	v_max_f32_e32 v5, v8, v5
	v_max3_f32 v5, v6, v7, v5
	v_sub_f32_e32 v6, v198, v5
	v_exp_f32_e32 v104, v6
	v_sub_f32_e32 v6, v199, v5
	v_sub_f32_e32 v8, v194, v5
	v_exp_f32_e32 v105, v6
	v_sub_f32_e32 v6, v196, v5
	v_exp_f32_e32 v120, v8
	v_sub_f32_e32 v8, v195, v5
	v_sub_f32_e32 v9, v190, v5
	v_exp_f32_e32 v122, v6
	v_sub_f32_e32 v6, v197, v5
	v_exp_f32_e32 v121, v8
	v_sub_f32_e32 v8, v130, v5
	v_exp_f32_e32 v92, v9
	v_sub_f32_e32 v9, v191, v5
	v_exp_f32_e32 v123, v6
	v_exp_f32_e32 v130, v8
	v_sub_f32_e32 v8, v131, v5
	v_exp_f32_e32 v93, v9
	v_sub_f32_e32 v9, v128, v5
	v_exp_f32_e32 v131, v8
	v_exp_f32_e32 v116, v9
	v_sub_f32_e32 v9, v129, v5
	v_exp_f32_e32 v117, v9
	v_sub_f32_e32 v9, v118, v5
	v_exp_f32_e32 v118, v9
	v_sub_f32_e32 v9, v119, v5
	v_add_f32_e32 v6, v104, v105
	v_add_f32_e32 v7, v122, v123
	v_exp_f32_e32 v119, v9
	v_sub_f32_e32 v9, v126, v5
	v_sub_f32_e32 v5, v127, v5
	v_add_f32_e32 v6, v6, v7
	v_add_f32_e32 v7, v120, v121
	v_add_f32_e32 v8, v130, v131
	v_exp_f32_e32 v128, v9
	v_exp_f32_e32 v129, v5
	v_add_f32_e32 v6, 0, v6
	v_add_f32_e32 v7, v7, v8
	v_add_f32_e32 v6, v7, v6
	v_add_f32_e32 v7, v92, v93
	v_add_f32_e32 v8, v116, v117
	v_add_f32_e32 v5, v7, v8
	v_add_f32_e32 v5, v5, v6
	v_add_f32_e32 v6, v118, v119
	v_add_f32_e32 v7, v128, v129
	v_add_f32_e32 v6, v6, v7
	v_add_f32_e32 v5, v6, v5
	v_mov_b32_e32 v6, v5
	s_nop 1
	v_permlane16_swap_b32_e32 v5, v6
	v_lshl_add_u32 v190, v18, 2, s9
	s_waitcnt lgkmcnt(0)
	v_add_f32_e32 v5, v5, v6
	v_mov_b32_e32 v6, v5
	s_nop 1
	v_permlane32_swap_b32_e32 v5, v6
	s_and_saveexec_b64 s[20:21], vcc
	s_cbranch_execz .LBB0_875
	s_waitcnt lgkmcnt(0)
	v_add_f32_e32 v5, v5, v6
	ds_write_b32 v190, v5 offset:4096
.LBB0_875:
	s_or_b64 exec, exec, s[20:21]
	s_waitcnt lgkmcnt(0)
	ds_read_b128 v[6:9], v4 offset:256
	s_waitcnt lgkmcnt(0)
	v_max_f32_e32 v5, v9, v9
	v_max_f32_e32 v8, v8, v8
	v_max_f32_e32 v5, v8, v5
	v_max3_f32 v5, v6, v7, v5
	v_sub_f32_e32 v8, v192, v5
	v_sub_f32_e32 v6, v112, v5
	v_exp_f32_e32 v112, v8
	v_sub_f32_e32 v8, v108, v5
	v_exp_f32_e32 v108, v8
	v_sub_f32_e32 v8, v109, v5
	v_sub_f32_e32 v9, v188, v5
	v_sub_f32_e32 v7, v113, v5
	v_exp_f32_e32 v98, v6
	v_sub_f32_e32 v6, v193, v5
	v_exp_f32_e32 v109, v8
	v_sub_f32_e32 v8, v186, v5
	v_exp_f32_e32 v82, v9
	v_sub_f32_e32 v9, v189, v5
	v_exp_f32_e32 v99, v7
	v_exp_f32_e32 v113, v6
	v_exp_f32_e32 v126, v8
	v_sub_f32_e32 v8, v187, v5
	v_exp_f32_e32 v83, v9
	v_sub_f32_e32 v9, v184, v5
	v_exp_f32_e32 v127, v8
	v_exp_f32_e32 v102, v9
	v_sub_f32_e32 v9, v185, v5
	v_exp_f32_e32 v103, v9
	v_sub_f32_e32 v9, v106, v5
	v_exp_f32_e32 v106, v9
	v_sub_f32_e32 v9, v107, v5
	v_add_f32_e32 v6, v98, v99
	v_add_f32_e32 v7, v112, v113
	v_exp_f32_e32 v107, v9
	v_sub_f32_e32 v9, v124, v5
	v_sub_f32_e32 v5, v125, v5
	v_add_f32_e32 v6, v6, v7
	v_add_f32_e32 v7, v108, v109
	v_add_f32_e32 v8, v126, v127
	v_exp_f32_e32 v124, v9
	v_exp_f32_e32 v125, v5
	v_add_f32_e32 v6, 0, v6
	v_add_f32_e32 v7, v7, v8
	v_add_f32_e32 v6, v7, v6
	v_add_f32_e32 v7, v82, v83
	v_add_f32_e32 v8, v102, v103
	v_add_f32_e32 v5, v7, v8
	v_add_f32_e32 v5, v5, v6
	v_add_f32_e32 v6, v106, v107
	v_add_f32_e32 v7, v124, v125
	v_add_f32_e32 v6, v6, v7
	v_add_f32_e32 v5, v6, v5
	v_mov_b32_e32 v6, v5
	s_nop 1
	v_permlane16_swap_b32_e32 v5, v6
	s_waitcnt lgkmcnt(0)
	v_add_f32_e32 v5, v5, v6
	v_mov_b32_e32 v6, v5
	s_nop 1
	v_permlane32_swap_b32_e32 v5, v6
	s_and_saveexec_b64 s[20:21], vcc
	s_cbranch_execz .LBB0_877
	s_waitcnt lgkmcnt(0)
	v_add_f32_e32 v5, v5, v6
	ds_write_b32 v190, v5 offset:4352
.LBB0_877:
	s_or_b64 exec, exec, s[20:21]
	s_waitcnt lgkmcnt(0)
	ds_read_b128 v[6:9], v4 offset:512
	s_waitcnt lgkmcnt(0)
	v_max_f32_e32 v5, v9, v9
	v_max_f32_e32 v8, v8, v8
	v_max_f32_e32 v5, v8, v5
	v_max3_f32 v5, v6, v7, v5
	v_sub_f32_e32 v8, v182, v5
	v_sub_f32_e32 v6, v96, v5
	v_exp_f32_e32 v96, v8
	v_sub_f32_e32 v8, v180, v5
	v_exp_f32_e32 v90, v8
	v_sub_f32_e32 v8, v181, v5
	v_sub_f32_e32 v9, v178, v5
	v_sub_f32_e32 v7, v97, v5
	v_exp_f32_e32 v80, v6
	v_sub_f32_e32 v6, v183, v5
	v_exp_f32_e32 v91, v8
	v_sub_f32_e32 v8, v114, v5
	v_exp_f32_e32 v66, v9
	v_sub_f32_e32 v9, v179, v5
	v_exp_f32_e32 v81, v7
	v_exp_f32_e32 v97, v6
	v_exp_f32_e32 v114, v8
	v_sub_f32_e32 v8, v115, v5
	v_exp_f32_e32 v67, v9
	v_sub_f32_e32 v9, v176, v5
	v_exp_f32_e32 v115, v8
	v_exp_f32_e32 v86, v9
	v_sub_f32_e32 v9, v177, v5
	v_exp_f32_e32 v87, v9
	v_sub_f32_e32 v9, v88, v5
	v_exp_f32_e32 v88, v9
	v_sub_f32_e32 v9, v89, v5
	v_add_f32_e32 v6, v80, v81
	v_add_f32_e32 v7, v96, v97
	v_exp_f32_e32 v89, v9
	v_sub_f32_e32 v9, v110, v5
	v_sub_f32_e32 v5, v111, v5
	v_add_f32_e32 v6, v6, v7
	v_add_f32_e32 v7, v90, v91
	v_add_f32_e32 v8, v114, v115
	v_exp_f32_e32 v110, v9
	v_exp_f32_e32 v111, v5
	v_add_f32_e32 v6, 0, v6
	v_add_f32_e32 v7, v7, v8
	v_add_f32_e32 v6, v7, v6
	v_add_f32_e32 v7, v66, v67
	v_add_f32_e32 v8, v86, v87
	v_add_f32_e32 v5, v7, v8
	v_add_f32_e32 v5, v5, v6
	v_add_f32_e32 v6, v88, v89
	v_add_f32_e32 v7, v110, v111
	v_add_f32_e32 v6, v6, v7
	v_add_f32_e32 v5, v6, v5
	v_mov_b32_e32 v6, v5
	s_nop 1
	v_permlane16_swap_b32_e32 v5, v6
	s_waitcnt lgkmcnt(0)
	v_add_f32_e32 v5, v5, v6
	v_mov_b32_e32 v6, v5
	s_nop 1
	v_permlane32_swap_b32_e32 v5, v6
	s_and_saveexec_b64 s[20:21], vcc
	s_cbranch_execz .LBB0_879
	s_waitcnt lgkmcnt(0)
	v_add_f32_e32 v5, v5, v6
	ds_write_b32 v190, v5 offset:4608
.LBB0_879:
	s_or_b64 exec, exec, s[20:21]
	s_waitcnt lgkmcnt(0)
	ds_read_b128 v[6:9], v4 offset:768
	s_waitcnt lgkmcnt(0)
	v_max_f32_e32 v5, v9, v9
	v_max_f32_e32 v8, v8, v8
	v_max_f32_e32 v5, v8, v5
	v_max3_f32 v5, v6, v7, v5
	v_sub_f32_e32 v8, v172, v5
	v_exp_f32_e32 v78, v8
	v_sub_f32_e32 v8, v170, v5
	v_sub_f32_e32 v6, v174, v5
	v_exp_f32_e32 v74, v8
	v_sub_f32_e32 v8, v171, v5
	v_sub_f32_e32 v9, v168, v5
	v_sub_f32_e32 v7, v175, v5
	v_exp_f32_e32 v64, v6
	v_sub_f32_e32 v6, v173, v5
	v_exp_f32_e32 v75, v8
	v_sub_f32_e32 v8, v100, v5
	v_exp_f32_e32 v50, v9
	v_sub_f32_e32 v9, v169, v5
	v_exp_f32_e32 v65, v7
	v_exp_f32_e32 v79, v6
	v_exp_f32_e32 v100, v8
	v_sub_f32_e32 v8, v101, v5
	v_exp_f32_e32 v51, v9
	v_sub_f32_e32 v9, v166, v5
	v_exp_f32_e32 v101, v8
	v_exp_f32_e32 v70, v9
	v_sub_f32_e32 v9, v167, v5
	v_exp_f32_e32 v71, v9
	v_sub_f32_e32 v9, v72, v5
	v_exp_f32_e32 v72, v9
	v_sub_f32_e32 v9, v73, v5
	v_add_f32_e32 v6, v64, v65
	v_add_f32_e32 v7, v78, v79
	v_exp_f32_e32 v73, v9
	v_sub_f32_e32 v9, v94, v5
	v_sub_f32_e32 v5, v95, v5
	v_add_f32_e32 v6, v6, v7
	v_add_f32_e32 v7, v74, v75
	v_add_f32_e32 v8, v100, v101
	v_exp_f32_e32 v94, v9
	v_exp_f32_e32 v95, v5
	v_add_f32_e32 v6, 0, v6
	v_add_f32_e32 v7, v7, v8
	v_add_f32_e32 v6, v7, v6
	v_add_f32_e32 v7, v50, v51
	v_add_f32_e32 v8, v70, v71
	v_add_f32_e32 v5, v7, v8
	v_add_f32_e32 v5, v5, v6
	v_add_f32_e32 v6, v72, v73
	v_add_f32_e32 v7, v94, v95
	v_add_f32_e32 v6, v6, v7
	v_add_f32_e32 v5, v6, v5
	v_mov_b32_e32 v6, v5
	s_nop 1
	v_permlane16_swap_b32_e32 v5, v6
	s_waitcnt lgkmcnt(0)
	v_add_f32_e32 v5, v5, v6
	v_mov_b32_e32 v6, v5
	s_nop 1
	v_permlane32_swap_b32_e32 v5, v6
	s_and_saveexec_b64 s[20:21], vcc
	s_cbranch_execz .LBB0_881
	s_waitcnt lgkmcnt(0)
	v_add_f32_e32 v5, v5, v6
	ds_write_b32 v190, v5 offset:4864
.LBB0_881:
	s_or_b64 exec, exec, s[20:21]
	s_waitcnt lgkmcnt(0)
	ds_read_b128 v[6:9], v4 offset:2048
	s_waitcnt lgkmcnt(0)
	v_max_f32_e32 v5, v9, v9
	v_max_f32_e32 v8, v8, v8
	v_max_f32_e32 v5, v8, v5
	v_max3_f32 v5, v6, v7, v5
	v_sub_f32_e32 v8, v162, v5
	v_exp_f32_e32 v62, v8
	v_sub_f32_e32 v8, v160, v5
	v_sub_f32_e32 v6, v164, v5
	v_exp_f32_e32 v58, v8
	v_sub_f32_e32 v8, v161, v5
	v_sub_f32_e32 v9, v158, v5
	v_sub_f32_e32 v7, v165, v5
	v_exp_f32_e32 v48, v6
	v_sub_f32_e32 v6, v163, v5
	v_exp_f32_e32 v59, v8
	v_sub_f32_e32 v8, v84, v5
	v_exp_f32_e32 v34, v9
	v_sub_f32_e32 v9, v159, v5
	v_exp_f32_e32 v49, v7
	v_exp_f32_e32 v63, v6
	v_exp_f32_e32 v84, v8
	v_sub_f32_e32 v8, v85, v5
	v_exp_f32_e32 v35, v9
	v_sub_f32_e32 v9, v156, v5
	v_exp_f32_e32 v85, v8
	v_exp_f32_e32 v54, v9
	v_sub_f32_e32 v9, v157, v5
	v_exp_f32_e32 v55, v9
	v_sub_f32_e32 v9, v56, v5
	v_exp_f32_e32 v56, v9
	v_sub_f32_e32 v9, v57, v5
	v_add_f32_e32 v6, v48, v49
	v_add_f32_e32 v7, v62, v63
	v_exp_f32_e32 v57, v9
	v_sub_f32_e32 v9, v76, v5
	v_sub_f32_e32 v5, v77, v5
	v_add_f32_e32 v6, v6, v7
	v_add_f32_e32 v7, v58, v59
	v_add_f32_e32 v8, v84, v85
	v_exp_f32_e32 v76, v9
	v_exp_f32_e32 v77, v5
	v_add_f32_e32 v6, 0, v6
	v_add_f32_e32 v7, v7, v8
	v_add_f32_e32 v6, v7, v6
	v_add_f32_e32 v7, v34, v35
	v_add_f32_e32 v8, v54, v55
	v_add_f32_e32 v5, v7, v8
	v_add_f32_e32 v5, v5, v6
	v_add_f32_e32 v6, v56, v57
	v_add_f32_e32 v7, v76, v77
	v_add_f32_e32 v6, v6, v7
	v_add_f32_e32 v5, v6, v5
	v_mov_b32_e32 v6, v5
	s_nop 1
	v_permlane16_swap_b32_e32 v5, v6
	s_waitcnt lgkmcnt(0)
	v_add_f32_e32 v5, v5, v6
	v_mov_b32_e32 v6, v5
	s_nop 1
	v_permlane32_swap_b32_e32 v5, v6
	s_and_saveexec_b64 s[20:21], vcc
	s_cbranch_execz .LBB0_883
	s_waitcnt lgkmcnt(0)
	v_add_f32_e32 v5, v5, v6
	ds_write_b32 v190, v5 offset:6144
.LBB0_883:
	s_or_b64 exec, exec, s[20:21]
	s_waitcnt lgkmcnt(0)
	ds_read_b128 v[6:9], v4 offset:2304
	s_waitcnt lgkmcnt(0)
	v_max_f32_e32 v5, v9, v9
	v_max_f32_e32 v8, v8, v8
	v_max_f32_e32 v5, v8, v5
	v_max3_f32 v5, v6, v7, v5
	v_sub_f32_e32 v8, v152, v5
	v_exp_f32_e32 v46, v8
	v_sub_f32_e32 v8, v150, v5
	v_sub_f32_e32 v6, v154, v5
	v_exp_f32_e32 v42, v8
	v_sub_f32_e32 v8, v151, v5
	v_sub_f32_e32 v9, v148, v5
	v_sub_f32_e32 v7, v155, v5
	v_exp_f32_e32 v32, v6
	v_sub_f32_e32 v6, v153, v5
	v_exp_f32_e32 v43, v8
	v_sub_f32_e32 v8, v68, v5
	v_exp_f32_e32 v20, v9
	v_sub_f32_e32 v9, v149, v5
	v_exp_f32_e32 v33, v7
	v_exp_f32_e32 v47, v6
	v_exp_f32_e32 v68, v8
	v_sub_f32_e32 v8, v69, v5
	v_exp_f32_e32 v21, v9
	v_sub_f32_e32 v9, v146, v5
	v_exp_f32_e32 v69, v8
	v_exp_f32_e32 v38, v9
	v_sub_f32_e32 v9, v147, v5
	v_exp_f32_e32 v39, v9
	v_sub_f32_e32 v9, v40, v5
	v_exp_f32_e32 v40, v9
	v_sub_f32_e32 v9, v41, v5
	v_add_f32_e32 v6, v32, v33
	v_add_f32_e32 v7, v46, v47
	v_exp_f32_e32 v41, v9
	v_sub_f32_e32 v9, v60, v5
	v_sub_f32_e32 v5, v61, v5
	v_add_f32_e32 v6, v6, v7
	v_add_f32_e32 v7, v42, v43
	v_add_f32_e32 v8, v68, v69
	v_exp_f32_e32 v60, v9
	v_exp_f32_e32 v61, v5
	v_add_f32_e32 v6, 0, v6
	v_add_f32_e32 v7, v7, v8
	v_add_f32_e32 v6, v7, v6
	v_add_f32_e32 v7, v20, v21
	v_add_f32_e32 v8, v38, v39
	v_add_f32_e32 v5, v7, v8
	v_add_f32_e32 v5, v5, v6
	v_add_f32_e32 v6, v40, v41
	v_add_f32_e32 v7, v60, v61
	v_add_f32_e32 v6, v6, v7
	v_add_f32_e32 v5, v6, v5
	v_mov_b32_e32 v6, v5
	s_nop 1
	v_permlane16_swap_b32_e32 v5, v6
	s_waitcnt lgkmcnt(0)
	v_add_f32_e32 v5, v5, v6
	v_mov_b32_e32 v6, v5
	s_nop 1
	v_permlane32_swap_b32_e32 v5, v6
	s_and_saveexec_b64 s[20:21], vcc
	s_cbranch_execz .LBB0_885
	s_waitcnt lgkmcnt(0)
	v_add_f32_e32 v5, v5, v6
	ds_write_b32 v190, v5 offset:6400
.LBB0_885:
	s_or_b64 exec, exec, s[20:21]
	s_waitcnt lgkmcnt(0)
	ds_read_b128 v[6:9], v4 offset:2560
	s_waitcnt lgkmcnt(0)
	v_max_f32_e32 v5, v9, v9
	v_max_f32_e32 v8, v8, v8
	v_max_f32_e32 v5, v8, v5
	v_max3_f32 v5, v6, v7, v5
	v_sub_f32_e32 v8, v142, v5
	v_exp_f32_e32 v30, v8
	v_sub_f32_e32 v8, v140, v5
	v_sub_f32_e32 v6, v144, v5
	v_exp_f32_e32 v26, v8
	v_sub_f32_e32 v8, v141, v5
	v_sub_f32_e32 v7, v145, v5
	v_exp_f32_e32 v18, v6
	v_sub_f32_e32 v6, v143, v5
	v_exp_f32_e32 v27, v8
	v_sub_f32_e32 v8, v52, v5
	v_exp_f32_e32 v19, v7
	v_exp_f32_e32 v31, v6
	v_exp_f32_e32 v52, v8
	v_sub_f32_e32 v8, v53, v5
	v_exp_f32_e32 v53, v8
	v_sub_f32_e32 v8, v138, v5
	v_sub_f32_e32 v9, v139, v5
	v_sub_f32_e32 v22, v136, v5
	v_sub_f32_e32 v23, v137, v5
	v_exp_f32_e32 v8, v8
	v_exp_f32_e32 v9, v9
	v_exp_f32_e32 v22, v22
	v_exp_f32_e32 v23, v23
	v_add_f32_e32 v6, v18, v19
	v_add_f32_e32 v7, v30, v31
	v_sub_f32_e32 v24, v24, v5
	v_sub_f32_e32 v25, v25, v5
	v_sub_f32_e32 v44, v44, v5
	v_sub_f32_e32 v5, v45, v5
	v_add_f32_e32 v6, v6, v7
	v_add_f32_e32 v7, v26, v27
	v_add_f32_e32 v140, v52, v53
	v_exp_f32_e32 v24, v24
	v_exp_f32_e32 v25, v25
	v_exp_f32_e32 v44, v44
	v_exp_f32_e32 v45, v5
	v_add_f32_e32 v6, 0, v6
	v_add_f32_e32 v7, v7, v140
	v_add_f32_e32 v6, v7, v6
	v_add_f32_e32 v7, v8, v9
	v_add_f32_e32 v136, v22, v23
	v_add_f32_e32 v5, v7, v136
	v_add_f32_e32 v5, v5, v6
	v_add_f32_e32 v6, v24, v25
	v_add_f32_e32 v7, v44, v45
	v_add_f32_e32 v6, v6, v7
	v_add_f32_e32 v5, v6, v5
	v_mov_b32_e32 v6, v5
	s_nop 1
	v_permlane16_swap_b32_e32 v5, v6
	s_waitcnt lgkmcnt(0)
	v_add_f32_e32 v5, v5, v6
	v_mov_b32_e32 v6, v5
	s_nop 1
	v_permlane32_swap_b32_e32 v5, v6
	s_and_saveexec_b64 s[20:21], vcc
	s_cbranch_execz .LBB0_887
	s_waitcnt lgkmcnt(0)
	v_add_f32_e32 v5, v5, v6
	ds_write_b32 v190, v5 offset:6656
.LBB0_887:
	s_or_b64 exec, exec, s[20:21]
	s_waitcnt lgkmcnt(0)
	ds_read_b128 v[4:7], v4 offset:2816
	s_waitcnt lgkmcnt(0)
	v_max_f32_e32 v7, v7, v7
	v_max_f32_e32 v6, v6, v6
	v_max_f32_e32 v6, v6, v7
	v_max3_f32 v136, v4, v5, v6
	v_sub_f32_e32 v4, v16, v136
	v_sub_f32_e32 v5, v17, v136
	v_sub_f32_e32 v16, v134, v136
	v_exp_f32_e32 v6, v4
	v_sub_f32_e32 v4, v135, v136
	v_exp_f32_e32 v7, v5
	v_exp_f32_e32 v16, v16
	v_exp_f32_e32 v17, v4
	v_sub_f32_e32 v14, v14, v136
	v_add_f32_e32 v4, v6, v7
	v_sub_f32_e32 v15, v15, v136
	v_add_f32_e32 v5, v16, v17
	v_sub_f32_e32 v36, v36, v136
	v_sub_f32_e32 v37, v37, v136
	v_exp_f32_e32 v14, v14
	v_exp_f32_e32 v15, v15
	v_exp_f32_e32 v36, v36
	v_exp_f32_e32 v37, v37
	v_add_f32_e32 v4, v4, v5
	v_add_f32_e32 v134, 0, v4
	v_sub_f32_e32 v4, v132, v136
	v_sub_f32_e32 v5, v133, v136
	v_sub_f32_e32 v10, v10, v136
	v_sub_f32_e32 v11, v11, v136
	v_exp_f32_e32 v4, v4
	v_exp_f32_e32 v5, v5
	v_exp_f32_e32 v10, v10
	v_exp_f32_e32 v11, v11
	v_sub_f32_e32 v12, v12, v136
	v_sub_f32_e32 v13, v13, v136
	v_sub_f32_e32 v28, v28, v136
	v_sub_f32_e32 v29, v29, v136
	v_add_f32_e32 v135, v14, v15
	v_add_f32_e32 v137, v36, v37
	v_exp_f32_e32 v12, v12
	v_exp_f32_e32 v13, v13
	v_exp_f32_e32 v28, v28
	v_exp_f32_e32 v29, v29
	v_add_f32_e32 v132, v135, v137
	v_add_f32_e32 v132, v132, v134
	v_add_f32_e32 v133, v4, v5
	v_add_f32_e32 v134, v10, v11
	v_add_f32_e32 v133, v133, v134
	v_add_f32_e32 v132, v133, v132
	v_add_f32_e32 v133, v12, v13
	v_add_f32_e32 v134, v28, v29
	v_add_f32_e32 v133, v133, v134
	v_add_f32_e32 v132, v133, v132
	v_mov_b32_e32 v133, v132
	s_nop 1
	v_permlane16_swap_b32_e32 v132, v133
	s_waitcnt lgkmcnt(0)
	v_add_f32_e32 v132, v132, v133
	v_mov_b32_e32 v2, v132
	s_nop 1
	v_permlane32_swap_b32_e32 v132, v2
	s_and_saveexec_b64 s[20:21], vcc
	s_cbranch_execz .LBB0_889
	s_waitcnt lgkmcnt(0)
	v_add_f32_e32 v2, v132, v2
	ds_write_b32 v190, v2 offset:6912

.LBB0_946:
	s_ashr_i32 s49, s48, 31
	s_andn2_b64 vcc, exec, s[56:57]
	s_lshl_b64 s[6:7], s[48:49], 19
	s_add_u32 s52, s62, s6
	s_addc_u32 s53, s63, s7
	s_and_b64 s[6:7], s[56:57], exec
	s_cselect_b32 s5, s53, s41
	s_cselect_b32 s6, s52, s40
	s_ashr_i32 s51, s50, 31
	s_lshl_b64 s[8:9], s[50:51], 19
	s_add_u32 s54, s64, s8
	s_addc_u32 s55, s65, s9
	s_and_b64 s[8:9], s[56:57], exec
	s_cselect_b32 s7, s55, s39
	s_cselect_b32 s8, s54, s38
	s_add_u32 s9, s38, 0x100
	v_cndmask_b32_e64 v4, 0, 1, s[56:57]
	s_addc_u32 s10, s39, 0
	v_cmp_ne_u32_e64 s[36:37], 1, v4
	s_add_u32 s38, s40, 0x40080
	s_addc_u32 s39, s41, 0
	s_mov_b32 s11, -2
	s_waitcnt lgkmcnt(0)
	s_add_u32 s12, s38, 0xfffc0080
	s_addc_u32 s13, s39, -1
	s_add_i32 s14, 0, 0x10000
	s_cmp_eq_u32 s11, 12
	s_cselect_b32 s57, s5, s13
	s_cselect_b32 s56, s6, s12
	s_cselect_b32 s41, s7, s10
	s_cselect_b32 s40, s8, s9
	s_add_i32 s15, 0, 0x14000
	v_add_u32_e32 v144, s14, v230
	v_add_u32_e32 v160, s15, v230
	ds_read_b128 v[124:127], v144
	ds_read_b128 v[128:131], v144 offset:1024
	ds_read_b128 v[136:139], v144 offset:2048
	ds_read_b128 v[144:147], v144 offset:3072
	ds_read_b128 v[148:151], v160
	ds_read_b128 v[152:155], v160 offset:1024
	ds_read_b128 v[156:159], v160 offset:2048
	ds_read_b128 v[160:163], v160 offset:3072
	v_lshl_add_u64 v[196:197], s[38:39], 0, v[222:223]
	s_add_i32 m0, s71, 0xc000
	ds_read_b128 v[164:167], v243
	ds_read_b128 v[168:171], v243 offset:1024
	ds_read_b128 v[172:175], v243 offset:2048
	ds_read_b128 v[176:179], v243 offset:3072
	ds_read_b128 v[180:183], v243 offset:4096
	ds_read_b128 v[184:187], v243 offset:5120
	ds_read_b128 v[188:191], v243 offset:6144
	ds_read_b128 v[192:195], v243 offset:7168
	global_load_lds_dwordx4 v[196:197], off
	v_lshl_add_u64 v[196:197], s[38:39], 0, v[220:221]
	s_add_i32 m0, s71, 0xe000
	s_nop 0
	global_load_lds_dwordx4 v[196:197], off
	s_waitcnt vmcnt(8)
	s_waitcnt lgkmcnt(0)
	s_barrier
	s_setprio 1
	s_waitcnt lgkmcnt(0)
	v_mfma_f32_16x16x32_bf16 v[140:143], v[124:127], v[164:167], 0
	v_mfma_f32_16x16x32_bf16 v[132:135], v[136:139], v[164:167], 0
	v_mfma_f32_16x16x32_bf16 v[112:115], v[124:127], v[172:175], 0
	v_mfma_f32_16x16x32_bf16 v[108:111], v[136:139], v[172:175], 0
	v_mfma_f32_16x16x32_bf16 v[96:99], v[124:127], v[180:183], 0
	v_mfma_f32_16x16x32_bf16 v[92:95], v[136:139], v[180:183], 0
	v_mfma_f32_16x16x32_bf16 v[80:83], v[124:127], v[188:191], 0
	v_mfma_f32_16x16x32_bf16 v[76:79], v[136:139], v[188:191], 0
	v_mfma_f32_16x16x32_bf16 v[140:143], v[128:131], v[168:171], v[140:143]
	v_mfma_f32_16x16x32_bf16 v[132:135], v[144:147], v[168:171], v[132:135]
	v_mfma_f32_16x16x32_bf16 v[112:115], v[128:131], v[176:179], v[112:115]
	v_mfma_f32_16x16x32_bf16 v[108:111], v[144:147], v[176:179], v[108:111]
	v_mfma_f32_16x16x32_bf16 v[96:99], v[128:131], v[184:187], v[96:99]
	v_mfma_f32_16x16x32_bf16 v[92:95], v[144:147], v[184:187], v[92:95]
	v_mfma_f32_16x16x32_bf16 v[80:83], v[128:131], v[192:195], v[80:83]
	v_mfma_f32_16x16x32_bf16 v[76:79], v[144:147], v[192:195], v[76:79]
	s_setprio 0
	s_setprio 1
	v_mfma_f32_16x16x32_bf16 v[120:123], v[148:151], v[164:167], 0
	v_mfma_f32_16x16x32_bf16 v[116:119], v[156:159], v[164:167], 0
	v_mfma_f32_16x16x32_bf16 v[104:107], v[148:151], v[172:175], 0
	v_mfma_f32_16x16x32_bf16 v[100:103], v[156:159], v[172:175], 0
	v_mfma_f32_16x16x32_bf16 v[88:91], v[148:151], v[180:183], 0
	v_mfma_f32_16x16x32_bf16 v[84:87], v[156:159], v[180:183], 0
	v_mfma_f32_16x16x32_bf16 v[72:75], v[148:151], v[188:191], 0
	v_mfma_f32_16x16x32_bf16 v[68:71], v[156:159], v[188:191], 0
	v_mfma_f32_16x16x32_bf16 v[120:123], v[152:155], v[168:171], v[120:123]
	v_mfma_f32_16x16x32_bf16 v[116:119], v[160:163], v[168:171], v[116:119]
	v_mfma_f32_16x16x32_bf16 v[104:107], v[152:155], v[176:179], v[104:107]
	v_mfma_f32_16x16x32_bf16 v[100:103], v[160:163], v[176:179], v[100:103]
	v_mfma_f32_16x16x32_bf16 v[88:91], v[152:155], v[184:187], v[88:91]
	v_mfma_f32_16x16x32_bf16 v[84:87], v[160:163], v[184:187], v[84:87]
	v_mfma_f32_16x16x32_bf16 v[72:75], v[152:155], v[192:195], v[72:75]
	v_mfma_f32_16x16x32_bf16 v[68:71], v[160:163], v[192:195], v[68:71]
	s_setprio 0
	s_barrier
	s_add_i32 s12, s14, s70
	v_lshl_add_u64 v[196:197], s[40:41], 0, v[2:3]
	s_mov_b32 m0, s12
	ds_read_b128 v[164:167], v243 offset:16384
	ds_read_b128 v[168:171], v243 offset:17408
	ds_read_b128 v[172:175], v243 offset:18432
	ds_read_b128 v[176:179], v243 offset:19456
	ds_read_b128 v[180:183], v243 offset:20480
	ds_read_b128 v[184:187], v243 offset:21504
	ds_read_b128 v[188:191], v243 offset:22528
	ds_read_b128 v[192:195], v243 offset:23552
	global_load_lds_dwordx4 v[196:197], off
	s_add_i32 m0, s12, 0x2000
	s_add_u32 s12, s40, 0x40000
	v_lshl_add_u64 v[198:199], s[40:41], 0, v[218:219]
	s_addc_u32 s13, s41, 0
	s_add_i32 s14, s15, s70
	global_load_lds_dwordx4 v[198:199], off
	v_lshl_add_u64 v[200:201], s[12:13], 0, v[2:3]
	s_mov_b32 m0, s14
	v_lshl_add_u64 v[202:203], s[56:57], 0, v[216:217]
	global_load_lds_dwordx4 v[200:201], off
	v_lshl_add_u64 v[200:201], s[12:13], 0, v[218:219]
	s_add_i32 m0, s14, 0x2000
	s_nop 0
	global_load_lds_dwordx4 v[200:201], off
	v_lshl_add_u64 v[200:201], s[56:57], 0, v[0:1]
	s_mov_b32 m0, s71
	s_nop 0
	global_load_lds_dwordx4 v[200:201], off
	s_mov_b32 m0, s80
	s_nop 0
	global_load_lds_dwordx4 v[202:203], off
	s_waitcnt vmcnt(8)
	s_waitcnt lgkmcnt(0)
	s_barrier
	s_setprio 1
	s_waitcnt lgkmcnt(0)
	v_mfma_f32_16x16x32_bf16 v[64:67], v[124:127], v[164:167], 0
	v_mfma_f32_16x16x32_bf16 v[60:63], v[136:139], v[164:167], 0
	v_mfma_f32_16x16x32_bf16 v[48:51], v[124:127], v[172:175], 0
	v_mfma_f32_16x16x32_bf16 v[44:47], v[136:139], v[172:175], 0
	v_mfma_f32_16x16x32_bf16 v[32:35], v[124:127], v[180:183], 0
	v_mfma_f32_16x16x32_bf16 v[28:31], v[136:139], v[180:183], 0
	v_mfma_f32_16x16x32_bf16 v[16:19], v[124:127], v[188:191], 0
	v_mfma_f32_16x16x32_bf16 v[12:15], v[136:139], v[188:191], 0
	v_mfma_f32_16x16x32_bf16 v[64:67], v[128:131], v[168:171], v[64:67]
	v_mfma_f32_16x16x32_bf16 v[60:63], v[144:147], v[168:171], v[60:63]
	v_mfma_f32_16x16x32_bf16 v[48:51], v[128:131], v[176:179], v[48:51]
	v_mfma_f32_16x16x32_bf16 v[44:47], v[144:147], v[176:179], v[44:47]
	v_mfma_f32_16x16x32_bf16 v[32:35], v[128:131], v[184:187], v[32:35]
	v_mfma_f32_16x16x32_bf16 v[28:31], v[144:147], v[184:187], v[28:31]
	v_mfma_f32_16x16x32_bf16 v[16:19], v[128:131], v[192:195], v[16:19]
	v_mfma_f32_16x16x32_bf16 v[12:15], v[144:147], v[192:195], v[12:15]
	s_setprio 0
	s_setprio 1
	v_mfma_f32_16x16x32_bf16 v[56:59], v[148:151], v[164:167], 0
	v_mfma_f32_16x16x32_bf16 v[52:55], v[156:159], v[164:167], 0
	v_mfma_f32_16x16x32_bf16 v[40:43], v[148:151], v[172:175], 0
	v_mfma_f32_16x16x32_bf16 v[36:39], v[156:159], v[172:175], 0
	v_mfma_f32_16x16x32_bf16 v[24:27], v[148:151], v[180:183], 0
	v_mfma_f32_16x16x32_bf16 v[20:23], v[156:159], v[180:183], 0
	v_mfma_f32_16x16x32_bf16 v[8:11], v[148:151], v[188:191], 0
	v_mfma_f32_16x16x32_bf16 v[4:7], v[156:159], v[188:191], 0
	v_mfma_f32_16x16x32_bf16 v[56:59], v[152:155], v[168:171], v[56:59]
	v_mfma_f32_16x16x32_bf16 v[52:55], v[160:163], v[168:171], v[52:55]
	v_mfma_f32_16x16x32_bf16 v[40:43], v[152:155], v[176:179], v[40:43]
	v_mfma_f32_16x16x32_bf16 v[36:39], v[160:163], v[176:179], v[36:39]
	v_mfma_f32_16x16x32_bf16 v[24:27], v[152:155], v[184:187], v[24:27]
	v_mfma_f32_16x16x32_bf16 v[20:23], v[160:163], v[184:187], v[20:23]
	v_mfma_f32_16x16x32_bf16 v[8:11], v[152:155], v[192:195], v[8:11]
	v_mfma_f32_16x16x32_bf16 v[4:7], v[160:163], v[192:195], v[4:7]
	s_setprio 0
	s_barrier
	s_add_i32 s14, 0, 0x18000
	s_add_i32 s15, 0, 0x1c000
	v_add_u32_e32 v144, s14, v230
	v_add_u32_e32 v160, s15, v230
	ds_read_b128 v[124:127], v144
	ds_read_b128 v[128:131], v144 offset:1024
	ds_read_b128 v[136:139], v144 offset:2048
	ds_read_b128 v[144:147], v144 offset:3072
	ds_read_b128 v[148:151], v160
	ds_read_b128 v[152:155], v160 offset:1024
	ds_read_b128 v[156:159], v160 offset:2048
	ds_read_b128 v[160:163], v160 offset:3072
	s_add_u32 s12, s56, 0x40000
	s_addc_u32 s13, s57, 0
	s_mov_b32 m0, s81
	v_lshl_add_u64 v[204:205], s[12:13], 0, v[0:1]
	ds_read_b128 v[164:167], v243 offset:32768
	ds_read_b128 v[168:171], v243 offset:33792
	ds_read_b128 v[172:175], v243 offset:34816
	ds_read_b128 v[176:179], v243 offset:35840
	ds_read_b128 v[180:183], v243 offset:36864
	ds_read_b128 v[184:187], v243 offset:37888
	ds_read_b128 v[188:191], v243 offset:38912
	ds_read_b128 v[192:195], v243 offset:39936
	global_load_lds_dwordx4 v[204:205], off
	v_lshl_add_u64 v[204:205], s[12:13], 0, v[216:217]
	s_mov_b32 m0, s82
	s_nop 0
	global_load_lds_dwordx4 v[204:205], off
	s_waitcnt vmcnt(8)
	s_waitcnt lgkmcnt(0)
	s_barrier
	s_setprio 1
	s_waitcnt lgkmcnt(0)
	v_mfma_f32_16x16x32_bf16 v[140:143], v[124:127], v[164:167], v[140:143]
	v_mfma_f32_16x16x32_bf16 v[132:135], v[136:139], v[164:167], v[132:135]
	v_mfma_f32_16x16x32_bf16 v[112:115], v[124:127], v[172:175], v[112:115]
	v_mfma_f32_16x16x32_bf16 v[108:111], v[136:139], v[172:175], v[108:111]
	v_mfma_f32_16x16x32_bf16 v[96:99], v[124:127], v[180:183], v[96:99]
	v_mfma_f32_16x16x32_bf16 v[92:95], v[136:139], v[180:183], v[92:95]
	v_mfma_f32_16x16x32_bf16 v[80:83], v[124:127], v[188:191], v[80:83]
	v_mfma_f32_16x16x32_bf16 v[76:79], v[136:139], v[188:191], v[76:79]
	v_mfma_f32_16x16x32_bf16 v[140:143], v[128:131], v[168:171], v[140:143]
	v_mfma_f32_16x16x32_bf16 v[132:135], v[144:147], v[168:171], v[132:135]
	v_mfma_f32_16x16x32_bf16 v[112:115], v[128:131], v[176:179], v[112:115]
	v_mfma_f32_16x16x32_bf16 v[108:111], v[144:147], v[176:179], v[108:111]
	v_mfma_f32_16x16x32_bf16 v[96:99], v[128:131], v[184:187], v[96:99]
	v_mfma_f32_16x16x32_bf16 v[92:95], v[144:147], v[184:187], v[92:95]
	v_mfma_f32_16x16x32_bf16 v[80:83], v[128:131], v[192:195], v[80:83]
	v_mfma_f32_16x16x32_bf16 v[76:79], v[144:147], v[192:195], v[76:79]
	s_setprio 0
	s_setprio 1
	v_mfma_f32_16x16x32_bf16 v[120:123], v[148:151], v[164:167], v[120:123]
	v_mfma_f32_16x16x32_bf16 v[116:119], v[156:159], v[164:167], v[116:119]
	v_mfma_f32_16x16x32_bf16 v[104:107], v[148:151], v[172:175], v[104:107]
	v_mfma_f32_16x16x32_bf16 v[100:103], v[156:159], v[172:175], v[100:103]
	v_mfma_f32_16x16x32_bf16 v[88:91], v[148:151], v[180:183], v[88:91]
	v_mfma_f32_16x16x32_bf16 v[84:87], v[156:159], v[180:183], v[84:87]
	v_mfma_f32_16x16x32_bf16 v[72:75], v[148:151], v[188:191], v[72:75]
	v_mfma_f32_16x16x32_bf16 v[68:71], v[156:159], v[188:191], v[68:71]
	v_mfma_f32_16x16x32_bf16 v[120:123], v[152:155], v[168:171], v[120:123]
	v_mfma_f32_16x16x32_bf16 v[116:119], v[160:163], v[168:171], v[116:119]
	v_mfma_f32_16x16x32_bf16 v[104:107], v[152:155], v[176:179], v[104:107]
	v_mfma_f32_16x16x32_bf16 v[100:103], v[160:163], v[176:179], v[100:103]
	v_mfma_f32_16x16x32_bf16 v[88:91], v[152:155], v[184:187], v[88:91]
	v_mfma_f32_16x16x32_bf16 v[84:87], v[160:163], v[184:187], v[84:87]
	v_mfma_f32_16x16x32_bf16 v[72:75], v[152:155], v[192:195], v[72:75]
	v_mfma_f32_16x16x32_bf16 v[68:71], v[160:163], v[192:195], v[68:71]
	s_setprio 0
	s_barrier
	s_add_i32 s12, s14, s70
	v_lshl_add_u64 v[196:197], v[196:197], 0, s[68:69]
	s_mov_b32 m0, s12
	ds_read_b128 v[164:167], v243 offset:49152
	ds_read_b128 v[168:171], v243 offset:50176
	ds_read_b128 v[172:175], v243 offset:51200
	ds_read_b128 v[176:179], v243 offset:52224
	ds_read_b128 v[180:183], v243 offset:53248
	ds_read_b128 v[184:187], v243 offset:54272
	ds_read_b128 v[188:191], v243 offset:55296
	ds_read_b128 v[192:195], v243 offset:56320
	global_load_lds_dwordx4 v[196:197], off
	s_add_i32 m0, s12, 0x2000
	s_add_u32 s12, s40, 0x40080
	v_lshl_add_u64 v[196:197], v[198:199], 0, s[68:69]
	s_addc_u32 s13, s41, 0
	s_add_i32 s14, s15, s70
	global_load_lds_dwordx4 v[196:197], off
	v_lshl_add_u64 v[196:197], s[12:13], 0, v[2:3]
	s_mov_b32 m0, s14
	s_nop 0
	global_load_lds_dwordx4 v[196:197], off
	v_lshl_add_u64 v[196:197], s[12:13], 0, v[218:219]
	s_add_i32 m0, s14, 0x2000
	s_nop 0
	global_load_lds_dwordx4 v[196:197], off
	v_lshl_add_u64 v[196:197], v[200:201], 0, s[68:69]
	s_mov_b32 m0, s85
	s_nop 0
	global_load_lds_dwordx4 v[196:197], off
	v_lshl_add_u64 v[196:197], v[202:203], 0, s[68:69]
	s_mov_b32 m0, s87
	s_nop 0
	global_load_lds_dwordx4 v[196:197], off
	s_waitcnt vmcnt(8)
	s_waitcnt lgkmcnt(0)
	s_barrier
	s_setprio 1
	s_waitcnt lgkmcnt(0)
	v_mfma_f32_16x16x32_bf16 v[64:67], v[124:127], v[164:167], v[64:67]
	v_mfma_f32_16x16x32_bf16 v[60:63], v[136:139], v[164:167], v[60:63]
	v_mfma_f32_16x16x32_bf16 v[48:51], v[124:127], v[172:175], v[48:51]
	v_mfma_f32_16x16x32_bf16 v[44:47], v[136:139], v[172:175], v[44:47]
	v_mfma_f32_16x16x32_bf16 v[32:35], v[124:127], v[180:183], v[32:35]
	v_mfma_f32_16x16x32_bf16 v[28:31], v[136:139], v[180:183], v[28:31]
	v_mfma_f32_16x16x32_bf16 v[16:19], v[124:127], v[188:191], v[16:19]
	v_mfma_f32_16x16x32_bf16 v[12:15], v[136:139], v[188:191], v[12:15]
	v_mfma_f32_16x16x32_bf16 v[64:67], v[128:131], v[168:171], v[64:67]
	v_mfma_f32_16x16x32_bf16 v[60:63], v[144:147], v[168:171], v[60:63]
	v_mfma_f32_16x16x32_bf16 v[48:51], v[128:131], v[176:179], v[48:51]
	v_mfma_f32_16x16x32_bf16 v[44:47], v[144:147], v[176:179], v[44:47]
	v_mfma_f32_16x16x32_bf16 v[32:35], v[128:131], v[184:187], v[32:35]
	v_mfma_f32_16x16x32_bf16 v[28:31], v[144:147], v[184:187], v[28:31]
	v_mfma_f32_16x16x32_bf16 v[16:19], v[128:131], v[192:195], v[16:19]
	v_mfma_f32_16x16x32_bf16 v[12:15], v[144:147], v[192:195], v[12:15]
	s_setprio 0
	s_setprio 1
	v_mfma_f32_16x16x32_bf16 v[56:59], v[148:151], v[164:167], v[56:59]
	v_mfma_f32_16x16x32_bf16 v[52:55], v[156:159], v[164:167], v[52:55]
	v_mfma_f32_16x16x32_bf16 v[40:43], v[148:151], v[172:175], v[40:43]
	v_mfma_f32_16x16x32_bf16 v[36:39], v[156:159], v[172:175], v[36:39]
	v_mfma_f32_16x16x32_bf16 v[24:27], v[148:151], v[180:183], v[24:27]
	v_mfma_f32_16x16x32_bf16 v[20:23], v[156:159], v[180:183], v[20:23]
	v_mfma_f32_16x16x32_bf16 v[8:11], v[148:151], v[188:191], v[8:11]
	v_mfma_f32_16x16x32_bf16 v[4:7], v[156:159], v[188:191], v[4:7]
	v_mfma_f32_16x16x32_bf16 v[56:59], v[152:155], v[168:171], v[56:59]
	v_mfma_f32_16x16x32_bf16 v[52:55], v[160:163], v[168:171], v[52:55]
	v_mfma_f32_16x16x32_bf16 v[40:43], v[152:155], v[176:179], v[40:43]
	v_mfma_f32_16x16x32_bf16 v[36:39], v[160:163], v[176:179], v[36:39]
	v_mfma_f32_16x16x32_bf16 v[24:27], v[152:155], v[184:187], v[24:27]
	v_mfma_f32_16x16x32_bf16 v[20:23], v[160:163], v[184:187], v[20:23]
	v_mfma_f32_16x16x32_bf16 v[8:11], v[152:155], v[192:195], v[8:11]
	v_mfma_f32_16x16x32_bf16 v[4:7], v[160:163], v[192:195], v[4:7]
	s_setprio 0
	s_barrier
	s_add_i32 s11, s11, 2
	s_add_u32 s9, s9, 0x100
	s_addc_u32 s10, s10, 0
	s_add_u32 s38, s38, 0x100
	s_addc_u32 s39, s39, 0
	s_cmp_gt_u32 s11, 13

.LBB0_950:
	v_mul_f32_e32 v124, v141, v141
	v_mul_f32_e32 v125, v143, v143
	v_fmac_f32_e32 v124, v140, v140
	v_fmac_f32_e32 v125, v142, v142
	v_add_f32_e32 v124, v124, v125
	v_mul_f32_e32 v125, v133, v133
	v_mul_f32_e32 v126, v135, v135
	v_fmac_f32_e32 v125, v132, v132
	v_fmac_f32_e32 v126, v134, v134
	v_add_f32_e32 v125, v125, v126
	v_add_f32_e32 v124, v124, v125
	v_mul_f32_e32 v125, v121, v121
	v_mul_f32_e32 v126, v123, v123
	v_fmac_f32_e32 v125, v120, v120
	v_fmac_f32_e32 v126, v122, v122
	v_add_f32_e32 v125, v125, v126
	v_add_f32_e32 v124, v124, v125
	v_mul_f32_e32 v125, v117, v117
	v_mul_f32_e32 v126, v119, v119
	v_fmac_f32_e32 v125, v116, v116
	v_fmac_f32_e32 v126, v118, v118
	v_add_f32_e32 v125, v125, v126
	v_add_f32_e32 v124, v124, v125
	v_mov_b32_e32 v125, v124
	s_nop 1
	v_permlane16_swap_b32_e32 v124, v125
	v_mov_b32_e32 v246, v234
	s_waitcnt lgkmcnt(0)
	v_add_f32_e32 v125, v124, v125
	v_mov_b32_e32 v126, v125
	s_nop 1
	v_permlane32_swap_b32_e32 v125, v126
	v_cmp_gt_u32_e64 s[38:39], 16, v246
	v_lshl_add_u32 v124, v246, 4, s88
	s_and_saveexec_b64 s[40:41], s[38:39]
	s_cbranch_execz .LBB0_952
	s_waitcnt lgkmcnt(0)
	v_add_f32_e32 v125, v125, v126
	ds_write_b32 v124, v125
.LBB0_952:
	s_or_b64 exec, exec, s[40:41]
	v_mul_f32_e32 v125, v113, v113
	s_waitcnt lgkmcnt(0)
	v_mul_f32_e32 v126, v115, v115
	v_fmac_f32_e32 v125, v112, v112
	v_fmac_f32_e32 v126, v114, v114
	v_add_f32_e32 v125, v125, v126
	v_mul_f32_e32 v126, v109, v109
	v_mul_f32_e32 v127, v111, v111
	v_fmac_f32_e32 v126, v108, v108
	v_fmac_f32_e32 v127, v110, v110
	v_add_f32_e32 v126, v126, v127
	v_add_f32_e32 v125, v125, v126
	v_mul_f32_e32 v126, v105, v105
	v_mul_f32_e32 v127, v107, v107
	v_fmac_f32_e32 v126, v104, v104
	v_fmac_f32_e32 v127, v106, v106
	v_add_f32_e32 v126, v126, v127
	v_add_f32_e32 v125, v125, v126
	v_mul_f32_e32 v126, v101, v101
	v_mul_f32_e32 v127, v103, v103
	v_fmac_f32_e32 v126, v100, v100
	v_fmac_f32_e32 v127, v102, v102
	v_add_f32_e32 v126, v126, v127
	v_add_f32_e32 v125, v125, v126
	v_mov_b32_e32 v126, v125
	s_nop 1
	v_permlane16_swap_b32_e32 v125, v126
	s_waitcnt lgkmcnt(0)
	v_add_f32_e32 v125, v125, v126
	v_mov_b32_e32 v126, v125
	s_nop 1
	v_permlane32_swap_b32_e32 v125, v126
	s_and_saveexec_b64 s[40:41], s[38:39]
	s_cbranch_execz .LBB0_954
	s_waitcnt lgkmcnt(0)
	v_add_f32_e32 v125, v125, v126
	ds_write_b32 v124, v125 offset:256
.LBB0_954:
	s_or_b64 exec, exec, s[40:41]
	v_mul_f32_e32 v125, v97, v97
	s_waitcnt lgkmcnt(0)
	v_mul_f32_e32 v126, v99, v99
	v_fmac_f32_e32 v125, v96, v96
	v_fmac_f32_e32 v126, v98, v98
	v_add_f32_e32 v125, v125, v126
	v_mul_f32_e32 v126, v93, v93
	v_mul_f32_e32 v127, v95, v95
	v_fmac_f32_e32 v126, v92, v92
	v_fmac_f32_e32 v127, v94, v94
	v_add_f32_e32 v126, v126, v127
	v_add_f32_e32 v125, v125, v126
	v_mul_f32_e32 v126, v89, v89
	v_mul_f32_e32 v127, v91, v91
	v_fmac_f32_e32 v126, v88, v88
	v_fmac_f32_e32 v127, v90, v90
	v_add_f32_e32 v126, v126, v127
	v_add_f32_e32 v125, v125, v126
	v_mul_f32_e32 v126, v85, v85
	v_mul_f32_e32 v127, v87, v87
	v_fmac_f32_e32 v126, v84, v84
	v_fmac_f32_e32 v127, v86, v86
	v_add_f32_e32 v126, v126, v127
	v_add_f32_e32 v125, v125, v126
	v_mov_b32_e32 v126, v125
	s_nop 1
	v_permlane16_swap_b32_e32 v125, v126
	s_waitcnt lgkmcnt(0)
	v_add_f32_e32 v125, v125, v126
	v_mov_b32_e32 v126, v125
	s_nop 1
	v_permlane32_swap_b32_e32 v125, v126
	s_and_saveexec_b64 s[40:41], s[38:39]
	s_cbranch_execz .LBB0_956
	s_waitcnt lgkmcnt(0)
	v_add_f32_e32 v125, v125, v126
	ds_write_b32 v124, v125 offset:512
.LBB0_956:
	s_or_b64 exec, exec, s[40:41]
	v_mul_f32_e32 v125, v81, v81
	s_waitcnt lgkmcnt(0)
	v_mul_f32_e32 v126, v83, v83
	v_fmac_f32_e32 v125, v80, v80
	v_fmac_f32_e32 v126, v82, v82
	v_add_f32_e32 v125, v125, v126
	v_mul_f32_e32 v126, v77, v77
	v_mul_f32_e32 v127, v79, v79
	v_fmac_f32_e32 v126, v76, v76
	v_fmac_f32_e32 v127, v78, v78
	v_add_f32_e32 v126, v126, v127
	v_add_f32_e32 v125, v125, v126
	v_mul_f32_e32 v126, v73, v73
	v_mul_f32_e32 v127, v75, v75
	v_fmac_f32_e32 v126, v72, v72
	v_fmac_f32_e32 v127, v74, v74
	v_add_f32_e32 v126, v126, v127
	v_add_f32_e32 v125, v125, v126
	v_mul_f32_e32 v126, v69, v69
	v_mul_f32_e32 v127, v71, v71
	v_fmac_f32_e32 v126, v68, v68
	v_fmac_f32_e32 v127, v70, v70
	v_add_f32_e32 v126, v126, v127
	v_add_f32_e32 v125, v125, v126
	v_mov_b32_e32 v126, v125
	s_nop 1
	v_permlane16_swap_b32_e32 v125, v126
	s_waitcnt lgkmcnt(0)
	v_add_f32_e32 v125, v125, v126
	v_mov_b32_e32 v126, v125
	s_nop 1
	v_permlane32_swap_b32_e32 v125, v126
	s_and_saveexec_b64 s[40:41], s[38:39]
	s_cbranch_execz .LBB0_958
	s_waitcnt lgkmcnt(0)
	v_add_f32_e32 v125, v125, v126
	ds_write_b32 v124, v125 offset:768
.LBB0_958:
	s_or_b64 exec, exec, s[40:41]
	v_mul_f32_e32 v125, v65, v65
	s_waitcnt lgkmcnt(0)
	v_mul_f32_e32 v126, v67, v67
	v_fmac_f32_e32 v125, v64, v64
	v_fmac_f32_e32 v126, v66, v66
	v_add_f32_e32 v125, v125, v126
	v_mul_f32_e32 v126, v61, v61
	v_mul_f32_e32 v127, v63, v63
	v_fmac_f32_e32 v126, v60, v60
	v_fmac_f32_e32 v127, v62, v62
	v_add_f32_e32 v126, v126, v127
	v_add_f32_e32 v125, v125, v126
	v_mul_f32_e32 v126, v57, v57
	v_mul_f32_e32 v127, v59, v59
	v_fmac_f32_e32 v126, v56, v56
	v_fmac_f32_e32 v127, v58, v58
	v_add_f32_e32 v126, v126, v127
	v_add_f32_e32 v125, v125, v126
	v_mul_f32_e32 v126, v53, v53
	v_mul_f32_e32 v127, v55, v55
	v_fmac_f32_e32 v126, v52, v52
	v_fmac_f32_e32 v127, v54, v54
	v_add_f32_e32 v126, v126, v127
	v_add_f32_e32 v125, v125, v126
	v_mov_b32_e32 v126, v125
	s_nop 1
	v_permlane16_swap_b32_e32 v125, v126
	s_waitcnt lgkmcnt(0)
	v_add_f32_e32 v125, v125, v126
	v_mov_b32_e32 v126, v125
	s_nop 1
	v_permlane32_swap_b32_e32 v125, v126
	s_and_saveexec_b64 s[40:41], s[38:39]
	s_cbranch_execz .LBB0_960
	s_waitcnt lgkmcnt(0)
	v_add_f32_e32 v125, v125, v126
	ds_write_b32 v124, v125 offset:2048
.LBB0_960:
	s_or_b64 exec, exec, s[40:41]
	v_mul_f32_e32 v125, v49, v49
	s_waitcnt lgkmcnt(0)
	v_mul_f32_e32 v126, v51, v51
	v_fmac_f32_e32 v125, v48, v48
	v_fmac_f32_e32 v126, v50, v50
	v_add_f32_e32 v125, v125, v126
	v_mul_f32_e32 v126, v45, v45
	v_mul_f32_e32 v127, v47, v47
	v_fmac_f32_e32 v126, v44, v44
	v_fmac_f32_e32 v127, v46, v46
	v_add_f32_e32 v126, v126, v127
	v_add_f32_e32 v125, v125, v126
	v_mul_f32_e32 v126, v41, v41
	v_mul_f32_e32 v127, v43, v43
	v_fmac_f32_e32 v126, v40, v40
	v_fmac_f32_e32 v127, v42, v42
	v_add_f32_e32 v126, v126, v127
	v_add_f32_e32 v125, v125, v126
	v_mul_f32_e32 v126, v37, v37
	v_mul_f32_e32 v127, v39, v39
	v_fmac_f32_e32 v126, v36, v36
	v_fmac_f32_e32 v127, v38, v38
	v_add_f32_e32 v126, v126, v127
	v_add_f32_e32 v125, v125, v126
	v_mov_b32_e32 v126, v125
	s_nop 1
	v_permlane16_swap_b32_e32 v125, v126
	s_waitcnt lgkmcnt(0)
	v_add_f32_e32 v125, v125, v126
	v_mov_b32_e32 v126, v125
	s_nop 1
	v_permlane32_swap_b32_e32 v125, v126
	s_and_saveexec_b64 s[40:41], s[38:39]
	s_cbranch_execz .LBB0_962
	s_waitcnt lgkmcnt(0)
	v_add_f32_e32 v125, v125, v126
	ds_write_b32 v124, v125 offset:2304
.LBB0_962:
	s_or_b64 exec, exec, s[40:41]
	v_mul_f32_e32 v125, v33, v33
	s_waitcnt lgkmcnt(0)
	v_mul_f32_e32 v126, v35, v35
	v_fmac_f32_e32 v125, v32, v32
	v_fmac_f32_e32 v126, v34, v34
	v_add_f32_e32 v125, v125, v126
	v_mul_f32_e32 v126, v29, v29
	v_mul_f32_e32 v127, v31, v31
	v_fmac_f32_e32 v126, v28, v28
	v_fmac_f32_e32 v127, v30, v30
	v_add_f32_e32 v126, v126, v127
	v_add_f32_e32 v125, v125, v126
	v_mul_f32_e32 v126, v25, v25
	v_mul_f32_e32 v127, v27, v27
	v_fmac_f32_e32 v126, v24, v24
	v_fmac_f32_e32 v127, v26, v26
	v_add_f32_e32 v126, v126, v127
	v_add_f32_e32 v125, v125, v126
	v_mul_f32_e32 v126, v21, v21
	v_mul_f32_e32 v127, v23, v23
	v_fmac_f32_e32 v126, v20, v20
	v_fmac_f32_e32 v127, v22, v22
	v_add_f32_e32 v126, v126, v127
	v_add_f32_e32 v125, v125, v126
	v_mov_b32_e32 v126, v125
	s_nop 1
	v_permlane16_swap_b32_e32 v125, v126
	s_waitcnt lgkmcnt(0)
	v_add_f32_e32 v125, v125, v126
	v_mov_b32_e32 v126, v125
	s_nop 1
	v_permlane32_swap_b32_e32 v125, v126
	s_and_saveexec_b64 s[40:41], s[38:39]
	s_cbranch_execz .LBB0_964
	s_waitcnt lgkmcnt(0)
	v_add_f32_e32 v125, v125, v126
	ds_write_b32 v124, v125 offset:2560
.LBB0_964:
	s_or_b64 exec, exec, s[40:41]
	v_mul_f32_e32 v125, v17, v17
	s_waitcnt lgkmcnt(0)
	v_mul_f32_e32 v126, v19, v19
	v_fmac_f32_e32 v125, v16, v16
	v_fmac_f32_e32 v126, v18, v18
	v_add_f32_e32 v125, v125, v126
	v_mul_f32_e32 v126, v13, v13
	v_mul_f32_e32 v127, v15, v15
	v_fmac_f32_e32 v126, v12, v12
	v_fmac_f32_e32 v127, v14, v14
	v_add_f32_e32 v126, v126, v127
	v_add_f32_e32 v125, v125, v126
	v_mul_f32_e32 v126, v9, v9
	v_mul_f32_e32 v127, v11, v11
	v_fmac_f32_e32 v126, v8, v8
	v_fmac_f32_e32 v127, v10, v10
	v_add_f32_e32 v126, v126, v127
	v_add_f32_e32 v125, v125, v126
	v_mul_f32_e32 v126, v5, v5
	v_mul_f32_e32 v127, v7, v7
	v_fmac_f32_e32 v126, v4, v4
	v_fmac_f32_e32 v127, v6, v6
	v_add_f32_e32 v126, v126, v127
	v_add_f32_e32 v125, v125, v126
	v_mov_b32_e32 v126, v125
	s_nop 1
	v_permlane16_swap_b32_e32 v125, v126
	s_waitcnt lgkmcnt(0)
	v_add_f32_e32 v125, v125, v126
	v_mov_b32_e32 v126, v125
	s_nop 1
	v_permlane32_swap_b32_e32 v125, v126
	s_and_saveexec_b64 s[40:41], s[38:39]
	s_cbranch_execz .LBB0_966
	s_waitcnt lgkmcnt(0)
	v_add_f32_e32 v125, v125, v126
	ds_write_b32 v124, v125 offset:2816

.LBB0_982:
	v_add_f32_e32 v212, v212, v213
	v_add_f32_e32 v213, v214, v215
	v_add_f32_e32 v212, v212, v213
	v_mov_b32_e32 v213, v212
	s_nop 1
	v_permlane32_swap_b32_e32 v212, v213
	s_and_saveexec_b64 s[56:57], s[40:41]
	s_cbranch_execz .LBB0_984
	s_waitcnt lgkmcnt(0)
	v_add_f32_e32 v212, v212, v213
	v_fmamk_f32 v212, v212, 0x3a000000, v232
	v_rsq_f32_e32 v212, v212
	v_lshl_add_u32 v213, v247, 2, 0
	v_add_u32_e32 v213, 0x21400, v213
	ds_write_b32 v213, v212
.LBB0_984:
	s_or_b64 exec, exec, s[56:57]
	v_or_b32_e32 v212, s83, v248
	s_waitcnt lgkmcnt(0)
	v_lshl_add_u32 v213, v212, 2, 0
	s_waitcnt lgkmcnt(0)
	s_barrier
	v_add_u32_e32 v213, 0x21400, v213
	ds_read_b32 v214, v213
	s_waitcnt vmcnt(0)
	v_lshlrev_b32_e32 v246, 16, v208
	v_and_b32_e32 v247, 0xffff0000, v208
	v_lshlrev_b32_e32 v208, 16, v209
	v_and_b32_e32 v209, 0xffff0000, v209
	s_waitcnt lgkmcnt(0)
	v_pk_mul_f32 v[142:143], v[142:143], v[214:215] op_sel_hi:[1,0]
	v_pk_mul_f32 v[140:141], v[140:141], v[214:215] op_sel_hi:[1,0]
	v_pk_fma_f32 v[142:143], v[146:147], v[142:143], v[208:209]
	v_pk_fma_f32 v[140:141], v[144:145], v[140:141], v[246:247]
	v_mul_f32_e32 v209, v143, v143
	v_mul_f32_e32 v208, v141, v141
	v_fmac_f32_e32 v208, v140, v140
	v_fmac_f32_e32 v209, v142, v142
	v_add_f32_e32 v215, v208, v209
	v_cvt_pk_bf16_f32 v140, v140, v141
	v_cvt_pk_bf16_f32 v141, v142, v143
	v_lshlrev_b32_e32 v142, 16, v210
	v_and_b32_e32 v143, 0xffff0000, v210
	v_lshlrev_b32_e32 v208, 16, v211
	v_and_b32_e32 v209, 0xffff0000, v211
	v_pk_mul_f32 v[134:135], v[134:135], v[214:215] op_sel_hi:[1,0]
	v_pk_mul_f32 v[132:133], v[132:133], v[214:215] op_sel_hi:[1,0]
	v_pk_fma_f32 v[134:135], v[138:139], v[134:135], v[208:209]
	v_pk_fma_f32 v[132:133], v[136:137], v[132:133], v[142:143]
	v_mul_f32_e32 v143, v135, v135
	v_mul_f32_e32 v142, v133, v133
	v_fmac_f32_e32 v142, v132, v132
	v_fmac_f32_e32 v143, v134, v134
	v_add_f32_e32 v142, v142, v143
	v_add_f32_e32 v208, v215, v142
	v_cvt_pk_bf16_f32 v142, v132, v133
	v_cvt_pk_bf16_f32 v143, v134, v135
	v_lshlrev_b32_e32 v134, 16, v204
	v_and_b32_e32 v135, 0xffff0000, v204
	v_lshlrev_b32_e32 v204, 16, v205
	v_and_b32_e32 v205, 0xffff0000, v205
	v_pk_mul_f32 v[122:123], v[122:123], v[214:215] op_sel_hi:[1,0]
	v_pk_mul_f32 v[120:121], v[120:121], v[214:215] op_sel_hi:[1,0]
	v_pk_fma_f32 v[122:123], v[130:131], v[122:123], v[204:205]
	v_pk_fma_f32 v[120:121], v[128:129], v[120:121], v[134:135]
	v_mul_f32_e32 v135, v123, v123
	v_mul_f32_e32 v134, v121, v121
	v_fmac_f32_e32 v134, v120, v120
	v_fmac_f32_e32 v135, v122, v122
	v_add_f32_e32 v134, v134, v135
	v_add_f32_e32 v208, v134, v208
	v_lshlrev_b32_e32 v134, 16, v206
	v_and_b32_e32 v135, 0xffff0000, v206
	v_lshlrev_b32_e32 v204, 16, v207
	v_and_b32_e32 v205, 0xffff0000, v207
	v_pk_mul_f32 v[118:119], v[118:119], v[214:215] op_sel_hi:[1,0]
	v_pk_mul_f32 v[116:117], v[116:117], v[214:215] op_sel_hi:[1,0]
	v_pk_fma_f32 v[204:205], v[126:127], v[118:119], v[204:205]
	v_pk_fma_f32 v[134:135], v[124:125], v[116:117], v[134:135]
	v_mul_f32_e32 v117, v205, v205
	v_mul_f32_e32 v116, v135, v135
	v_fmac_f32_e32 v116, v134, v134
	v_fmac_f32_e32 v117, v204, v204
	v_add_f32_e32 v116, v116, v117
	v_add_f32_e32 v119, v116, v208
	v_mov_b32_e32 v206, v119
	s_nop 1
	v_permlane16_swap_b32_e32 v119, v206
	v_add_u32_e32 v228, v212, v245
	v_ashrrev_i32_e32 v229, 31, v228
	v_lshlrev_b64 v[132:133], 12, v[228:229]
	v_lshl_add_u64 v[116:117], s[24:25], 0, v[132:133]
	v_lshl_add_u64 v[132:133], v[226:227], 1, v[116:117]
	s_waitcnt lgkmcnt(0)
	v_add_f32_e32 v116, v119, v206
	v_mov_b32_e32 v117, v116
	s_nop 1
	v_permlane32_swap_b32_e32 v116, v117
	global_store_dwordx4 v[132:133], v[140:143], off
	v_cvt_pk_bf16_f32 v118, v120, v121
	v_cvt_pk_bf16_f32 v119, v122, v123
	v_cvt_pk_bf16_f32 v120, v134, v135
	v_cvt_pk_bf16_f32 v121, v204, v205
	global_store_dwordx4 v[132:133], v[118:121], off offset:256
	s_and_saveexec_b64 s[56:57], s[38:39]
	s_cbranch_execz .LBB0_986
	v_lshl_add_u32 v118, v212, 4, s66
	s_waitcnt lgkmcnt(0)
	v_add_f32_e32 v116, v116, v117
	ds_write_b32 v118, v116
.LBB0_986:
	s_or_b64 exec, exec, s[56:57]
	v_or_b32_e32 v116, 16, v212
	s_waitcnt lgkmcnt(0)
	v_lshl_add_u32 v117, v116, 2, 0
	v_add_u32_e32 v117, 0x21400, v117
	ds_read_b32 v118, v117
	v_lshlrev_b32_e32 v132, 16, v201
	v_and_b32_e32 v133, 0xffff0000, v201
	v_lshlrev_b32_e32 v122, 16, v200
	v_and_b32_e32 v123, 0xffff0000, v200
	s_waitcnt lgkmcnt(0)
	v_pk_mul_f32 v[114:115], v[114:115], v[118:119] op_sel_hi:[1,0]
	v_pk_mul_f32 v[112:113], v[112:113], v[118:119] op_sel_hi:[1,0]
	v_pk_fma_f32 v[114:115], v[146:147], v[114:115], v[132:133]
	v_pk_fma_f32 v[112:113], v[144:145], v[112:113], v[122:123]
	v_mul_f32_e32 v119, v115, v115
	v_mul_f32_e32 v117, v113, v113
	v_fmac_f32_e32 v119, v114, v114
	v_fmac_f32_e32 v117, v112, v112
	v_cvt_pk_bf16_f32 v112, v112, v113
	v_cvt_pk_bf16_f32 v113, v114, v115
	v_lshlrev_b32_e32 v114, 16, v202
	v_and_b32_e32 v115, 0xffff0000, v202
	v_lshlrev_b32_e32 v122, 16, v203
	v_and_b32_e32 v123, 0xffff0000, v203
	v_pk_mul_f32 v[110:111], v[110:111], v[118:119] op_sel_hi:[1,0]
	v_pk_mul_f32 v[108:109], v[108:109], v[118:119] op_sel_hi:[1,0]
	v_pk_fma_f32 v[110:111], v[138:139], v[110:111], v[122:123]
	v_pk_fma_f32 v[108:109], v[136:137], v[108:109], v[114:115]
	v_mul_f32_e32 v115, v111, v111
	v_mul_f32_e32 v114, v109, v109
	v_add_u32_e32 v120, v116, v245
	v_fmac_f32_e32 v114, v108, v108
	v_fmac_f32_e32 v115, v110, v110
	v_ashrrev_i32_e32 v121, 31, v120
	v_add_f32_e32 v117, v117, v119
	v_add_f32_e32 v114, v114, v115
	v_add_f32_e32 v117, v117, v114
	v_cvt_pk_bf16_f32 v114, v108, v109
	v_cvt_pk_bf16_f32 v115, v110, v111
	v_lshlrev_b64 v[108:109], 12, v[120:121]
	v_lshlrev_b32_e32 v110, 16, v196
	v_and_b32_e32 v111, 0xffff0000, v196
	v_lshlrev_b32_e32 v120, 16, v197
	v_and_b32_e32 v121, 0xffff0000, v197
	v_pk_mul_f32 v[106:107], v[106:107], v[118:119] op_sel_hi:[1,0]
	v_pk_mul_f32 v[104:105], v[104:105], v[118:119] op_sel_hi:[1,0]
	v_pk_fma_f32 v[106:107], v[130:131], v[106:107], v[120:121]
	v_pk_fma_f32 v[104:105], v[128:129], v[104:105], v[110:111]
	v_mul_f32_e32 v111, v107, v107
	v_mul_f32_e32 v110, v105, v105
	v_fmac_f32_e32 v110, v104, v104
	v_fmac_f32_e32 v111, v106, v106
	v_add_f32_e32 v110, v110, v111
	v_add_f32_e32 v117, v110, v117
	v_lshlrev_b32_e32 v110, 16, v198
	v_and_b32_e32 v111, 0xffff0000, v198
	v_lshlrev_b32_e32 v120, 16, v199
	v_and_b32_e32 v121, 0xffff0000, v199
	v_pk_mul_f32 v[102:103], v[102:103], v[118:119] op_sel_hi:[1,0]
	v_pk_mul_f32 v[100:101], v[100:101], v[118:119] op_sel_hi:[1,0]
	v_pk_fma_f32 v[118:119], v[126:127], v[102:103], v[120:121]
	v_pk_fma_f32 v[110:111], v[124:125], v[100:101], v[110:111]
	v_mul_f32_e32 v101, v119, v119
	v_mul_f32_e32 v100, v111, v111
	v_fmac_f32_e32 v100, v110, v110
	v_fmac_f32_e32 v101, v118, v118
	v_add_f32_e32 v100, v100, v101
	v_add_f32_e32 v103, v100, v117
	v_mov_b32_e32 v117, v103
	s_nop 1
	v_permlane16_swap_b32_e32 v103, v117
	v_lshl_add_u64 v[100:101], s[24:25], 0, v[108:109]
	v_lshl_add_u64 v[108:109], v[226:227], 1, v[100:101]
	global_store_dwordx4 v[108:109], v[112:115], off
	v_cvt_pk_bf16_f32 v102, v104, v105
	s_waitcnt lgkmcnt(0)
	v_add_f32_e32 v100, v103, v117
	v_mov_b32_e32 v101, v100
	s_nop 1
	v_permlane32_swap_b32_e32 v100, v101
	v_cvt_pk_bf16_f32 v103, v106, v107
	v_cvt_pk_bf16_f32 v104, v110, v111
	v_cvt_pk_bf16_f32 v105, v118, v119
	global_store_dwordx4 v[108:109], v[102:105], off offset:256
	s_and_saveexec_b64 s[56:57], s[38:39]
	s_cbranch_execz .LBB0_988
	v_lshl_add_u32 v102, v116, 4, s66
	s_waitcnt lgkmcnt(0)
	v_add_f32_e32 v100, v100, v101
	ds_write_b32 v102, v100
.LBB0_988:
	s_or_b64 exec, exec, s[56:57]
	v_or_b32_e32 v100, 32, v212
	s_waitcnt lgkmcnt(0)
	v_lshl_add_u32 v101, v100, 2, 0
	v_add_u32_e32 v101, 0x21400, v101
	ds_read_b32 v102, v101
	v_lshlrev_b32_e32 v108, 16, v193
	v_and_b32_e32 v109, 0xffff0000, v193
	v_lshlrev_b32_e32 v106, 16, v192
	v_and_b32_e32 v107, 0xffff0000, v192
	s_waitcnt lgkmcnt(0)
	v_pk_mul_f32 v[98:99], v[98:99], v[102:103] op_sel_hi:[1,0]
	v_pk_mul_f32 v[96:97], v[96:97], v[102:103] op_sel_hi:[1,0]
	v_pk_fma_f32 v[98:99], v[146:147], v[98:99], v[108:109]
	v_pk_fma_f32 v[96:97], v[144:145], v[96:97], v[106:107]
	v_mul_f32_e32 v103, v99, v99
	v_mul_f32_e32 v101, v97, v97
	v_fmac_f32_e32 v103, v98, v98
	v_fmac_f32_e32 v101, v96, v96
	v_cvt_pk_bf16_f32 v96, v96, v97
	v_cvt_pk_bf16_f32 v97, v98, v99
	v_lshlrev_b32_e32 v98, 16, v194
	v_and_b32_e32 v99, 0xffff0000, v194
	v_lshlrev_b32_e32 v106, 16, v195
	v_and_b32_e32 v107, 0xffff0000, v195
	v_pk_mul_f32 v[94:95], v[94:95], v[102:103] op_sel_hi:[1,0]
	v_pk_mul_f32 v[92:93], v[92:93], v[102:103] op_sel_hi:[1,0]
	v_pk_fma_f32 v[94:95], v[138:139], v[94:95], v[106:107]
	v_pk_fma_f32 v[92:93], v[136:137], v[92:93], v[98:99]
	v_mul_f32_e32 v99, v95, v95
	v_mul_f32_e32 v98, v93, v93
	v_add_u32_e32 v104, v100, v245
	v_fmac_f32_e32 v98, v92, v92
	v_fmac_f32_e32 v99, v94, v94
	v_ashrrev_i32_e32 v105, 31, v104
	v_add_f32_e32 v101, v101, v103
	v_add_f32_e32 v98, v98, v99
	v_add_f32_e32 v101, v101, v98
	v_cvt_pk_bf16_f32 v98, v92, v93
	v_cvt_pk_bf16_f32 v99, v94, v95
	v_lshlrev_b64 v[92:93], 12, v[104:105]
	v_lshlrev_b32_e32 v94, 16, v188
	v_and_b32_e32 v95, 0xffff0000, v188
	v_lshlrev_b32_e32 v104, 16, v189
	v_and_b32_e32 v105, 0xffff0000, v189
	v_pk_mul_f32 v[90:91], v[90:91], v[102:103] op_sel_hi:[1,0]
	v_pk_mul_f32 v[88:89], v[88:89], v[102:103] op_sel_hi:[1,0]
	v_pk_fma_f32 v[90:91], v[130:131], v[90:91], v[104:105]
	v_pk_fma_f32 v[88:89], v[128:129], v[88:89], v[94:95]
	v_mul_f32_e32 v95, v91, v91
	v_mul_f32_e32 v94, v89, v89
	v_fmac_f32_e32 v94, v88, v88
	v_fmac_f32_e32 v95, v90, v90
	v_add_f32_e32 v94, v94, v95
	v_add_f32_e32 v101, v94, v101
	v_lshlrev_b32_e32 v94, 16, v190
	v_and_b32_e32 v95, 0xffff0000, v190
	v_lshlrev_b32_e32 v104, 16, v191
	v_and_b32_e32 v105, 0xffff0000, v191
	v_pk_mul_f32 v[86:87], v[86:87], v[102:103] op_sel_hi:[1,0]
	v_pk_mul_f32 v[84:85], v[84:85], v[102:103] op_sel_hi:[1,0]
	v_pk_fma_f32 v[102:103], v[126:127], v[86:87], v[104:105]
	v_pk_fma_f32 v[94:95], v[124:125], v[84:85], v[94:95]
	v_mul_f32_e32 v85, v103, v103
	v_mul_f32_e32 v84, v95, v95
	v_fmac_f32_e32 v84, v94, v94
	v_fmac_f32_e32 v85, v102, v102
	v_add_f32_e32 v84, v84, v85
	v_add_f32_e32 v87, v84, v101
	v_mov_b32_e32 v101, v87
	s_nop 1
	v_permlane16_swap_b32_e32 v87, v101
	v_lshl_add_u64 v[84:85], s[24:25], 0, v[92:93]
	v_lshl_add_u64 v[92:93], v[226:227], 1, v[84:85]
	global_store_dwordx4 v[92:93], v[96:99], off
	v_cvt_pk_bf16_f32 v86, v88, v89
	s_waitcnt lgkmcnt(0)
	v_add_f32_e32 v84, v87, v101
	v_mov_b32_e32 v85, v84
	s_nop 1
	v_permlane32_swap_b32_e32 v84, v85
	v_cvt_pk_bf16_f32 v87, v90, v91
	v_cvt_pk_bf16_f32 v88, v94, v95
	v_cvt_pk_bf16_f32 v89, v102, v103
	global_store_dwordx4 v[92:93], v[86:89], off offset:256
	s_and_saveexec_b64 s[56:57], s[38:39]
	s_cbranch_execz .LBB0_990
	v_lshl_add_u32 v86, v100, 4, s66
	s_waitcnt lgkmcnt(0)
	v_add_f32_e32 v84, v84, v85
	ds_write_b32 v86, v84
.LBB0_990:
	s_or_b64 exec, exec, s[56:57]
	v_or_b32_e32 v84, 48, v212
	s_waitcnt lgkmcnt(0)
	v_lshl_add_u32 v85, v84, 2, 0
	v_add_u32_e32 v85, 0x21400, v85
	ds_read_b32 v86, v85
	v_lshlrev_b32_e32 v92, 16, v185
	v_and_b32_e32 v93, 0xffff0000, v185
	v_lshlrev_b32_e32 v90, 16, v184
	v_and_b32_e32 v91, 0xffff0000, v184
	s_waitcnt lgkmcnt(0)
	v_pk_mul_f32 v[82:83], v[82:83], v[86:87] op_sel_hi:[1,0]
	v_pk_mul_f32 v[80:81], v[80:81], v[86:87] op_sel_hi:[1,0]
	v_pk_fma_f32 v[82:83], v[146:147], v[82:83], v[92:93]
	v_pk_fma_f32 v[80:81], v[144:145], v[80:81], v[90:91]
	v_mul_f32_e32 v87, v83, v83
	v_mul_f32_e32 v85, v81, v81
	v_fmac_f32_e32 v87, v82, v82
	v_fmac_f32_e32 v85, v80, v80
	v_cvt_pk_bf16_f32 v80, v80, v81
	v_cvt_pk_bf16_f32 v81, v82, v83
	v_lshlrev_b32_e32 v82, 16, v186
	v_and_b32_e32 v83, 0xffff0000, v186
	v_lshlrev_b32_e32 v90, 16, v187
	v_and_b32_e32 v91, 0xffff0000, v187
	v_pk_mul_f32 v[78:79], v[78:79], v[86:87] op_sel_hi:[1,0]
	v_pk_mul_f32 v[76:77], v[76:77], v[86:87] op_sel_hi:[1,0]
	v_pk_fma_f32 v[78:79], v[138:139], v[78:79], v[90:91]
	v_pk_fma_f32 v[76:77], v[136:137], v[76:77], v[82:83]
	v_mul_f32_e32 v83, v79, v79
	v_mul_f32_e32 v82, v77, v77
	v_add_u32_e32 v88, v84, v245
	v_fmac_f32_e32 v82, v76, v76
	v_fmac_f32_e32 v83, v78, v78
	v_ashrrev_i32_e32 v89, 31, v88
	v_add_f32_e32 v85, v85, v87
	v_add_f32_e32 v82, v82, v83
	v_add_f32_e32 v85, v85, v82
	v_cvt_pk_bf16_f32 v82, v76, v77
	v_cvt_pk_bf16_f32 v83, v78, v79
	v_lshlrev_b64 v[76:77], 12, v[88:89]
	v_lshlrev_b32_e32 v78, 16, v180
	v_and_b32_e32 v79, 0xffff0000, v180
	v_lshlrev_b32_e32 v88, 16, v181
	v_and_b32_e32 v89, 0xffff0000, v181
	v_pk_mul_f32 v[74:75], v[74:75], v[86:87] op_sel_hi:[1,0]
	v_pk_mul_f32 v[72:73], v[72:73], v[86:87] op_sel_hi:[1,0]
	v_pk_fma_f32 v[74:75], v[130:131], v[74:75], v[88:89]
	v_pk_fma_f32 v[72:73], v[128:129], v[72:73], v[78:79]
	v_mul_f32_e32 v79, v75, v75
	v_mul_f32_e32 v78, v73, v73
	v_fmac_f32_e32 v78, v72, v72
	v_fmac_f32_e32 v79, v74, v74
	v_add_f32_e32 v78, v78, v79
	v_add_f32_e32 v85, v78, v85
	v_lshlrev_b32_e32 v78, 16, v182
	v_and_b32_e32 v79, 0xffff0000, v182
	v_lshlrev_b32_e32 v88, 16, v183
	v_and_b32_e32 v89, 0xffff0000, v183
	v_pk_mul_f32 v[70:71], v[70:71], v[86:87] op_sel_hi:[1,0]
	v_pk_mul_f32 v[68:69], v[68:69], v[86:87] op_sel_hi:[1,0]
	v_pk_fma_f32 v[86:87], v[126:127], v[70:71], v[88:89]
	v_pk_fma_f32 v[78:79], v[124:125], v[68:69], v[78:79]
	v_mul_f32_e32 v69, v87, v87
	v_mul_f32_e32 v68, v79, v79
	v_fmac_f32_e32 v68, v78, v78
	v_fmac_f32_e32 v69, v86, v86
	v_add_f32_e32 v68, v68, v69
	v_add_f32_e32 v71, v68, v85
	ds_bpermute_b32 v85, v231, v71
	v_lshl_add_u64 v[68:69], s[24:25], 0, v[76:77]
	v_lshl_add_u64 v[76:77], v[226:227], 1, v[68:69]
	global_store_dwordx4 v[76:77], v[80:83], off
	v_cvt_pk_bf16_f32 v70, v72, v73
	s_waitcnt lgkmcnt(0)
	v_add_f32_e32 v68, v71, v85
	v_mov_b32_e32 v69, v68
	s_nop 1
	v_permlane32_swap_b32_e32 v68, v69
	v_cvt_pk_bf16_f32 v71, v74, v75
	v_cvt_pk_bf16_f32 v72, v78, v79
	v_cvt_pk_bf16_f32 v73, v86, v87
	global_store_dwordx4 v[76:77], v[70:73], off offset:256
	s_and_saveexec_b64 s[56:57], s[38:39]
	s_cbranch_execz .LBB0_992
	v_lshl_add_u32 v70, v84, 4, s66
	s_waitcnt lgkmcnt(0)
	v_add_f32_e32 v68, v68, v69
	ds_write_b32 v70, v68
.LBB0_992:
	s_or_b64 exec, exec, s[56:57]
	ds_read_b32 v70, v213 offset:512
	v_lshlrev_b32_e32 v76, 16, v177
	v_and_b32_e32 v77, 0xffff0000, v177
	v_lshlrev_b32_e32 v74, 16, v176
	v_and_b32_e32 v75, 0xffff0000, v176
	s_waitcnt lgkmcnt(0)
	v_pk_mul_f32 v[66:67], v[66:67], v[70:71] op_sel_hi:[1,0]
	v_pk_mul_f32 v[64:65], v[64:65], v[70:71] op_sel_hi:[1,0]
	v_pk_fma_f32 v[66:67], v[146:147], v[66:67], v[76:77]
	v_pk_fma_f32 v[64:65], v[144:145], v[64:65], v[74:75]
	v_mul_f32_e32 v71, v67, v67
	v_mul_f32_e32 v69, v65, v65
	v_fmac_f32_e32 v71, v66, v66
	v_fmac_f32_e32 v69, v64, v64
	v_cvt_pk_bf16_f32 v64, v64, v65
	v_cvt_pk_bf16_f32 v65, v66, v67
	v_lshlrev_b32_e32 v66, 16, v178
	v_and_b32_e32 v67, 0xffff0000, v178
	v_lshlrev_b32_e32 v74, 16, v179
	v_and_b32_e32 v75, 0xffff0000, v179
	v_pk_mul_f32 v[62:63], v[62:63], v[70:71] op_sel_hi:[1,0]
	v_pk_mul_f32 v[60:61], v[60:61], v[70:71] op_sel_hi:[1,0]
	v_pk_fma_f32 v[62:63], v[138:139], v[62:63], v[74:75]
	v_pk_fma_f32 v[60:61], v[136:137], v[60:61], v[66:67]
	v_add_u32_e32 v68, 0x80, v212
	v_mul_f32_e32 v66, v61, v61
	v_mul_f32_e32 v67, v63, v63
	v_add_u32_e32 v72, v68, v245
	v_fmac_f32_e32 v66, v60, v60
	v_fmac_f32_e32 v67, v62, v62
	v_ashrrev_i32_e32 v73, 31, v72
	v_add_f32_e32 v69, v69, v71
	v_add_f32_e32 v66, v66, v67
	v_add_f32_e32 v69, v69, v66
	v_cvt_pk_bf16_f32 v66, v60, v61
	v_cvt_pk_bf16_f32 v67, v62, v63
	v_lshlrev_b64 v[60:61], 12, v[72:73]
	v_lshlrev_b32_e32 v62, 16, v172
	v_and_b32_e32 v63, 0xffff0000, v172
	v_lshlrev_b32_e32 v72, 16, v173
	v_and_b32_e32 v73, 0xffff0000, v173
	v_pk_mul_f32 v[58:59], v[58:59], v[70:71] op_sel_hi:[1,0]
	v_pk_mul_f32 v[56:57], v[56:57], v[70:71] op_sel_hi:[1,0]
	v_pk_fma_f32 v[58:59], v[130:131], v[58:59], v[72:73]
	v_pk_fma_f32 v[56:57], v[128:129], v[56:57], v[62:63]
	v_mul_f32_e32 v63, v59, v59
	v_mul_f32_e32 v62, v57, v57
	v_fmac_f32_e32 v62, v56, v56
	v_fmac_f32_e32 v63, v58, v58
	v_add_f32_e32 v62, v62, v63
	v_add_f32_e32 v69, v62, v69
	v_lshlrev_b32_e32 v62, 16, v174
	v_and_b32_e32 v63, 0xffff0000, v174
	v_lshlrev_b32_e32 v72, 16, v175
	v_and_b32_e32 v73, 0xffff0000, v175
	v_pk_mul_f32 v[54:55], v[54:55], v[70:71] op_sel_hi:[1,0]
	v_pk_mul_f32 v[52:53], v[52:53], v[70:71] op_sel_hi:[1,0]
	v_pk_fma_f32 v[70:71], v[126:127], v[54:55], v[72:73]
	v_pk_fma_f32 v[62:63], v[124:125], v[52:53], v[62:63]
	v_mul_f32_e32 v53, v71, v71
	v_mul_f32_e32 v52, v63, v63
	v_fmac_f32_e32 v52, v62, v62
	v_fmac_f32_e32 v53, v70, v70
	v_add_f32_e32 v52, v52, v53
	v_add_f32_e32 v55, v52, v69
	v_mov_b32_e32 v69, v55
	s_nop 1
	v_permlane16_swap_b32_e32 v55, v69
	v_lshl_add_u64 v[52:53], s[24:25], 0, v[60:61]
	v_lshl_add_u64 v[60:61], v[226:227], 1, v[52:53]
	global_store_dwordx4 v[60:61], v[64:67], off
	v_cvt_pk_bf16_f32 v54, v56, v57
	s_waitcnt lgkmcnt(0)
	v_add_f32_e32 v52, v55, v69
	v_mov_b32_e32 v53, v52
	s_nop 1
	v_permlane32_swap_b32_e32 v52, v53
	v_cvt_pk_bf16_f32 v55, v58, v59
	v_cvt_pk_bf16_f32 v56, v62, v63
	v_cvt_pk_bf16_f32 v57, v70, v71
	global_store_dwordx4 v[60:61], v[54:57], off offset:256
	s_and_saveexec_b64 s[56:57], s[38:39]
	s_cbranch_execz .LBB0_994
	v_lshl_add_u32 v54, v68, 4, s66
	s_waitcnt lgkmcnt(0)
	v_add_f32_e32 v52, v52, v53
	ds_write_b32 v54, v52
.LBB0_994:
	s_or_b64 exec, exec, s[56:57]
	ds_read_b32 v54, v213 offset:576
	v_lshlrev_b32_e32 v60, 16, v169
	v_and_b32_e32 v61, 0xffff0000, v169
	v_lshlrev_b32_e32 v58, 16, v168
	v_and_b32_e32 v59, 0xffff0000, v168
	s_waitcnt lgkmcnt(0)
	v_pk_mul_f32 v[50:51], v[50:51], v[54:55] op_sel_hi:[1,0]
	v_pk_mul_f32 v[48:49], v[48:49], v[54:55] op_sel_hi:[1,0]
	v_pk_fma_f32 v[50:51], v[146:147], v[50:51], v[60:61]
	v_pk_fma_f32 v[48:49], v[144:145], v[48:49], v[58:59]
	v_mul_f32_e32 v55, v51, v51
	v_mul_f32_e32 v53, v49, v49
	v_fmac_f32_e32 v55, v50, v50
	v_fmac_f32_e32 v53, v48, v48
	v_cvt_pk_bf16_f32 v48, v48, v49
	v_cvt_pk_bf16_f32 v49, v50, v51
	v_lshlrev_b32_e32 v50, 16, v170
	v_and_b32_e32 v51, 0xffff0000, v170
	v_lshlrev_b32_e32 v58, 16, v171
	v_and_b32_e32 v59, 0xffff0000, v171
	v_pk_mul_f32 v[46:47], v[46:47], v[54:55] op_sel_hi:[1,0]
	v_pk_mul_f32 v[44:45], v[44:45], v[54:55] op_sel_hi:[1,0]
	v_pk_fma_f32 v[46:47], v[138:139], v[46:47], v[58:59]
	v_pk_fma_f32 v[44:45], v[136:137], v[44:45], v[50:51]
	v_add_u32_e32 v52, 0x90, v212
	v_mul_f32_e32 v50, v45, v45
	v_mul_f32_e32 v51, v47, v47
	v_add_u32_e32 v56, v52, v245
	v_fmac_f32_e32 v50, v44, v44
	v_fmac_f32_e32 v51, v46, v46
	v_ashrrev_i32_e32 v57, 31, v56
	v_add_f32_e32 v53, v53, v55
	v_add_f32_e32 v50, v50, v51
	v_add_f32_e32 v53, v53, v50
	v_cvt_pk_bf16_f32 v50, v44, v45
	v_cvt_pk_bf16_f32 v51, v46, v47
	v_lshlrev_b64 v[44:45], 12, v[56:57]
	v_lshlrev_b32_e32 v46, 16, v164
	v_and_b32_e32 v47, 0xffff0000, v164
	v_lshlrev_b32_e32 v56, 16, v165
	v_and_b32_e32 v57, 0xffff0000, v165
	v_pk_mul_f32 v[42:43], v[42:43], v[54:55] op_sel_hi:[1,0]
	v_pk_mul_f32 v[40:41], v[40:41], v[54:55] op_sel_hi:[1,0]
	v_pk_fma_f32 v[42:43], v[130:131], v[42:43], v[56:57]
	v_pk_fma_f32 v[40:41], v[128:129], v[40:41], v[46:47]
	v_mul_f32_e32 v47, v43, v43
	v_mul_f32_e32 v46, v41, v41
	v_fmac_f32_e32 v46, v40, v40
	v_fmac_f32_e32 v47, v42, v42
	v_add_f32_e32 v46, v46, v47
	v_add_f32_e32 v53, v46, v53
	v_lshlrev_b32_e32 v46, 16, v166
	v_and_b32_e32 v47, 0xffff0000, v166
	v_lshlrev_b32_e32 v56, 16, v167
	v_and_b32_e32 v57, 0xffff0000, v167
	v_pk_mul_f32 v[38:39], v[38:39], v[54:55] op_sel_hi:[1,0]
	v_pk_mul_f32 v[36:37], v[36:37], v[54:55] op_sel_hi:[1,0]
	v_pk_fma_f32 v[54:55], v[126:127], v[38:39], v[56:57]
	v_pk_fma_f32 v[46:47], v[124:125], v[36:37], v[46:47]
	v_mul_f32_e32 v37, v55, v55
	v_mul_f32_e32 v36, v47, v47
	v_fmac_f32_e32 v36, v46, v46
	v_fmac_f32_e32 v37, v54, v54
	v_add_f32_e32 v36, v36, v37
	v_add_f32_e32 v39, v36, v53
	v_mov_b32_e32 v53, v39
	s_nop 1
	v_permlane16_swap_b32_e32 v39, v53
	v_lshl_add_u64 v[36:37], s[24:25], 0, v[44:45]
	v_lshl_add_u64 v[44:45], v[226:227], 1, v[36:37]
	global_store_dwordx4 v[44:45], v[48:51], off
	v_cvt_pk_bf16_f32 v38, v40, v41
	s_waitcnt lgkmcnt(0)
	v_add_f32_e32 v36, v39, v53
	v_mov_b32_e32 v37, v36
	s_nop 1
	v_permlane32_swap_b32_e32 v36, v37
	v_cvt_pk_bf16_f32 v39, v42, v43
	v_cvt_pk_bf16_f32 v40, v46, v47
	v_cvt_pk_bf16_f32 v41, v54, v55
	global_store_dwordx4 v[44:45], v[38:41], off offset:256
	s_and_saveexec_b64 s[56:57], s[38:39]
	s_cbranch_execz .LBB0_996
	v_lshl_add_u32 v38, v52, 4, s66
	s_waitcnt lgkmcnt(0)
	v_add_f32_e32 v36, v36, v37
	ds_write_b32 v38, v36
.LBB0_996:
	s_or_b64 exec, exec, s[56:57]
	ds_read_b32 v38, v213 offset:640
	v_lshlrev_b32_e32 v44, 16, v161
	v_and_b32_e32 v45, 0xffff0000, v161
	v_lshlrev_b32_e32 v42, 16, v160
	v_and_b32_e32 v43, 0xffff0000, v160
	s_waitcnt lgkmcnt(0)
	v_pk_mul_f32 v[34:35], v[34:35], v[38:39] op_sel_hi:[1,0]
	v_pk_mul_f32 v[32:33], v[32:33], v[38:39] op_sel_hi:[1,0]
	v_pk_fma_f32 v[34:35], v[146:147], v[34:35], v[44:45]
	v_pk_fma_f32 v[32:33], v[144:145], v[32:33], v[42:43]
	v_mul_f32_e32 v39, v35, v35
	v_mul_f32_e32 v37, v33, v33
	v_fmac_f32_e32 v39, v34, v34
	v_fmac_f32_e32 v37, v32, v32
	v_cvt_pk_bf16_f32 v32, v32, v33
	v_cvt_pk_bf16_f32 v33, v34, v35
	v_lshlrev_b32_e32 v34, 16, v162
	v_and_b32_e32 v35, 0xffff0000, v162
	v_lshlrev_b32_e32 v42, 16, v163
	v_and_b32_e32 v43, 0xffff0000, v163
	v_pk_mul_f32 v[30:31], v[30:31], v[38:39] op_sel_hi:[1,0]
	v_pk_mul_f32 v[28:29], v[28:29], v[38:39] op_sel_hi:[1,0]
	v_pk_fma_f32 v[30:31], v[138:139], v[30:31], v[42:43]
	v_pk_fma_f32 v[28:29], v[136:137], v[28:29], v[34:35]
	v_add_u32_e32 v36, 0xa0, v212
	v_mul_f32_e32 v34, v29, v29
	v_mul_f32_e32 v35, v31, v31
	v_add_u32_e32 v40, v36, v245
	v_fmac_f32_e32 v34, v28, v28
	v_fmac_f32_e32 v35, v30, v30
	v_ashrrev_i32_e32 v41, 31, v40
	v_add_f32_e32 v37, v37, v39
	v_add_f32_e32 v34, v34, v35
	v_add_f32_e32 v37, v37, v34
	v_cvt_pk_bf16_f32 v34, v28, v29
	v_cvt_pk_bf16_f32 v35, v30, v31
	v_lshlrev_b64 v[28:29], 12, v[40:41]
	v_lshlrev_b32_e32 v30, 16, v156
	v_and_b32_e32 v31, 0xffff0000, v156
	v_lshlrev_b32_e32 v40, 16, v157
	v_and_b32_e32 v41, 0xffff0000, v157
	v_pk_mul_f32 v[26:27], v[26:27], v[38:39] op_sel_hi:[1,0]
	v_pk_mul_f32 v[24:25], v[24:25], v[38:39] op_sel_hi:[1,0]
	v_pk_fma_f32 v[26:27], v[130:131], v[26:27], v[40:41]
	v_pk_fma_f32 v[24:25], v[128:129], v[24:25], v[30:31]
	v_mul_f32_e32 v31, v27, v27
	v_mul_f32_e32 v30, v25, v25
	v_fmac_f32_e32 v30, v24, v24
	v_fmac_f32_e32 v31, v26, v26
	v_add_f32_e32 v30, v30, v31
	v_add_f32_e32 v37, v30, v37
	v_lshlrev_b32_e32 v30, 16, v158
	v_and_b32_e32 v31, 0xffff0000, v158
	v_lshlrev_b32_e32 v40, 16, v159
	v_and_b32_e32 v41, 0xffff0000, v159
	v_pk_mul_f32 v[22:23], v[22:23], v[38:39] op_sel_hi:[1,0]
	v_pk_mul_f32 v[20:21], v[20:21], v[38:39] op_sel_hi:[1,0]
	v_pk_fma_f32 v[38:39], v[126:127], v[22:23], v[40:41]
	v_pk_fma_f32 v[30:31], v[124:125], v[20:21], v[30:31]
	v_mul_f32_e32 v21, v39, v39
	v_mul_f32_e32 v20, v31, v31
	v_fmac_f32_e32 v20, v30, v30
	v_fmac_f32_e32 v21, v38, v38
	v_add_f32_e32 v20, v20, v21
	v_add_f32_e32 v23, v20, v37
	v_mov_b32_e32 v37, v23
	s_nop 1
	v_permlane16_swap_b32_e32 v23, v37
	v_lshl_add_u64 v[20:21], s[24:25], 0, v[28:29]
	v_lshl_add_u64 v[28:29], v[226:227], 1, v[20:21]
	global_store_dwordx4 v[28:29], v[32:35], off
	v_cvt_pk_bf16_f32 v22, v24, v25
	s_waitcnt lgkmcnt(0)
	v_add_f32_e32 v20, v23, v37
	v_mov_b32_e32 v21, v20
	s_nop 1
	v_permlane32_swap_b32_e32 v20, v21
	v_cvt_pk_bf16_f32 v23, v26, v27
	v_cvt_pk_bf16_f32 v24, v30, v31
	v_cvt_pk_bf16_f32 v25, v38, v39
	global_store_dwordx4 v[28:29], v[22:25], off offset:256
	s_and_saveexec_b64 s[56:57], s[38:39]
	s_cbranch_execz .LBB0_998
	v_lshl_add_u32 v22, v36, 4, s66
	s_waitcnt lgkmcnt(0)
	v_add_f32_e32 v20, v20, v21
	ds_write_b32 v22, v20
.LBB0_998:
	s_or_b64 exec, exec, s[56:57]
	ds_read_b32 v22, v213 offset:704
	v_lshlrev_b32_e32 v28, 16, v153
	v_and_b32_e32 v29, 0xffff0000, v153
	v_lshlrev_b32_e32 v26, 16, v152
	v_and_b32_e32 v27, 0xffff0000, v152
	s_waitcnt lgkmcnt(0)
	v_pk_mul_f32 v[18:19], v[18:19], v[22:23] op_sel_hi:[1,0]
	v_pk_mul_f32 v[16:17], v[16:17], v[22:23] op_sel_hi:[1,0]
	v_pk_fma_f32 v[18:19], v[146:147], v[18:19], v[28:29]
	v_pk_fma_f32 v[16:17], v[144:145], v[16:17], v[26:27]
	v_mul_f32_e32 v23, v19, v19
	v_mul_f32_e32 v21, v17, v17
	v_fmac_f32_e32 v23, v18, v18
	v_fmac_f32_e32 v21, v16, v16
	v_cvt_pk_bf16_f32 v16, v16, v17
	v_cvt_pk_bf16_f32 v17, v18, v19
	v_lshlrev_b32_e32 v18, 16, v154
	v_and_b32_e32 v19, 0xffff0000, v154
	v_lshlrev_b32_e32 v26, 16, v155
	v_and_b32_e32 v27, 0xffff0000, v155
	v_pk_mul_f32 v[14:15], v[14:15], v[22:23] op_sel_hi:[1,0]
	v_pk_mul_f32 v[12:13], v[12:13], v[22:23] op_sel_hi:[1,0]
	v_pk_fma_f32 v[14:15], v[138:139], v[14:15], v[26:27]
	v_pk_fma_f32 v[12:13], v[136:137], v[12:13], v[18:19]
	v_add_u32_e32 v20, 0xb0, v212
	v_mul_f32_e32 v18, v13, v13
	v_mul_f32_e32 v19, v15, v15
	v_add_u32_e32 v24, v20, v245
	v_fmac_f32_e32 v18, v12, v12
	v_fmac_f32_e32 v19, v14, v14
	v_ashrrev_i32_e32 v25, 31, v24
	v_add_f32_e32 v21, v21, v23
	v_add_f32_e32 v18, v18, v19
	v_add_f32_e32 v21, v21, v18
	v_cvt_pk_bf16_f32 v18, v12, v13
	v_cvt_pk_bf16_f32 v19, v14, v15
	v_lshlrev_b64 v[12:13], 12, v[24:25]
	v_lshlrev_b32_e32 v14, 16, v148
	v_and_b32_e32 v15, 0xffff0000, v148
	v_lshlrev_b32_e32 v24, 16, v149
	v_and_b32_e32 v25, 0xffff0000, v149
	v_pk_mul_f32 v[10:11], v[10:11], v[22:23] op_sel_hi:[1,0]
	v_pk_mul_f32 v[8:9], v[8:9], v[22:23] op_sel_hi:[1,0]
	v_pk_fma_f32 v[10:11], v[130:131], v[10:11], v[24:25]
	v_pk_fma_f32 v[8:9], v[128:129], v[8:9], v[14:15]
	v_mul_f32_e32 v15, v11, v11
	v_mul_f32_e32 v14, v9, v9
	v_fmac_f32_e32 v14, v8, v8
	v_fmac_f32_e32 v15, v10, v10
	v_add_f32_e32 v14, v14, v15
	v_add_f32_e32 v21, v14, v21
	v_lshlrev_b32_e32 v14, 16, v150
	v_and_b32_e32 v15, 0xffff0000, v150
	v_lshlrev_b32_e32 v24, 16, v151
	v_and_b32_e32 v25, 0xffff0000, v151
	v_pk_mul_f32 v[6:7], v[6:7], v[22:23] op_sel_hi:[1,0]
	v_pk_mul_f32 v[4:5], v[4:5], v[22:23] op_sel_hi:[1,0]
	v_pk_fma_f32 v[22:23], v[126:127], v[6:7], v[24:25]
	v_pk_fma_f32 v[14:15], v[124:125], v[4:5], v[14:15]
	v_mul_f32_e32 v5, v23, v23
	v_mul_f32_e32 v4, v15, v15
	v_fmac_f32_e32 v4, v14, v14
	v_fmac_f32_e32 v5, v22, v22
	v_add_f32_e32 v4, v4, v5
	v_add_f32_e32 v7, v4, v21
	v_mov_b32_e32 v21, v7
	s_nop 1
	v_permlane16_swap_b32_e32 v7, v21
	v_lshl_add_u64 v[4:5], s[24:25], 0, v[12:13]
	v_lshl_add_u64 v[12:13], v[226:227], 1, v[4:5]
	global_store_dwordx4 v[12:13], v[16:19], off
	v_cvt_pk_bf16_f32 v6, v8, v9
	s_waitcnt lgkmcnt(0)
	v_add_f32_e32 v4, v7, v21
	v_mov_b32_e32 v5, v4
	s_nop 1
	v_permlane32_swap_b32_e32 v4, v5
	v_cvt_pk_bf16_f32 v7, v10, v11
	v_cvt_pk_bf16_f32 v8, v14, v15
	v_cvt_pk_bf16_f32 v9, v22, v23
	global_store_dwordx4 v[12:13], v[6:9], off offset:256
	s_and_saveexec_b64 s[56:57], s[38:39]
	s_cbranch_execz .LBB0_1000
	v_lshl_add_u32 v6, v20, 4, s66
	s_waitcnt lgkmcnt(0)
	v_add_f32_e32 v4, v4, v5
	ds_write_b32 v6, v4

.LBB0_1133:
	s_add_u32 s5, s40, 0x100
	s_addc_u32 s6, s41, 0
	s_mov_b32 s7, -2
	s_waitcnt lgkmcnt(0)
	s_add_u32 s40, s38, 0x100
	s_addc_u32 s41, s39, 0
	s_add_i32 s8, 0, 0x10000
	s_cmpk_eq_i32 s7, 0x54
	s_cselect_b32 s45, s61, s41
	s_cselect_b32 s44, s60, s40
	s_cselect_b32 s43, s63, s6
	s_cselect_b32 s42, s62, s5
	s_add_i32 s10, 0, 0x14000
	v_add_u32_e32 v112, s8, v242
	v_add_u32_e32 v148, s10, v242
	ds_read_b128 v[92:95], v112
	ds_read_b128 v[100:103], v112 offset:1024
	ds_read_b128 v[108:111], v112 offset:2048
	ds_read_b128 v[112:115], v112 offset:3072
	ds_read_b128 v[116:119], v148
	ds_read_b128 v[128:131], v148 offset:1024
	ds_read_b128 v[140:143], v148 offset:2048
	ds_read_b128 v[148:151], v148 offset:3072
	v_lshl_add_u64 v[196:197], s[38:39], 0, v[222:223]
	s_add_i32 m0, s83, 0xc000
	ds_read_b128 v[160:163], v245
	ds_read_b128 v[168:171], v245 offset:1024
	ds_read_b128 v[172:175], v245 offset:2048
	ds_read_b128 v[176:179], v245 offset:3072
	ds_read_b128 v[180:183], v245 offset:4096
	ds_read_b128 v[184:187], v245 offset:5120
	ds_read_b128 v[188:191], v245 offset:6144
	ds_read_b128 v[192:195], v245 offset:7168
	global_load_lds_dwordx4 v[196:197], off
	v_lshl_add_u64 v[196:197], s[38:39], 0, v[220:221]
	s_add_i32 m0, s83, 0xe000
	s_nop 0
	global_load_lds_dwordx4 v[196:197], off
	s_waitcnt vmcnt(8)
	s_waitcnt lgkmcnt(0)
	s_barrier
	s_setprio 1
	s_waitcnt lgkmcnt(0)
	v_mfma_f32_16x16x32_bf16 v[164:167], v[92:95], v[160:163], 0
	v_mfma_f32_16x16x32_bf16 v[156:159], v[108:111], v[160:163], 0
	v_mfma_f32_16x16x32_bf16 v[136:139], v[92:95], v[172:175], 0
	v_mfma_f32_16x16x32_bf16 v[132:135], v[108:111], v[172:175], 0
	v_mfma_f32_16x16x32_bf16 v[104:107], v[92:95], v[180:183], 0
	v_mfma_f32_16x16x32_bf16 v[96:99], v[108:111], v[180:183], 0
	v_mfma_f32_16x16x32_bf16 v[80:83], v[92:95], v[188:191], 0
	v_mfma_f32_16x16x32_bf16 v[76:79], v[108:111], v[188:191], 0
	v_mfma_f32_16x16x32_bf16 v[164:167], v[100:103], v[168:171], v[164:167]
	v_mfma_f32_16x16x32_bf16 v[156:159], v[112:115], v[168:171], v[156:159]
	v_mfma_f32_16x16x32_bf16 v[136:139], v[100:103], v[176:179], v[136:139]
	v_mfma_f32_16x16x32_bf16 v[132:135], v[112:115], v[176:179], v[132:135]
	v_mfma_f32_16x16x32_bf16 v[104:107], v[100:103], v[184:187], v[104:107]
	v_mfma_f32_16x16x32_bf16 v[96:99], v[112:115], v[184:187], v[96:99]
	v_mfma_f32_16x16x32_bf16 v[80:83], v[100:103], v[192:195], v[80:83]
	v_mfma_f32_16x16x32_bf16 v[76:79], v[112:115], v[192:195], v[76:79]
	s_setprio 0
	s_setprio 1
	v_mfma_f32_16x16x32_bf16 v[152:155], v[116:119], v[160:163], 0
	v_mfma_f32_16x16x32_bf16 v[144:147], v[140:143], v[160:163], 0
	v_mfma_f32_16x16x32_bf16 v[124:127], v[116:119], v[172:175], 0
	v_mfma_f32_16x16x32_bf16 v[120:123], v[140:143], v[172:175], 0
	v_mfma_f32_16x16x32_bf16 v[88:91], v[116:119], v[180:183], 0
	v_mfma_f32_16x16x32_bf16 v[84:87], v[140:143], v[180:183], 0
	v_mfma_f32_16x16x32_bf16 v[72:75], v[116:119], v[188:191], 0
	v_mfma_f32_16x16x32_bf16 v[68:71], v[140:143], v[188:191], 0
	v_mfma_f32_16x16x32_bf16 v[152:155], v[128:131], v[168:171], v[152:155]
	v_mfma_f32_16x16x32_bf16 v[144:147], v[148:151], v[168:171], v[144:147]
	v_mfma_f32_16x16x32_bf16 v[124:127], v[128:131], v[176:179], v[124:127]
	v_mfma_f32_16x16x32_bf16 v[120:123], v[148:151], v[176:179], v[120:123]
	v_mfma_f32_16x16x32_bf16 v[88:91], v[128:131], v[184:187], v[88:91]
	v_mfma_f32_16x16x32_bf16 v[84:87], v[148:151], v[184:187], v[84:87]
	v_mfma_f32_16x16x32_bf16 v[72:75], v[128:131], v[192:195], v[72:75]
	v_mfma_f32_16x16x32_bf16 v[68:71], v[148:151], v[192:195], v[68:71]
	s_setprio 0
	s_barrier
	s_add_i32 s8, s8, s82
	v_lshl_add_u64 v[196:197], s[42:43], 0, v[2:3]
	s_mov_b32 m0, s8
	ds_read_b128 v[160:163], v245 offset:16384
	ds_read_b128 v[168:171], v245 offset:17408
	ds_read_b128 v[172:175], v245 offset:18432
	ds_read_b128 v[176:179], v245 offset:19456
	ds_read_b128 v[180:183], v245 offset:20480
	ds_read_b128 v[184:187], v245 offset:21504
	ds_read_b128 v[188:191], v245 offset:22528
	ds_read_b128 v[192:195], v245 offset:23552
	global_load_lds_dwordx4 v[196:197], off
	s_add_i32 m0, s8, 0x2000
	s_add_u32 s8, s42, 0x160000
	v_lshl_add_u64 v[198:199], s[42:43], 0, v[218:219]
	s_addc_u32 s9, s43, 0
	s_add_i32 s10, s10, s82
	global_load_lds_dwordx4 v[198:199], off
	v_lshl_add_u64 v[200:201], s[8:9], 0, v[2:3]
	s_mov_b32 m0, s10
	v_lshl_add_u64 v[202:203], s[44:45], 0, v[216:217]
	global_load_lds_dwordx4 v[200:201], off
	v_lshl_add_u64 v[200:201], s[8:9], 0, v[218:219]
	s_add_i32 m0, s10, 0x2000
	s_nop 0
	global_load_lds_dwordx4 v[200:201], off
	v_lshl_add_u64 v[200:201], s[44:45], 0, v[0:1]
	s_mov_b32 m0, s83
	s_nop 0
	global_load_lds_dwordx4 v[200:201], off
	s_mov_b32 m0, s84
	s_nop 0
	global_load_lds_dwordx4 v[202:203], off
	s_waitcnt vmcnt(8)
	s_waitcnt lgkmcnt(0)
	s_barrier
	s_setprio 1
	s_waitcnt lgkmcnt(0)
	v_mfma_f32_16x16x32_bf16 v[64:67], v[92:95], v[160:163], 0
	v_mfma_f32_16x16x32_bf16 v[60:63], v[108:111], v[160:163], 0
	v_mfma_f32_16x16x32_bf16 v[48:51], v[92:95], v[172:175], 0
	v_mfma_f32_16x16x32_bf16 v[44:47], v[108:111], v[172:175], 0
	v_mfma_f32_16x16x32_bf16 v[32:35], v[92:95], v[180:183], 0
	v_mfma_f32_16x16x32_bf16 v[28:31], v[108:111], v[180:183], 0
	v_mfma_f32_16x16x32_bf16 v[16:19], v[92:95], v[188:191], 0
	v_mfma_f32_16x16x32_bf16 v[12:15], v[108:111], v[188:191], 0
	v_mfma_f32_16x16x32_bf16 v[64:67], v[100:103], v[168:171], v[64:67]
	v_mfma_f32_16x16x32_bf16 v[60:63], v[112:115], v[168:171], v[60:63]
	v_mfma_f32_16x16x32_bf16 v[48:51], v[100:103], v[176:179], v[48:51]
	v_mfma_f32_16x16x32_bf16 v[44:47], v[112:115], v[176:179], v[44:47]
	v_mfma_f32_16x16x32_bf16 v[32:35], v[100:103], v[184:187], v[32:35]
	v_mfma_f32_16x16x32_bf16 v[28:31], v[112:115], v[184:187], v[28:31]
	v_mfma_f32_16x16x32_bf16 v[16:19], v[100:103], v[192:195], v[16:19]
	v_mfma_f32_16x16x32_bf16 v[12:15], v[112:115], v[192:195], v[12:15]
	s_setprio 0
	s_setprio 1
	v_mfma_f32_16x16x32_bf16 v[56:59], v[116:119], v[160:163], 0
	v_mfma_f32_16x16x32_bf16 v[52:55], v[140:143], v[160:163], 0
	v_mfma_f32_16x16x32_bf16 v[40:43], v[116:119], v[172:175], 0
	v_mfma_f32_16x16x32_bf16 v[36:39], v[140:143], v[172:175], 0
	v_mfma_f32_16x16x32_bf16 v[24:27], v[116:119], v[180:183], 0
	v_mfma_f32_16x16x32_bf16 v[20:23], v[140:143], v[180:183], 0
	v_mfma_f32_16x16x32_bf16 v[8:11], v[116:119], v[188:191], 0
	v_mfma_f32_16x16x32_bf16 v[4:7], v[140:143], v[188:191], 0
	v_mfma_f32_16x16x32_bf16 v[56:59], v[128:131], v[168:171], v[56:59]
	v_mfma_f32_16x16x32_bf16 v[52:55], v[148:151], v[168:171], v[52:55]
	v_mfma_f32_16x16x32_bf16 v[40:43], v[128:131], v[176:179], v[40:43]
	v_mfma_f32_16x16x32_bf16 v[36:39], v[148:151], v[176:179], v[36:39]
	v_mfma_f32_16x16x32_bf16 v[24:27], v[128:131], v[184:187], v[24:27]
	v_mfma_f32_16x16x32_bf16 v[20:23], v[148:151], v[184:187], v[20:23]
	v_mfma_f32_16x16x32_bf16 v[8:11], v[128:131], v[192:195], v[8:11]
	v_mfma_f32_16x16x32_bf16 v[4:7], v[148:151], v[192:195], v[4:7]
	s_setprio 0
	s_barrier
	s_add_i32 s10, 0, 0x18000
	s_add_i32 s11, 0, 0x1c000
	v_add_u32_e32 v112, s10, v242
	v_add_u32_e32 v148, s11, v242
	ds_read_b128 v[92:95], v112
	ds_read_b128 v[100:103], v112 offset:1024
	ds_read_b128 v[108:111], v112 offset:2048
	ds_read_b128 v[112:115], v112 offset:3072
	ds_read_b128 v[116:119], v148
	ds_read_b128 v[128:131], v148 offset:1024
	ds_read_b128 v[140:143], v148 offset:2048
	ds_read_b128 v[148:151], v148 offset:3072
	s_add_u32 s8, s44, 0x160000
	s_addc_u32 s9, s45, 0
	s_mov_b32 m0, s85
	v_lshl_add_u64 v[204:205], s[8:9], 0, v[0:1]
	ds_read_b128 v[160:163], v245 offset:32768
	ds_read_b128 v[168:171], v245 offset:33792
	ds_read_b128 v[172:175], v245 offset:34816
	ds_read_b128 v[176:179], v245 offset:35840
	ds_read_b128 v[180:183], v245 offset:36864
	ds_read_b128 v[184:187], v245 offset:37888
	ds_read_b128 v[188:191], v245 offset:38912
	ds_read_b128 v[192:195], v245 offset:39936
	global_load_lds_dwordx4 v[204:205], off
	v_lshl_add_u64 v[204:205], s[8:9], 0, v[216:217]
	s_mov_b32 m0, s87
	s_nop 0
	global_load_lds_dwordx4 v[204:205], off
	s_waitcnt vmcnt(8)
	s_waitcnt lgkmcnt(0)
	s_barrier
	s_setprio 1
	s_waitcnt lgkmcnt(0)
	v_mfma_f32_16x16x32_bf16 v[164:167], v[92:95], v[160:163], v[164:167]
	v_mfma_f32_16x16x32_bf16 v[156:159], v[108:111], v[160:163], v[156:159]
	v_mfma_f32_16x16x32_bf16 v[136:139], v[92:95], v[172:175], v[136:139]
	v_mfma_f32_16x16x32_bf16 v[132:135], v[108:111], v[172:175], v[132:135]
	v_mfma_f32_16x16x32_bf16 v[104:107], v[92:95], v[180:183], v[104:107]
	v_mfma_f32_16x16x32_bf16 v[96:99], v[108:111], v[180:183], v[96:99]
	v_mfma_f32_16x16x32_bf16 v[80:83], v[92:95], v[188:191], v[80:83]
	v_mfma_f32_16x16x32_bf16 v[76:79], v[108:111], v[188:191], v[76:79]
	v_mfma_f32_16x16x32_bf16 v[164:167], v[100:103], v[168:171], v[164:167]
	v_mfma_f32_16x16x32_bf16 v[156:159], v[112:115], v[168:171], v[156:159]
	v_mfma_f32_16x16x32_bf16 v[136:139], v[100:103], v[176:179], v[136:139]
	v_mfma_f32_16x16x32_bf16 v[132:135], v[112:115], v[176:179], v[132:135]
	v_mfma_f32_16x16x32_bf16 v[104:107], v[100:103], v[184:187], v[104:107]
	v_mfma_f32_16x16x32_bf16 v[96:99], v[112:115], v[184:187], v[96:99]
	v_mfma_f32_16x16x32_bf16 v[80:83], v[100:103], v[192:195], v[80:83]
	v_mfma_f32_16x16x32_bf16 v[76:79], v[112:115], v[192:195], v[76:79]
	s_setprio 0
	s_setprio 1
	v_mfma_f32_16x16x32_bf16 v[152:155], v[116:119], v[160:163], v[152:155]
	v_mfma_f32_16x16x32_bf16 v[144:147], v[140:143], v[160:163], v[144:147]
	v_mfma_f32_16x16x32_bf16 v[124:127], v[116:119], v[172:175], v[124:127]
	v_mfma_f32_16x16x32_bf16 v[120:123], v[140:143], v[172:175], v[120:123]
	v_mfma_f32_16x16x32_bf16 v[88:91], v[116:119], v[180:183], v[88:91]
	v_mfma_f32_16x16x32_bf16 v[84:87], v[140:143], v[180:183], v[84:87]
	v_mfma_f32_16x16x32_bf16 v[72:75], v[116:119], v[188:191], v[72:75]
	v_mfma_f32_16x16x32_bf16 v[68:71], v[140:143], v[188:191], v[68:71]
	v_mfma_f32_16x16x32_bf16 v[152:155], v[128:131], v[168:171], v[152:155]
	v_mfma_f32_16x16x32_bf16 v[144:147], v[148:151], v[168:171], v[144:147]
	v_mfma_f32_16x16x32_bf16 v[124:127], v[128:131], v[176:179], v[124:127]
	v_mfma_f32_16x16x32_bf16 v[120:123], v[148:151], v[176:179], v[120:123]
	v_mfma_f32_16x16x32_bf16 v[88:91], v[128:131], v[184:187], v[88:91]
	v_mfma_f32_16x16x32_bf16 v[84:87], v[148:151], v[184:187], v[84:87]
	v_mfma_f32_16x16x32_bf16 v[72:75], v[128:131], v[192:195], v[72:75]
	v_mfma_f32_16x16x32_bf16 v[68:71], v[148:151], v[192:195], v[68:71]
	s_setprio 0
	s_barrier
	s_add_i32 s8, s10, s82
	v_lshl_add_u64 v[196:197], v[196:197], 0, s[68:69]
	s_mov_b32 m0, s8
	ds_read_b128 v[160:163], v245 offset:49152
	ds_read_b128 v[168:171], v245 offset:50176
	ds_read_b128 v[172:175], v245 offset:51200
	ds_read_b128 v[176:179], v245 offset:52224
	ds_read_b128 v[180:183], v245 offset:53248
	ds_read_b128 v[184:187], v245 offset:54272
	ds_read_b128 v[188:191], v245 offset:55296
	ds_read_b128 v[192:195], v245 offset:56320
	global_load_lds_dwordx4 v[196:197], off
	s_add_i32 m0, s8, 0x2000
	s_add_u32 s8, s42, 0x160080
	v_lshl_add_u64 v[196:197], v[198:199], 0, s[68:69]
	s_addc_u32 s9, s43, 0
	s_add_i32 s10, s11, s82
	global_load_lds_dwordx4 v[196:197], off
	v_lshl_add_u64 v[196:197], s[8:9], 0, v[2:3]
	s_mov_b32 m0, s10
	s_nop 0
	global_load_lds_dwordx4 v[196:197], off
	v_lshl_add_u64 v[196:197], s[8:9], 0, v[218:219]
	s_add_i32 m0, s10, 0x2000
	s_nop 0
	global_load_lds_dwordx4 v[196:197], off
	v_lshl_add_u64 v[196:197], v[200:201], 0, s[68:69]
	s_mov_b32 m0, s72
	s_nop 0
	global_load_lds_dwordx4 v[196:197], off
	v_lshl_add_u64 v[196:197], v[202:203], 0, s[68:69]
	s_mov_b32 m0, s88
	s_nop 0
	global_load_lds_dwordx4 v[196:197], off
	s_waitcnt vmcnt(8)
	s_waitcnt lgkmcnt(0)
	s_barrier
	s_setprio 1
	s_waitcnt lgkmcnt(0)
	v_mfma_f32_16x16x32_bf16 v[64:67], v[92:95], v[160:163], v[64:67]
	v_mfma_f32_16x16x32_bf16 v[60:63], v[108:111], v[160:163], v[60:63]
	v_mfma_f32_16x16x32_bf16 v[48:51], v[92:95], v[172:175], v[48:51]
	v_mfma_f32_16x16x32_bf16 v[44:47], v[108:111], v[172:175], v[44:47]
	v_mfma_f32_16x16x32_bf16 v[32:35], v[92:95], v[180:183], v[32:35]
	v_mfma_f32_16x16x32_bf16 v[28:31], v[108:111], v[180:183], v[28:31]
	v_mfma_f32_16x16x32_bf16 v[16:19], v[92:95], v[188:191], v[16:19]
	v_mfma_f32_16x16x32_bf16 v[12:15], v[108:111], v[188:191], v[12:15]
	v_mfma_f32_16x16x32_bf16 v[64:67], v[100:103], v[168:171], v[64:67]
	v_mfma_f32_16x16x32_bf16 v[60:63], v[112:115], v[168:171], v[60:63]
	v_mfma_f32_16x16x32_bf16 v[48:51], v[100:103], v[176:179], v[48:51]
	v_mfma_f32_16x16x32_bf16 v[44:47], v[112:115], v[176:179], v[44:47]
	v_mfma_f32_16x16x32_bf16 v[32:35], v[100:103], v[184:187], v[32:35]
	v_mfma_f32_16x16x32_bf16 v[28:31], v[112:115], v[184:187], v[28:31]
	v_mfma_f32_16x16x32_bf16 v[16:19], v[100:103], v[192:195], v[16:19]
	v_mfma_f32_16x16x32_bf16 v[12:15], v[112:115], v[192:195], v[12:15]
	s_setprio 0
	s_setprio 1
	v_mfma_f32_16x16x32_bf16 v[56:59], v[116:119], v[160:163], v[56:59]
	v_mfma_f32_16x16x32_bf16 v[52:55], v[140:143], v[160:163], v[52:55]
	v_mfma_f32_16x16x32_bf16 v[40:43], v[116:119], v[172:175], v[40:43]
	v_mfma_f32_16x16x32_bf16 v[36:39], v[140:143], v[172:175], v[36:39]
	v_mfma_f32_16x16x32_bf16 v[24:27], v[116:119], v[180:183], v[24:27]
	v_mfma_f32_16x16x32_bf16 v[20:23], v[140:143], v[180:183], v[20:23]
	v_mfma_f32_16x16x32_bf16 v[8:11], v[116:119], v[188:191], v[8:11]
	v_mfma_f32_16x16x32_bf16 v[4:7], v[140:143], v[188:191], v[4:7]
	v_mfma_f32_16x16x32_bf16 v[56:59], v[128:131], v[168:171], v[56:59]
	v_mfma_f32_16x16x32_bf16 v[52:55], v[148:151], v[168:171], v[52:55]
	v_mfma_f32_16x16x32_bf16 v[40:43], v[128:131], v[176:179], v[40:43]
	v_mfma_f32_16x16x32_bf16 v[36:39], v[148:151], v[176:179], v[36:39]
	v_mfma_f32_16x16x32_bf16 v[24:27], v[128:131], v[184:187], v[24:27]
	v_mfma_f32_16x16x32_bf16 v[20:23], v[148:151], v[184:187], v[20:23]
	v_mfma_f32_16x16x32_bf16 v[8:11], v[128:131], v[192:195], v[8:11]
	v_mfma_f32_16x16x32_bf16 v[4:7], v[148:151], v[192:195], v[4:7]
	s_setprio 0
	s_barrier
	s_add_i32 s7, s7, 2
	s_add_u32 s5, s5, 0x100
	s_addc_u32 s6, s6, 0
	s_cmpk_gt_u32 s7, 0x55
	s_mov_b64 s[38:39], s[40:41]

.LBB0_1137:
	v_mul_f32_e32 v92, v165, v165
	v_mul_f32_e32 v93, v167, v167
	v_fmac_f32_e32 v92, v164, v164
	v_fmac_f32_e32 v93, v166, v166
	v_add_f32_e32 v92, v92, v93
	v_mul_f32_e32 v93, v157, v157
	v_mul_f32_e32 v94, v159, v159
	v_fmac_f32_e32 v93, v156, v156
	v_fmac_f32_e32 v94, v158, v158
	v_add_f32_e32 v93, v93, v94
	v_add_f32_e32 v92, v92, v93
	v_mul_f32_e32 v93, v153, v153
	v_mul_f32_e32 v94, v155, v155
	v_fmac_f32_e32 v93, v152, v152
	v_fmac_f32_e32 v94, v154, v154
	v_add_f32_e32 v93, v93, v94
	v_add_f32_e32 v92, v92, v93
	v_mul_f32_e32 v93, v145, v145
	v_mul_f32_e32 v94, v147, v147
	v_fmac_f32_e32 v93, v144, v144
	v_fmac_f32_e32 v94, v146, v146
	v_add_f32_e32 v93, v93, v94
	v_add_f32_e32 v92, v92, v93
	v_mov_b32_e32 v93, v92
	s_nop 1
	v_permlane16_swap_b32_e32 v92, v93
	v_mov_b32_e32 v248, v234
	s_waitcnt lgkmcnt(0)
	v_add_f32_e32 v93, v92, v93
	v_mov_b32_e32 v94, v93
	s_nop 1
	v_permlane32_swap_b32_e32 v93, v94
	v_cmp_gt_u32_e64 s[38:39], 16, v248
	v_lshl_add_u32 v92, v248, 4, s90
	s_and_saveexec_b64 s[40:41], s[38:39]
	s_cbranch_execz .LBB0_1139
	s_waitcnt lgkmcnt(0)
	v_add_f32_e32 v93, v93, v94
	ds_write_b32 v92, v93
.LBB0_1139:
	s_or_b64 exec, exec, s[40:41]
	v_mul_f32_e32 v93, v137, v137
	s_waitcnt lgkmcnt(0)
	v_mul_f32_e32 v94, v139, v139
	v_fmac_f32_e32 v93, v136, v136
	v_fmac_f32_e32 v94, v138, v138
	v_add_f32_e32 v93, v93, v94
	v_mul_f32_e32 v94, v133, v133
	v_mul_f32_e32 v95, v135, v135
	v_fmac_f32_e32 v94, v132, v132
	v_fmac_f32_e32 v95, v134, v134
	v_add_f32_e32 v94, v94, v95
	v_add_f32_e32 v93, v93, v94
	v_mul_f32_e32 v94, v125, v125
	v_mul_f32_e32 v95, v127, v127
	v_fmac_f32_e32 v94, v124, v124
	v_fmac_f32_e32 v95, v126, v126
	v_add_f32_e32 v94, v94, v95
	v_add_f32_e32 v93, v93, v94
	v_mul_f32_e32 v94, v121, v121
	v_mul_f32_e32 v95, v123, v123
	v_fmac_f32_e32 v94, v120, v120
	v_fmac_f32_e32 v95, v122, v122
	v_add_f32_e32 v94, v94, v95
	v_add_f32_e32 v93, v93, v94
	v_mov_b32_e32 v94, v93
	s_nop 1
	v_permlane16_swap_b32_e32 v93, v94
	s_waitcnt lgkmcnt(0)
	v_add_f32_e32 v93, v93, v94
	v_mov_b32_e32 v94, v93
	s_nop 1
	v_permlane32_swap_b32_e32 v93, v94
	s_and_saveexec_b64 s[40:41], s[38:39]
	s_cbranch_execz .LBB0_1141
	s_waitcnt lgkmcnt(0)
	v_add_f32_e32 v93, v93, v94
	ds_write_b32 v92, v93 offset:256
.LBB0_1141:
	s_or_b64 exec, exec, s[40:41]
	v_mul_f32_e32 v93, v105, v105
	s_waitcnt lgkmcnt(0)
	v_mul_f32_e32 v94, v107, v107
	v_fmac_f32_e32 v93, v104, v104
	v_fmac_f32_e32 v94, v106, v106
	v_add_f32_e32 v93, v93, v94
	v_mul_f32_e32 v94, v97, v97
	v_mul_f32_e32 v95, v99, v99
	v_fmac_f32_e32 v94, v96, v96
	v_fmac_f32_e32 v95, v98, v98
	v_add_f32_e32 v94, v94, v95
	v_add_f32_e32 v93, v93, v94
	v_mul_f32_e32 v94, v89, v89
	v_mul_f32_e32 v95, v91, v91
	v_fmac_f32_e32 v94, v88, v88
	v_fmac_f32_e32 v95, v90, v90
	v_add_f32_e32 v94, v94, v95
	v_add_f32_e32 v93, v93, v94
	v_mul_f32_e32 v94, v85, v85
	v_mul_f32_e32 v95, v87, v87
	v_fmac_f32_e32 v94, v84, v84
	v_fmac_f32_e32 v95, v86, v86
	v_add_f32_e32 v94, v94, v95
	v_add_f32_e32 v93, v93, v94
	v_mov_b32_e32 v94, v93
	s_nop 1
	v_permlane16_swap_b32_e32 v93, v94
	s_waitcnt lgkmcnt(0)
	v_add_f32_e32 v93, v93, v94
	v_mov_b32_e32 v94, v93
	s_nop 1
	v_permlane32_swap_b32_e32 v93, v94
	s_and_saveexec_b64 s[40:41], s[38:39]
	s_cbranch_execz .LBB0_1143
	s_waitcnt lgkmcnt(0)
	v_add_f32_e32 v93, v93, v94
	ds_write_b32 v92, v93 offset:512
.LBB0_1143:
	s_or_b64 exec, exec, s[40:41]
	v_mul_f32_e32 v93, v81, v81
	s_waitcnt lgkmcnt(0)
	v_mul_f32_e32 v94, v83, v83
	v_fmac_f32_e32 v93, v80, v80
	v_fmac_f32_e32 v94, v82, v82
	v_add_f32_e32 v93, v93, v94
	v_mul_f32_e32 v94, v77, v77
	v_mul_f32_e32 v95, v79, v79
	v_fmac_f32_e32 v94, v76, v76
	v_fmac_f32_e32 v95, v78, v78
	v_add_f32_e32 v94, v94, v95
	v_add_f32_e32 v93, v93, v94
	v_mul_f32_e32 v94, v73, v73
	v_mul_f32_e32 v95, v75, v75
	v_fmac_f32_e32 v94, v72, v72
	v_fmac_f32_e32 v95, v74, v74
	v_add_f32_e32 v94, v94, v95
	v_add_f32_e32 v93, v93, v94
	v_mul_f32_e32 v94, v69, v69
	v_mul_f32_e32 v95, v71, v71
	v_fmac_f32_e32 v94, v68, v68
	v_fmac_f32_e32 v95, v70, v70
	v_add_f32_e32 v94, v94, v95
	v_add_f32_e32 v93, v93, v94
	v_mov_b32_e32 v94, v93
	s_nop 1
	v_permlane16_swap_b32_e32 v93, v94
	s_waitcnt lgkmcnt(0)
	v_add_f32_e32 v93, v93, v94
	v_mov_b32_e32 v94, v93
	s_nop 1
	v_permlane32_swap_b32_e32 v93, v94
	s_and_saveexec_b64 s[40:41], s[38:39]
	s_cbranch_execz .LBB0_1145
	s_waitcnt lgkmcnt(0)
	v_add_f32_e32 v93, v93, v94
	ds_write_b32 v92, v93 offset:768
.LBB0_1145:
	s_or_b64 exec, exec, s[40:41]
	v_mul_f32_e32 v93, v65, v65
	s_waitcnt lgkmcnt(0)
	v_mul_f32_e32 v94, v67, v67
	v_fmac_f32_e32 v93, v64, v64
	v_fmac_f32_e32 v94, v66, v66
	v_add_f32_e32 v93, v93, v94
	v_mul_f32_e32 v94, v61, v61
	v_mul_f32_e32 v95, v63, v63
	v_fmac_f32_e32 v94, v60, v60
	v_fmac_f32_e32 v95, v62, v62
	v_add_f32_e32 v94, v94, v95
	v_add_f32_e32 v93, v93, v94
	v_mul_f32_e32 v94, v57, v57
	v_mul_f32_e32 v95, v59, v59
	v_fmac_f32_e32 v94, v56, v56
	v_fmac_f32_e32 v95, v58, v58
	v_add_f32_e32 v94, v94, v95
	v_add_f32_e32 v93, v93, v94
	v_mul_f32_e32 v94, v53, v53
	v_mul_f32_e32 v95, v55, v55
	v_fmac_f32_e32 v94, v52, v52
	v_fmac_f32_e32 v95, v54, v54
	v_add_f32_e32 v94, v94, v95
	v_add_f32_e32 v93, v93, v94
	v_mov_b32_e32 v94, v93
	s_nop 1
	v_permlane16_swap_b32_e32 v93, v94
	s_waitcnt lgkmcnt(0)
	v_add_f32_e32 v93, v93, v94
	v_mov_b32_e32 v94, v93
	s_nop 1
	v_permlane32_swap_b32_e32 v93, v94
	s_and_saveexec_b64 s[40:41], s[38:39]
	s_cbranch_execz .LBB0_1147
	s_waitcnt lgkmcnt(0)
	v_add_f32_e32 v93, v93, v94
	ds_write_b32 v92, v93 offset:2048
.LBB0_1147:
	s_or_b64 exec, exec, s[40:41]
	v_mul_f32_e32 v93, v49, v49
	s_waitcnt lgkmcnt(0)
	v_mul_f32_e32 v94, v51, v51
	v_fmac_f32_e32 v93, v48, v48
	v_fmac_f32_e32 v94, v50, v50
	v_add_f32_e32 v93, v93, v94
	v_mul_f32_e32 v94, v45, v45
	v_mul_f32_e32 v95, v47, v47
	v_fmac_f32_e32 v94, v44, v44
	v_fmac_f32_e32 v95, v46, v46
	v_add_f32_e32 v94, v94, v95
	v_add_f32_e32 v93, v93, v94
	v_mul_f32_e32 v94, v41, v41
	v_mul_f32_e32 v95, v43, v43
	v_fmac_f32_e32 v94, v40, v40
	v_fmac_f32_e32 v95, v42, v42
	v_add_f32_e32 v94, v94, v95
	v_add_f32_e32 v93, v93, v94
	v_mul_f32_e32 v94, v37, v37
	v_mul_f32_e32 v95, v39, v39
	v_fmac_f32_e32 v94, v36, v36
	v_fmac_f32_e32 v95, v38, v38
	v_add_f32_e32 v94, v94, v95
	v_add_f32_e32 v93, v93, v94
	v_mov_b32_e32 v94, v93
	s_nop 1
	v_permlane16_swap_b32_e32 v93, v94
	s_waitcnt lgkmcnt(0)
	v_add_f32_e32 v93, v93, v94
	v_mov_b32_e32 v94, v93
	s_nop 1
	v_permlane32_swap_b32_e32 v93, v94
	s_and_saveexec_b64 s[40:41], s[38:39]
	s_cbranch_execz .LBB0_1149
	s_waitcnt lgkmcnt(0)
	v_add_f32_e32 v93, v93, v94
	ds_write_b32 v92, v93 offset:2304
.LBB0_1149:
	s_or_b64 exec, exec, s[40:41]
	v_mul_f32_e32 v93, v33, v33
	s_waitcnt lgkmcnt(0)
	v_mul_f32_e32 v94, v35, v35
	v_fmac_f32_e32 v93, v32, v32
	v_fmac_f32_e32 v94, v34, v34
	v_add_f32_e32 v93, v93, v94
	v_mul_f32_e32 v94, v29, v29
	v_mul_f32_e32 v95, v31, v31
	v_fmac_f32_e32 v94, v28, v28
	v_fmac_f32_e32 v95, v30, v30
	v_add_f32_e32 v94, v94, v95
	v_add_f32_e32 v93, v93, v94
	v_mul_f32_e32 v94, v25, v25
	v_mul_f32_e32 v95, v27, v27
	v_fmac_f32_e32 v94, v24, v24
	v_fmac_f32_e32 v95, v26, v26
	v_add_f32_e32 v94, v94, v95
	v_add_f32_e32 v93, v93, v94
	v_mul_f32_e32 v94, v21, v21
	v_mul_f32_e32 v95, v23, v23
	v_fmac_f32_e32 v94, v20, v20
	v_fmac_f32_e32 v95, v22, v22
	v_add_f32_e32 v94, v94, v95
	v_add_f32_e32 v93, v93, v94
	v_mov_b32_e32 v94, v93
	s_nop 1
	v_permlane16_swap_b32_e32 v93, v94
	s_waitcnt lgkmcnt(0)
	v_add_f32_e32 v93, v93, v94
	v_mov_b32_e32 v94, v93
	s_nop 1
	v_permlane32_swap_b32_e32 v93, v94
	s_and_saveexec_b64 s[40:41], s[38:39]
	s_cbranch_execz .LBB0_1151
	s_waitcnt lgkmcnt(0)
	v_add_f32_e32 v93, v93, v94
	ds_write_b32 v92, v93 offset:2560
.LBB0_1151:
	s_or_b64 exec, exec, s[40:41]
	v_mul_f32_e32 v93, v17, v17
	s_waitcnt lgkmcnt(0)
	v_mul_f32_e32 v94, v19, v19
	v_fmac_f32_e32 v93, v16, v16
	v_fmac_f32_e32 v94, v18, v18
	v_add_f32_e32 v93, v93, v94
	v_mul_f32_e32 v94, v13, v13
	v_mul_f32_e32 v95, v15, v15
	v_fmac_f32_e32 v94, v12, v12
	v_fmac_f32_e32 v95, v14, v14
	v_add_f32_e32 v94, v94, v95
	v_add_f32_e32 v93, v93, v94
	v_mul_f32_e32 v94, v9, v9
	v_mul_f32_e32 v95, v11, v11
	v_fmac_f32_e32 v94, v8, v8
	v_fmac_f32_e32 v95, v10, v10
	v_add_f32_e32 v94, v94, v95
	v_add_f32_e32 v93, v93, v94
	v_mul_f32_e32 v94, v5, v5
	v_mul_f32_e32 v95, v7, v7
	v_fmac_f32_e32 v94, v4, v4
	v_fmac_f32_e32 v95, v6, v6
	v_add_f32_e32 v94, v94, v95
	v_add_f32_e32 v93, v93, v94
	v_mov_b32_e32 v94, v93
	s_nop 1
	v_permlane16_swap_b32_e32 v93, v94
	s_waitcnt lgkmcnt(0)
	v_add_f32_e32 v93, v93, v94
	v_mov_b32_e32 v94, v93
	s_nop 1
	v_permlane32_swap_b32_e32 v93, v94
	s_and_saveexec_b64 s[40:41], s[38:39]
	s_cbranch_execz .LBB0_1153
	s_waitcnt lgkmcnt(0)
	v_add_f32_e32 v93, v93, v94
	ds_write_b32 v92, v93 offset:2816

.LBB0_1169:
	v_add_f32_e32 v212, v212, v213
	v_add_f32_e32 v213, v214, v215
	v_add_f32_e32 v212, v212, v213
	v_mov_b32_e32 v213, v212
	s_nop 1
	v_permlane32_swap_b32_e32 v212, v213
	s_and_saveexec_b64 s[42:43], s[40:41]
	s_cbranch_execz .LBB0_1171
	s_waitcnt lgkmcnt(0)
	v_add_f32_e32 v212, v212, v213
	v_fmamk_f32 v212, v212, 0x3a000000, v232
	v_rsq_f32_e32 v212, v212
	v_lshl_add_u32 v213, v249, 2, 0
	v_add_u32_e32 v213, 0x21400, v213
	ds_write_b32 v213, v212

.LBB0_1183:
	v_mul_f32_e32 v165, v165, v165
	v_mul_f32_e32 v157, v157, v157
	v_fmac_f32_e32 v165, v164, v164
	v_mul_f32_e32 v164, v167, v167
	v_fmac_f32_e32 v157, v156, v156
	v_mul_f32_e32 v156, v159, v159
	v_mul_f32_e32 v153, v153, v153
	v_fmac_f32_e32 v164, v166, v166
	v_fmac_f32_e32 v156, v158, v158
	v_fmac_f32_e32 v153, v152, v152
	v_mul_f32_e32 v152, v155, v155
	v_mul_f32_e32 v145, v145, v145
	v_add_f32_e32 v164, v165, v164
	v_add_f32_e32 v156, v157, v156
	v_fmac_f32_e32 v152, v154, v154
	v_fmac_f32_e32 v145, v144, v144
	v_mul_f32_e32 v144, v147, v147
	v_add_f32_e32 v156, v164, v156
	v_add_f32_e32 v152, v153, v152
	v_fmac_f32_e32 v144, v146, v146
	v_add_f32_e32 v152, v152, v156
	v_add_f32_e32 v144, v145, v144
	v_add_f32_e32 v144, v144, v152
	v_mov_b32_e32 v145, v144
	s_nop 1
	v_permlane16_swap_b32_e32 v144, v145
	s_waitcnt lgkmcnt(0)
	v_add_f32_e32 v144, v144, v145
	v_mov_b32_e32 v145, v144
	s_nop 1
	v_permlane32_swap_b32_e32 v144, v145
	s_and_saveexec_b64 s[64:65], s[38:39]
	s_cbranch_execz .LBB0_1185
	v_lshl_add_u32 v146, v248, 4, s89
	s_waitcnt lgkmcnt(0)
	v_add_f32_e32 v144, v144, v145
	ds_write_b32 v146, v144

.LBB0_1197:
	v_mul_f32_e32 v137, v137, v137
	v_mul_f32_e32 v133, v133, v133
	v_fmac_f32_e32 v137, v136, v136
	v_mul_f32_e32 v136, v139, v139
	v_fmac_f32_e32 v133, v132, v132
	v_mul_f32_e32 v132, v135, v135
	v_mul_f32_e32 v125, v125, v125
	v_fmac_f32_e32 v136, v138, v138
	v_fmac_f32_e32 v132, v134, v134
	v_fmac_f32_e32 v125, v124, v124
	v_mul_f32_e32 v124, v127, v127
	v_mul_f32_e32 v121, v121, v121
	v_add_f32_e32 v136, v137, v136
	v_add_f32_e32 v132, v133, v132
	v_fmac_f32_e32 v124, v126, v126
	v_fmac_f32_e32 v121, v120, v120
	v_mul_f32_e32 v120, v123, v123
	v_add_f32_e32 v132, v136, v132
	v_add_f32_e32 v124, v125, v124
	v_fmac_f32_e32 v120, v122, v122
	v_add_f32_e32 v124, v124, v132
	v_add_f32_e32 v120, v121, v120
	v_add_f32_e32 v120, v120, v124
	v_mov_b32_e32 v121, v120
	s_nop 1
	v_permlane16_swap_b32_e32 v120, v121
	s_waitcnt lgkmcnt(0)
	v_add_f32_e32 v120, v120, v121
	v_mov_b32_e32 v121, v120
	s_nop 1
	v_permlane32_swap_b32_e32 v120, v121
	s_and_saveexec_b64 s[64:65], s[38:39]
	s_cbranch_execz .LBB0_1199
	v_lshl_add_u32 v122, v158, 4, s89
	s_waitcnt lgkmcnt(0)
	v_add_f32_e32 v120, v120, v121
	ds_write_b32 v122, v120

.LBB0_1211:
	v_mul_f32_e32 v105, v105, v105
	v_mul_f32_e32 v97, v97, v97
	v_fmac_f32_e32 v105, v104, v104
	v_mul_f32_e32 v104, v107, v107
	v_fmac_f32_e32 v97, v96, v96
	v_mul_f32_e32 v96, v99, v99
	v_mul_f32_e32 v89, v89, v89
	v_fmac_f32_e32 v104, v106, v106
	v_fmac_f32_e32 v96, v98, v98
	v_fmac_f32_e32 v89, v88, v88
	v_mul_f32_e32 v88, v91, v91
	v_mul_f32_e32 v85, v85, v85
	v_add_f32_e32 v104, v105, v104
	v_add_f32_e32 v96, v97, v96
	v_fmac_f32_e32 v88, v90, v90
	v_fmac_f32_e32 v85, v84, v84
	v_mul_f32_e32 v84, v87, v87
	v_add_f32_e32 v96, v104, v96
	v_add_f32_e32 v88, v89, v88
	v_fmac_f32_e32 v84, v86, v86
	v_add_f32_e32 v88, v88, v96
	v_add_f32_e32 v84, v85, v84
	v_add_f32_e32 v84, v84, v88
	v_mov_b32_e32 v85, v84
	s_nop 1
	v_permlane16_swap_b32_e32 v84, v85
	s_waitcnt lgkmcnt(0)
	v_add_f32_e32 v84, v84, v85
	v_mov_b32_e32 v85, v84
	s_nop 1
	v_permlane32_swap_b32_e32 v84, v85
	s_and_saveexec_b64 s[64:65], s[38:39]
	s_cbranch_execz .LBB0_1213
	v_lshl_add_u32 v86, v134, 4, s89
	s_waitcnt lgkmcnt(0)
	v_add_f32_e32 v84, v84, v85
	ds_write_b32 v86, v84

.LBB0_1225:
	v_mul_f32_e32 v81, v81, v81
	v_mul_f32_e32 v77, v77, v77
	v_fmac_f32_e32 v81, v80, v80
	v_mul_f32_e32 v80, v83, v83
	v_fmac_f32_e32 v77, v76, v76
	v_mul_f32_e32 v76, v79, v79
	v_mul_f32_e32 v73, v73, v73
	v_fmac_f32_e32 v80, v82, v82
	v_fmac_f32_e32 v76, v78, v78
	v_fmac_f32_e32 v73, v72, v72
	v_mul_f32_e32 v72, v75, v75
	v_mul_f32_e32 v69, v69, v69
	v_add_f32_e32 v80, v81, v80
	v_add_f32_e32 v76, v77, v76
	v_fmac_f32_e32 v72, v74, v74
	v_fmac_f32_e32 v69, v68, v68
	v_mul_f32_e32 v68, v71, v71
	v_add_f32_e32 v76, v80, v76
	v_add_f32_e32 v72, v73, v72
	v_fmac_f32_e32 v68, v70, v70
	v_add_f32_e32 v72, v72, v76
	v_add_f32_e32 v68, v69, v68
	v_add_f32_e32 v68, v68, v72
	v_mov_b32_e32 v69, v68
	s_nop 1
	v_permlane16_swap_b32_e32 v68, v69
	s_waitcnt lgkmcnt(0)
	v_add_f32_e32 v68, v68, v69
	v_mov_b32_e32 v69, v68
	s_nop 1
	v_permlane32_swap_b32_e32 v68, v69
	s_and_saveexec_b64 s[64:65], s[38:39]
	s_cbranch_execz .LBB0_1227
	v_lshl_add_u32 v70, v98, 4, s89
	s_waitcnt lgkmcnt(0)
	v_add_f32_e32 v68, v68, v69
	ds_write_b32 v70, v68

.LBB0_1239:
	v_mul_f32_e32 v65, v65, v65
	v_mul_f32_e32 v61, v61, v61
	v_fmac_f32_e32 v65, v64, v64
	v_mul_f32_e32 v64, v67, v67
	v_fmac_f32_e32 v61, v60, v60
	v_mul_f32_e32 v60, v63, v63
	v_mul_f32_e32 v57, v57, v57
	v_fmac_f32_e32 v64, v66, v66
	v_fmac_f32_e32 v60, v62, v62
	v_fmac_f32_e32 v57, v56, v56
	v_mul_f32_e32 v56, v59, v59
	v_mul_f32_e32 v53, v53, v53
	v_add_f32_e32 v64, v65, v64
	v_add_f32_e32 v60, v61, v60
	v_fmac_f32_e32 v56, v58, v58
	v_fmac_f32_e32 v53, v52, v52
	v_mul_f32_e32 v52, v55, v55
	v_add_f32_e32 v60, v64, v60
	v_add_f32_e32 v56, v57, v56
	v_fmac_f32_e32 v52, v54, v54
	v_add_f32_e32 v56, v56, v60
	v_add_f32_e32 v52, v53, v52
	v_add_f32_e32 v52, v52, v56
	v_mov_b32_e32 v53, v52
	s_nop 1
	v_permlane16_swap_b32_e32 v52, v53
	s_waitcnt lgkmcnt(0)
	v_add_f32_e32 v52, v52, v53
	v_mov_b32_e32 v53, v52
	s_nop 1
	v_permlane32_swap_b32_e32 v52, v53
	s_and_saveexec_b64 s[64:65], s[38:39]
	s_cbranch_execz .LBB0_1241
	v_lshl_add_u32 v54, v78, 4, s89
	s_waitcnt lgkmcnt(0)
	v_add_f32_e32 v52, v52, v53
	ds_write_b32 v54, v52

.LBB0_1253:
	v_mul_f32_e32 v49, v49, v49
	v_mul_f32_e32 v45, v45, v45
	v_fmac_f32_e32 v49, v48, v48
	v_mul_f32_e32 v48, v51, v51
	v_fmac_f32_e32 v45, v44, v44
	v_mul_f32_e32 v44, v47, v47
	v_mul_f32_e32 v41, v41, v41
	v_fmac_f32_e32 v48, v50, v50
	v_fmac_f32_e32 v44, v46, v46
	v_fmac_f32_e32 v41, v40, v40
	v_mul_f32_e32 v40, v43, v43
	v_mul_f32_e32 v37, v37, v37
	v_add_f32_e32 v48, v49, v48
	v_add_f32_e32 v44, v45, v44
	v_fmac_f32_e32 v40, v42, v42
	v_fmac_f32_e32 v37, v36, v36
	v_mul_f32_e32 v36, v39, v39
	v_add_f32_e32 v44, v48, v44
	v_add_f32_e32 v40, v41, v40
	v_fmac_f32_e32 v36, v38, v38
	v_add_f32_e32 v40, v40, v44
	v_add_f32_e32 v36, v37, v36
	v_add_f32_e32 v36, v36, v40
	v_mov_b32_e32 v37, v36
	s_nop 1
	v_permlane16_swap_b32_e32 v36, v37
	s_waitcnt lgkmcnt(0)
	v_add_f32_e32 v36, v36, v37
	v_mov_b32_e32 v37, v36
	s_nop 1
	v_permlane32_swap_b32_e32 v36, v37
	s_and_saveexec_b64 s[64:65], s[38:39]
	s_cbranch_execz .LBB0_1255
	v_lshl_add_u32 v38, v62, 4, s89
	s_waitcnt lgkmcnt(0)
	v_add_f32_e32 v36, v36, v37
	ds_write_b32 v38, v36

.LBB0_1267:
	v_mul_f32_e32 v33, v33, v33
	v_mul_f32_e32 v29, v29, v29
	v_fmac_f32_e32 v33, v32, v32
	v_mul_f32_e32 v32, v35, v35
	v_fmac_f32_e32 v29, v28, v28
	v_mul_f32_e32 v28, v31, v31
	v_mul_f32_e32 v25, v25, v25
	v_fmac_f32_e32 v32, v34, v34
	v_fmac_f32_e32 v28, v30, v30
	v_fmac_f32_e32 v25, v24, v24
	v_mul_f32_e32 v24, v27, v27
	v_mul_f32_e32 v21, v21, v21
	v_add_f32_e32 v32, v33, v32
	v_add_f32_e32 v28, v29, v28
	v_fmac_f32_e32 v24, v26, v26
	v_fmac_f32_e32 v21, v20, v20
	v_mul_f32_e32 v20, v23, v23
	v_add_f32_e32 v28, v32, v28
	v_add_f32_e32 v24, v25, v24
	v_fmac_f32_e32 v20, v22, v22
	v_add_f32_e32 v24, v24, v28
	v_add_f32_e32 v20, v21, v20
	v_add_f32_e32 v20, v20, v24
	v_mov_b32_e32 v21, v20
	s_nop 1
	v_permlane16_swap_b32_e32 v20, v21
	s_waitcnt lgkmcnt(0)
	v_add_f32_e32 v20, v20, v21
	v_mov_b32_e32 v21, v20
	s_nop 1
	v_permlane32_swap_b32_e32 v20, v21
	s_and_saveexec_b64 s[64:65], s[38:39]
	s_cbranch_execz .LBB0_1269
	v_lshl_add_u32 v22, v46, 4, s89
	s_waitcnt lgkmcnt(0)
	v_add_f32_e32 v20, v20, v21
	ds_write_b32 v22, v20

.LBB0_1281:
	v_mul_f32_e32 v17, v17, v17
	v_mul_f32_e32 v13, v13, v13
	v_fmac_f32_e32 v17, v16, v16
	v_mul_f32_e32 v16, v19, v19
	v_fmac_f32_e32 v13, v12, v12
	v_mul_f32_e32 v12, v15, v15
	v_mul_f32_e32 v9, v9, v9
	v_fmac_f32_e32 v16, v18, v18
	v_fmac_f32_e32 v12, v14, v14
	v_fmac_f32_e32 v9, v8, v8
	v_mul_f32_e32 v8, v11, v11
	v_mul_f32_e32 v5, v5, v5
	v_add_f32_e32 v16, v17, v16
	v_add_f32_e32 v12, v13, v12
	v_fmac_f32_e32 v8, v10, v10
	v_fmac_f32_e32 v5, v4, v4
	v_mul_f32_e32 v4, v7, v7
	v_add_f32_e32 v12, v16, v12
	v_add_f32_e32 v8, v9, v8
	v_fmac_f32_e32 v4, v6, v6
	v_add_f32_e32 v8, v8, v12
	v_add_f32_e32 v4, v5, v4
	v_add_f32_e32 v4, v4, v8
	v_mov_b32_e32 v5, v4
	s_nop 1
	v_permlane16_swap_b32_e32 v4, v5
	s_waitcnt lgkmcnt(0)
	v_add_f32_e32 v4, v4, v5
	v_mov_b32_e32 v5, v4
	s_nop 1
	v_permlane32_swap_b32_e32 v4, v5
	s_and_saveexec_b64 s[42:43], s[38:39]
	s_cbranch_execz .LBB0_1283
	v_lshl_add_u32 v6, v30, 4, s89
	s_waitcnt lgkmcnt(0)
	v_add_f32_e32 v4, v4, v5
	ds_write_b32 v6, v4
